# mod_item GEMV: trip-0 ada_w row loads of each half requested before the SiLU staging (overlaps both cold round trips)
# baseline (speedup 1.0000x reference)
.LBB0_139:
	s_barrier
	v_add_u32_e32 v248, s76, v110
	v_mad_i64_i32 v[250:251], s[72:73], v248, s75, v[74:75]
	global_load_dwordx4 v[216:219], v[250:251], off
	v_add_co_u32_e32 v212, vcc, 0x6000, v250
	s_nop 1
	v_addc_co_u32_e32 v213, vcc, 0, v251, vcc
	global_load_dwordx4 v[220:223], v[212:213], off
	v_add_co_u32_e32 v212, vcc, 0xc000, v250
	s_nop 1
	v_addc_co_u32_e32 v213, vcc, 0, v251, vcc
	global_load_dwordx4 v[224:227], v[212:213], off
	v_add_co_u32_e32 v212, vcc, 0x12000, v250
	s_nop 1
	v_addc_co_u32_e32 v213, vcc, 0, v251, vcc
	global_load_dwordx4 v[228:231], v[212:213], off
	v_add_co_u32_e32 v212, vcc, 0x18000, v250
	s_nop 1
	v_addc_co_u32_e32 v213, vcc, 0, v251, vcc
	global_load_dwordx4 v[232:235], v[212:213], off
	v_add_co_u32_e32 v212, vcc, 0x1e000, v250
	s_nop 1
	v_addc_co_u32_e32 v213, vcc, 0, v251, vcc
	global_load_dwordx4 v[236:239], v[212:213], off
	v_add_co_u32_e32 v212, vcc, 0x24000, v250
	s_nop 1
	v_addc_co_u32_e32 v213, vcc, 0, v251, vcc
	global_load_dwordx4 v[240:243], v[212:213], off
	v_add_co_u32_e32 v212, vcc, 0x2a000, v250
	s_nop 1
	v_addc_co_u32_e32 v213, vcc, 0, v251, vcc
	global_load_dwordx4 v[244:247], v[212:213], off
	s_and_saveexec_b64 s[6:7], s[4:5]
	s_cbranch_execz .LBB0_146
	v_add_u32_e32 v214, s76, v139
	v_lshlrev_b32_e32 v214, 2, v214
	global_load_dword v180, v214, s[38:39]
	v_add_u32_e32 v215, 0x400, v214
	global_load_dword v181, v215, s[38:39]
	v_add_u32_e32 v215, 0x1000, v214
	global_load_dword v182, v215, s[38:39]
	v_add_u32_e32 v215, 0x1400, v214
	global_load_dword v183, v215, s[38:39]
	v_add_u32_e32 v215, 0x2000, v214
	global_load_dword v184, v215, s[38:39]
	v_add_u32_e32 v215, 0x2400, v214
	global_load_dword v185, v215, s[38:39]
	v_add_u32_e32 v215, 0x3000, v214
	global_load_dword v186, v215, s[38:39]
	v_add_u32_e32 v215, 0x3400, v214
	global_load_dword v187, v215, s[38:39]
	v_add_u32_e32 v215, 0x4000, v214
	global_load_dword v188, v215, s[38:39]
	v_add_u32_e32 v215, 0x4400, v214
	global_load_dword v189, v215, s[38:39]
	v_add_u32_e32 v215, 0x5000, v214
	global_load_dword v190, v215, s[38:39]
	v_add_u32_e32 v215, 0x5400, v214
	global_load_dword v191, v215, s[38:39]
	v_add_u32_e32 v215, 0x6000, v214
	global_load_dword v192, v215, s[38:39]
	v_add_u32_e32 v215, 0x6400, v214
	global_load_dword v193, v215, s[38:39]
	v_add_u32_e32 v215, 0x7000, v214
	global_load_dword v194, v215, s[38:39]
	v_add_u32_e32 v215, 0x7400, v214
	global_load_dword v195, v215, s[38:39]
	v_add_u32_e32 v215, 0x8000, v214
	global_load_dword v196, v215, s[38:39]
	v_add_u32_e32 v215, 0x8400, v214
	global_load_dword v197, v215, s[38:39]
	v_add_u32_e32 v215, 0x9000, v214
	global_load_dword v198, v215, s[38:39]
	v_add_u32_e32 v215, 0x9400, v214
	global_load_dword v199, v215, s[38:39]
	v_add_u32_e32 v215, 0xa000, v214
	global_load_dword v200, v215, s[38:39]
	v_add_u32_e32 v215, 0xa400, v214
	global_load_dword v201, v215, s[38:39]
	v_add_u32_e32 v215, 0xb000, v214
	global_load_dword v202, v215, s[38:39]
	v_add_u32_e32 v215, 0xb400, v214
	global_load_dword v203, v215, s[38:39]
	v_add_u32_e32 v215, 0xc000, v214
	global_load_dword v204, v215, s[38:39]
	v_add_u32_e32 v215, 0xc400, v214
	global_load_dword v205, v215, s[38:39]
	v_add_u32_e32 v215, 0xd000, v214
	global_load_dword v206, v215, s[38:39]
	v_add_u32_e32 v215, 0xd400, v214
	global_load_dword v207, v215, s[38:39]
	v_add_u32_e32 v215, 0xe000, v214
	global_load_dword v208, v215, s[38:39]
	v_add_u32_e32 v215, 0xe400, v214
	global_load_dword v209, v215, s[38:39]
	v_add_u32_e32 v215, 0xf000, v214
	global_load_dword v210, v215, s[38:39]
	v_add_u32_e32 v215, 0xf400, v214
	global_load_dword v211, v215, s[38:39]
	global_load_dword v212, v214, s[42:43]
	v_add_u32_e32 v215, 0x400, v214
	global_load_dword v213, v215, s[42:43]
	s_waitcnt vmcnt(33)
	v_mov_b32_e32 v0, v180
	v_mul_f32_e32 v1, 0xbfb8aa3b, v0
	v_exp_f32_e32 v1, v1
	s_nop 0
	v_add_f32_e32 v1, 1.0, v1
	v_div_scale_f32 v4, s[72:73], v1, v1, 1.0
	v_rcp_f32_e32 v5, v4
	s_nop 0
	v_fma_f32 v6, -v4, v5, 1.0
	v_fmac_f32_e32 v5, v6, v5
	v_div_scale_f32 v6, vcc, 1.0, v1, 1.0
	v_mul_f32_e32 v7, v6, v5
	v_fma_f32 v10, -v4, v7, v6
	v_fmac_f32_e32 v7, v10, v5
	v_fma_f32 v4, -v4, v7, v6
	v_div_fmas_f32 v4, v4, v5, v7
	v_div_fixup_f32 v1, v4, v1, 1.0
	v_mul_f32_e32 v0, v0, v1
	ds_write_b32 v140, v0
	s_waitcnt vmcnt(32)
	v_mov_b32_e32 v0, v181
	v_mul_f32_e32 v1, 0xbfb8aa3b, v0
	v_exp_f32_e32 v1, v1
	s_nop 0
	v_add_f32_e32 v1, 1.0, v1
	v_div_scale_f32 v4, s[72:73], v1, v1, 1.0
	v_rcp_f32_e32 v5, v4
	s_nop 0
	v_fma_f32 v6, -v4, v5, 1.0
	v_fmac_f32_e32 v5, v6, v5
	v_div_scale_f32 v6, vcc, 1.0, v1, 1.0
	v_mul_f32_e32 v7, v6, v5
	v_fma_f32 v10, -v4, v7, v6
	v_fmac_f32_e32 v7, v10, v5
	v_fma_f32 v4, -v4, v7, v6
	v_div_fmas_f32 v4, v4, v5, v7
	v_div_fixup_f32 v1, v4, v1, 1.0
	v_mul_f32_e32 v0, v0, v1
	ds_write_b32 v140, v0 offset:1024
	s_waitcnt vmcnt(31)
	v_mov_b32_e32 v0, v182
	v_mul_f32_e32 v1, 0xbfb8aa3b, v0
	v_exp_f32_e32 v1, v1
	s_nop 0
	v_add_f32_e32 v1, 1.0, v1
	v_div_scale_f32 v4, s[72:73], v1, v1, 1.0
	v_rcp_f32_e32 v5, v4
	s_nop 0
	v_fma_f32 v6, -v4, v5, 1.0
	v_fmac_f32_e32 v5, v6, v5
	v_div_scale_f32 v6, vcc, 1.0, v1, 1.0
	v_mul_f32_e32 v7, v6, v5
	v_fma_f32 v10, -v4, v7, v6
	v_fmac_f32_e32 v7, v10, v5
	v_fma_f32 v4, -v4, v7, v6
	v_div_fmas_f32 v4, v4, v5, v7
	v_div_fixup_f32 v1, v4, v1, 1.0
	v_mul_f32_e32 v0, v0, v1
	ds_write_b32 v140, v0 offset:2048
	s_waitcnt vmcnt(30)
	v_mov_b32_e32 v0, v183
	v_mul_f32_e32 v1, 0xbfb8aa3b, v0
	v_exp_f32_e32 v1, v1
	s_nop 0
	v_add_f32_e32 v1, 1.0, v1
	v_div_scale_f32 v4, s[72:73], v1, v1, 1.0
	v_rcp_f32_e32 v5, v4
	s_nop 0
	v_fma_f32 v6, -v4, v5, 1.0
	v_fmac_f32_e32 v5, v6, v5
	v_div_scale_f32 v6, vcc, 1.0, v1, 1.0
	v_mul_f32_e32 v7, v6, v5
	v_fma_f32 v10, -v4, v7, v6
	v_fmac_f32_e32 v7, v10, v5
	v_fma_f32 v4, -v4, v7, v6
	v_div_fmas_f32 v4, v4, v5, v7
	v_div_fixup_f32 v1, v4, v1, 1.0
	v_mul_f32_e32 v0, v0, v1
	ds_write_b32 v140, v0 offset:3072
	s_waitcnt vmcnt(29)
	v_mov_b32_e32 v0, v184
	v_mul_f32_e32 v1, 0xbfb8aa3b, v0
	v_exp_f32_e32 v1, v1
	s_nop 0
	v_add_f32_e32 v1, 1.0, v1
	v_div_scale_f32 v4, s[72:73], v1, v1, 1.0
	v_rcp_f32_e32 v5, v4
	s_nop 0
	v_fma_f32 v6, -v4, v5, 1.0
	v_fmac_f32_e32 v5, v6, v5
	v_div_scale_f32 v6, vcc, 1.0, v1, 1.0
	v_mul_f32_e32 v7, v6, v5
	v_fma_f32 v10, -v4, v7, v6
	v_fmac_f32_e32 v7, v10, v5
	v_fma_f32 v4, -v4, v7, v6
	v_div_fmas_f32 v4, v4, v5, v7
	v_div_fixup_f32 v1, v4, v1, 1.0
	v_mul_f32_e32 v0, v0, v1
	ds_write_b32 v140, v0 offset:4096
	s_waitcnt vmcnt(28)
	v_mov_b32_e32 v0, v185
	v_mul_f32_e32 v1, 0xbfb8aa3b, v0
	v_exp_f32_e32 v1, v1
	s_nop 0
	v_add_f32_e32 v1, 1.0, v1
	v_div_scale_f32 v4, s[72:73], v1, v1, 1.0
	v_rcp_f32_e32 v5, v4
	s_nop 0
	v_fma_f32 v6, -v4, v5, 1.0
	v_fmac_f32_e32 v5, v6, v5
	v_div_scale_f32 v6, vcc, 1.0, v1, 1.0
	v_mul_f32_e32 v7, v6, v5
	v_fma_f32 v10, -v4, v7, v6
	v_fmac_f32_e32 v7, v10, v5
	v_fma_f32 v4, -v4, v7, v6
	v_div_fmas_f32 v4, v4, v5, v7
	v_div_fixup_f32 v1, v4, v1, 1.0
	v_mul_f32_e32 v0, v0, v1
	ds_write_b32 v140, v0 offset:5120
	s_waitcnt vmcnt(27)
	v_mov_b32_e32 v0, v186
	v_mul_f32_e32 v1, 0xbfb8aa3b, v0
	v_exp_f32_e32 v1, v1
	s_nop 0
	v_add_f32_e32 v1, 1.0, v1
	v_div_scale_f32 v4, s[72:73], v1, v1, 1.0
	v_rcp_f32_e32 v5, v4
	s_nop 0
	v_fma_f32 v6, -v4, v5, 1.0
	v_fmac_f32_e32 v5, v6, v5
	v_div_scale_f32 v6, vcc, 1.0, v1, 1.0
	v_mul_f32_e32 v7, v6, v5
	v_fma_f32 v10, -v4, v7, v6
	v_fmac_f32_e32 v7, v10, v5
	v_fma_f32 v4, -v4, v7, v6
	v_div_fmas_f32 v4, v4, v5, v7
	v_div_fixup_f32 v1, v4, v1, 1.0
	v_mul_f32_e32 v0, v0, v1
	ds_write_b32 v140, v0 offset:6144
	s_waitcnt vmcnt(26)
	v_mov_b32_e32 v0, v187
	v_mul_f32_e32 v1, 0xbfb8aa3b, v0
	v_exp_f32_e32 v1, v1
	s_nop 0
	v_add_f32_e32 v1, 1.0, v1
	v_div_scale_f32 v4, s[72:73], v1, v1, 1.0
	v_rcp_f32_e32 v5, v4
	s_nop 0
	v_fma_f32 v6, -v4, v5, 1.0
	v_fmac_f32_e32 v5, v6, v5
	v_div_scale_f32 v6, vcc, 1.0, v1, 1.0
	v_mul_f32_e32 v7, v6, v5
	v_fma_f32 v10, -v4, v7, v6
	v_fmac_f32_e32 v7, v10, v5
	v_fma_f32 v4, -v4, v7, v6
	v_div_fmas_f32 v4, v4, v5, v7
	v_div_fixup_f32 v1, v4, v1, 1.0
	v_mul_f32_e32 v0, v0, v1
	ds_write_b32 v140, v0 offset:7168
	s_waitcnt vmcnt(25)
	v_mov_b32_e32 v0, v188
	v_mul_f32_e32 v1, 0xbfb8aa3b, v0
	v_exp_f32_e32 v1, v1
	s_nop 0
	v_add_f32_e32 v1, 1.0, v1
	v_div_scale_f32 v4, s[72:73], v1, v1, 1.0
	v_rcp_f32_e32 v5, v4
	s_nop 0
	v_fma_f32 v6, -v4, v5, 1.0
	v_fmac_f32_e32 v5, v6, v5
	v_div_scale_f32 v6, vcc, 1.0, v1, 1.0
	v_mul_f32_e32 v7, v6, v5
	v_fma_f32 v10, -v4, v7, v6
	v_fmac_f32_e32 v7, v10, v5
	v_fma_f32 v4, -v4, v7, v6
	v_div_fmas_f32 v4, v4, v5, v7
	v_div_fixup_f32 v1, v4, v1, 1.0
	v_mul_f32_e32 v0, v0, v1
	ds_write_b32 v140, v0 offset:8192
	s_waitcnt vmcnt(24)
	v_mov_b32_e32 v0, v189
	v_mul_f32_e32 v1, 0xbfb8aa3b, v0
	v_exp_f32_e32 v1, v1
	s_nop 0
	v_add_f32_e32 v1, 1.0, v1
	v_div_scale_f32 v4, s[72:73], v1, v1, 1.0
	v_rcp_f32_e32 v5, v4
	s_nop 0
	v_fma_f32 v6, -v4, v5, 1.0
	v_fmac_f32_e32 v5, v6, v5
	v_div_scale_f32 v6, vcc, 1.0, v1, 1.0
	v_mul_f32_e32 v7, v6, v5
	v_fma_f32 v10, -v4, v7, v6
	v_fmac_f32_e32 v7, v10, v5
	v_fma_f32 v4, -v4, v7, v6
	v_div_fmas_f32 v4, v4, v5, v7
	v_div_fixup_f32 v1, v4, v1, 1.0
	v_mul_f32_e32 v0, v0, v1
	ds_write_b32 v140, v0 offset:9216
	s_waitcnt vmcnt(23)
	v_mov_b32_e32 v0, v190
	v_mul_f32_e32 v1, 0xbfb8aa3b, v0
	v_exp_f32_e32 v1, v1
	s_nop 0
	v_add_f32_e32 v1, 1.0, v1
	v_div_scale_f32 v4, s[72:73], v1, v1, 1.0
	v_rcp_f32_e32 v5, v4
	s_nop 0
	v_fma_f32 v6, -v4, v5, 1.0
	v_fmac_f32_e32 v5, v6, v5
	v_div_scale_f32 v6, vcc, 1.0, v1, 1.0
	v_mul_f32_e32 v7, v6, v5
	v_fma_f32 v10, -v4, v7, v6
	v_fmac_f32_e32 v7, v10, v5
	v_fma_f32 v4, -v4, v7, v6
	v_div_fmas_f32 v4, v4, v5, v7
	v_div_fixup_f32 v1, v4, v1, 1.0
	v_mul_f32_e32 v0, v0, v1
	ds_write_b32 v140, v0 offset:10240
	s_waitcnt vmcnt(22)
	v_mov_b32_e32 v0, v191
	v_mul_f32_e32 v1, 0xbfb8aa3b, v0
	v_exp_f32_e32 v1, v1
	s_nop 0
	v_add_f32_e32 v1, 1.0, v1
	v_div_scale_f32 v4, s[72:73], v1, v1, 1.0
	v_rcp_f32_e32 v5, v4
	s_nop 0
	v_fma_f32 v6, -v4, v5, 1.0
	v_fmac_f32_e32 v5, v6, v5
	v_div_scale_f32 v6, vcc, 1.0, v1, 1.0
	v_mul_f32_e32 v7, v6, v5
	v_fma_f32 v10, -v4, v7, v6
	v_fmac_f32_e32 v7, v10, v5
	v_fma_f32 v4, -v4, v7, v6
	v_div_fmas_f32 v4, v4, v5, v7
	v_div_fixup_f32 v1, v4, v1, 1.0
	v_mul_f32_e32 v0, v0, v1
	ds_write_b32 v140, v0 offset:11264
	s_waitcnt vmcnt(21)
	v_mov_b32_e32 v0, v192
	v_mul_f32_e32 v1, 0xbfb8aa3b, v0
	v_exp_f32_e32 v1, v1
	s_nop 0
	v_add_f32_e32 v1, 1.0, v1
	v_div_scale_f32 v4, s[72:73], v1, v1, 1.0
	v_rcp_f32_e32 v5, v4
	s_nop 0
	v_fma_f32 v6, -v4, v5, 1.0
	v_fmac_f32_e32 v5, v6, v5
	v_div_scale_f32 v6, vcc, 1.0, v1, 1.0
	v_mul_f32_e32 v7, v6, v5
	v_fma_f32 v10, -v4, v7, v6
	v_fmac_f32_e32 v7, v10, v5
	v_fma_f32 v4, -v4, v7, v6
	v_div_fmas_f32 v4, v4, v5, v7
	v_div_fixup_f32 v1, v4, v1, 1.0
	v_mul_f32_e32 v0, v0, v1
	ds_write_b32 v140, v0 offset:12288
	s_waitcnt vmcnt(20)
	v_mov_b32_e32 v0, v193
	v_mul_f32_e32 v1, 0xbfb8aa3b, v0
	v_exp_f32_e32 v1, v1
	s_nop 0
	v_add_f32_e32 v1, 1.0, v1
	v_div_scale_f32 v4, s[72:73], v1, v1, 1.0
	v_rcp_f32_e32 v5, v4
	s_nop 0
	v_fma_f32 v6, -v4, v5, 1.0
	v_fmac_f32_e32 v5, v6, v5
	v_div_scale_f32 v6, vcc, 1.0, v1, 1.0
	v_mul_f32_e32 v7, v6, v5
	v_fma_f32 v10, -v4, v7, v6
	v_fmac_f32_e32 v7, v10, v5
	v_fma_f32 v4, -v4, v7, v6
	v_div_fmas_f32 v4, v4, v5, v7
	v_div_fixup_f32 v1, v4, v1, 1.0
	v_mul_f32_e32 v0, v0, v1
	ds_write_b32 v140, v0 offset:13312
	s_waitcnt vmcnt(19)
	v_mov_b32_e32 v0, v194
	v_mul_f32_e32 v1, 0xbfb8aa3b, v0
	v_exp_f32_e32 v1, v1
	s_nop 0
	v_add_f32_e32 v1, 1.0, v1
	v_div_scale_f32 v4, s[72:73], v1, v1, 1.0
	v_rcp_f32_e32 v5, v4
	s_nop 0
	v_fma_f32 v6, -v4, v5, 1.0
	v_fmac_f32_e32 v5, v6, v5
	v_div_scale_f32 v6, vcc, 1.0, v1, 1.0
	v_mul_f32_e32 v7, v6, v5
	v_fma_f32 v10, -v4, v7, v6
	v_fmac_f32_e32 v7, v10, v5
	v_fma_f32 v4, -v4, v7, v6
	v_div_fmas_f32 v4, v4, v5, v7
	v_div_fixup_f32 v1, v4, v1, 1.0
	v_mul_f32_e32 v0, v0, v1
	ds_write_b32 v140, v0 offset:14336
	s_waitcnt vmcnt(18)
	v_mov_b32_e32 v0, v195
	v_mul_f32_e32 v1, 0xbfb8aa3b, v0
	v_exp_f32_e32 v1, v1
	s_nop 0
	v_add_f32_e32 v1, 1.0, v1
	v_div_scale_f32 v4, s[72:73], v1, v1, 1.0
	v_rcp_f32_e32 v5, v4
	s_nop 0
	v_fma_f32 v6, -v4, v5, 1.0
	v_fmac_f32_e32 v5, v6, v5
	v_div_scale_f32 v6, vcc, 1.0, v1, 1.0
	v_mul_f32_e32 v7, v6, v5
	v_fma_f32 v10, -v4, v7, v6
	v_fmac_f32_e32 v7, v10, v5
	v_fma_f32 v4, -v4, v7, v6
	v_div_fmas_f32 v4, v4, v5, v7
	v_div_fixup_f32 v1, v4, v1, 1.0
	v_mul_f32_e32 v0, v0, v1
	ds_write_b32 v140, v0 offset:15360
	s_waitcnt vmcnt(17)
	v_mov_b32_e32 v0, v196
	v_mul_f32_e32 v1, 0xbfb8aa3b, v0
	v_exp_f32_e32 v1, v1
	s_nop 0
	v_add_f32_e32 v1, 1.0, v1
	v_div_scale_f32 v4, s[72:73], v1, v1, 1.0
	v_rcp_f32_e32 v5, v4
	s_nop 0
	v_fma_f32 v6, -v4, v5, 1.0
	v_fmac_f32_e32 v5, v6, v5
	v_div_scale_f32 v6, vcc, 1.0, v1, 1.0
	v_mul_f32_e32 v7, v6, v5
	v_fma_f32 v10, -v4, v7, v6
	v_fmac_f32_e32 v7, v10, v5
	v_fma_f32 v4, -v4, v7, v6
	v_div_fmas_f32 v4, v4, v5, v7
	v_div_fixup_f32 v1, v4, v1, 1.0
	v_mul_f32_e32 v0, v0, v1
	ds_write_b32 v140, v0 offset:16384
	s_waitcnt vmcnt(16)
	v_mov_b32_e32 v0, v197
	v_mul_f32_e32 v1, 0xbfb8aa3b, v0
	v_exp_f32_e32 v1, v1
	s_nop 0
	v_add_f32_e32 v1, 1.0, v1
	v_div_scale_f32 v4, s[72:73], v1, v1, 1.0
	v_rcp_f32_e32 v5, v4
	s_nop 0
	v_fma_f32 v6, -v4, v5, 1.0
	v_fmac_f32_e32 v5, v6, v5
	v_div_scale_f32 v6, vcc, 1.0, v1, 1.0
	v_mul_f32_e32 v7, v6, v5
	v_fma_f32 v10, -v4, v7, v6
	v_fmac_f32_e32 v7, v10, v5
	v_fma_f32 v4, -v4, v7, v6
	v_div_fmas_f32 v4, v4, v5, v7
	v_div_fixup_f32 v1, v4, v1, 1.0
	v_mul_f32_e32 v0, v0, v1
	ds_write_b32 v140, v0 offset:17408
	s_waitcnt vmcnt(15)
	v_mov_b32_e32 v0, v198
	v_mul_f32_e32 v1, 0xbfb8aa3b, v0
	v_exp_f32_e32 v1, v1
	s_nop 0
	v_add_f32_e32 v1, 1.0, v1
	v_div_scale_f32 v4, s[72:73], v1, v1, 1.0
	v_rcp_f32_e32 v5, v4
	s_nop 0
	v_fma_f32 v6, -v4, v5, 1.0
	v_fmac_f32_e32 v5, v6, v5
	v_div_scale_f32 v6, vcc, 1.0, v1, 1.0
	v_mul_f32_e32 v7, v6, v5
	v_fma_f32 v10, -v4, v7, v6
	v_fmac_f32_e32 v7, v10, v5
	v_fma_f32 v4, -v4, v7, v6
	v_div_fmas_f32 v4, v4, v5, v7
	v_div_fixup_f32 v1, v4, v1, 1.0
	v_mul_f32_e32 v0, v0, v1
	ds_write_b32 v140, v0 offset:18432
	s_waitcnt vmcnt(14)
	v_mov_b32_e32 v0, v199
	v_mul_f32_e32 v1, 0xbfb8aa3b, v0
	v_exp_f32_e32 v1, v1
	s_nop 0
	v_add_f32_e32 v1, 1.0, v1
	v_div_scale_f32 v4, s[72:73], v1, v1, 1.0
	v_rcp_f32_e32 v5, v4
	s_nop 0
	v_fma_f32 v6, -v4, v5, 1.0
	v_fmac_f32_e32 v5, v6, v5
	v_div_scale_f32 v6, vcc, 1.0, v1, 1.0
	v_mul_f32_e32 v7, v6, v5
	v_fma_f32 v10, -v4, v7, v6
	v_fmac_f32_e32 v7, v10, v5
	v_fma_f32 v4, -v4, v7, v6
	v_div_fmas_f32 v4, v4, v5, v7
	v_div_fixup_f32 v1, v4, v1, 1.0
	v_mul_f32_e32 v0, v0, v1
	ds_write_b32 v140, v0 offset:19456
	s_waitcnt vmcnt(13)
	v_mov_b32_e32 v0, v200
	v_mul_f32_e32 v1, 0xbfb8aa3b, v0
	v_exp_f32_e32 v1, v1
	s_nop 0
	v_add_f32_e32 v1, 1.0, v1
	v_div_scale_f32 v4, s[72:73], v1, v1, 1.0
	v_rcp_f32_e32 v5, v4
	s_nop 0
	v_fma_f32 v6, -v4, v5, 1.0
	v_fmac_f32_e32 v5, v6, v5
	v_div_scale_f32 v6, vcc, 1.0, v1, 1.0
	v_mul_f32_e32 v7, v6, v5
	v_fma_f32 v10, -v4, v7, v6
	v_fmac_f32_e32 v7, v10, v5
	v_fma_f32 v4, -v4, v7, v6
	v_div_fmas_f32 v4, v4, v5, v7
	v_div_fixup_f32 v1, v4, v1, 1.0
	v_mul_f32_e32 v0, v0, v1
	ds_write_b32 v140, v0 offset:20480
	s_waitcnt vmcnt(12)
	v_mov_b32_e32 v0, v201
	v_mul_f32_e32 v1, 0xbfb8aa3b, v0
	v_exp_f32_e32 v1, v1
	s_nop 0
	v_add_f32_e32 v1, 1.0, v1
	v_div_scale_f32 v4, s[72:73], v1, v1, 1.0
	v_rcp_f32_e32 v5, v4
	s_nop 0
	v_fma_f32 v6, -v4, v5, 1.0
	v_fmac_f32_e32 v5, v6, v5
	v_div_scale_f32 v6, vcc, 1.0, v1, 1.0
	v_mul_f32_e32 v7, v6, v5
	v_fma_f32 v10, -v4, v7, v6
	v_fmac_f32_e32 v7, v10, v5
	v_fma_f32 v4, -v4, v7, v6
	v_div_fmas_f32 v4, v4, v5, v7
	v_div_fixup_f32 v1, v4, v1, 1.0
	v_mul_f32_e32 v0, v0, v1
	ds_write_b32 v140, v0 offset:21504
	s_waitcnt vmcnt(11)
	v_mov_b32_e32 v0, v202
	v_mul_f32_e32 v1, 0xbfb8aa3b, v0
	v_exp_f32_e32 v1, v1
	s_nop 0
	v_add_f32_e32 v1, 1.0, v1
	v_div_scale_f32 v4, s[72:73], v1, v1, 1.0
	v_rcp_f32_e32 v5, v4
	s_nop 0
	v_fma_f32 v6, -v4, v5, 1.0
	v_fmac_f32_e32 v5, v6, v5
	v_div_scale_f32 v6, vcc, 1.0, v1, 1.0
	v_mul_f32_e32 v7, v6, v5
	v_fma_f32 v10, -v4, v7, v6
	v_fmac_f32_e32 v7, v10, v5
	v_fma_f32 v4, -v4, v7, v6
	v_div_fmas_f32 v4, v4, v5, v7
	v_div_fixup_f32 v1, v4, v1, 1.0
	v_mul_f32_e32 v0, v0, v1
	ds_write_b32 v140, v0 offset:22528
	s_waitcnt vmcnt(10)
	v_mov_b32_e32 v0, v203
	v_mul_f32_e32 v1, 0xbfb8aa3b, v0
	v_exp_f32_e32 v1, v1
	s_nop 0
	v_add_f32_e32 v1, 1.0, v1
	v_div_scale_f32 v4, s[72:73], v1, v1, 1.0
	v_rcp_f32_e32 v5, v4
	s_nop 0
	v_fma_f32 v6, -v4, v5, 1.0
	v_fmac_f32_e32 v5, v6, v5
	v_div_scale_f32 v6, vcc, 1.0, v1, 1.0
	v_mul_f32_e32 v7, v6, v5
	v_fma_f32 v10, -v4, v7, v6
	v_fmac_f32_e32 v7, v10, v5
	v_fma_f32 v4, -v4, v7, v6
	v_div_fmas_f32 v4, v4, v5, v7
	v_div_fixup_f32 v1, v4, v1, 1.0
	v_mul_f32_e32 v0, v0, v1
	ds_write_b32 v140, v0 offset:23552
	s_waitcnt vmcnt(9)
	v_mov_b32_e32 v0, v204
	v_mul_f32_e32 v1, 0xbfb8aa3b, v0
	v_exp_f32_e32 v1, v1
	s_nop 0
	v_add_f32_e32 v1, 1.0, v1
	v_div_scale_f32 v4, s[72:73], v1, v1, 1.0
	v_rcp_f32_e32 v5, v4
	s_nop 0
	v_fma_f32 v6, -v4, v5, 1.0
	v_fmac_f32_e32 v5, v6, v5
	v_div_scale_f32 v6, vcc, 1.0, v1, 1.0
	v_mul_f32_e32 v7, v6, v5
	v_fma_f32 v10, -v4, v7, v6
	v_fmac_f32_e32 v7, v10, v5
	v_fma_f32 v4, -v4, v7, v6
	v_div_fmas_f32 v4, v4, v5, v7
	v_div_fixup_f32 v1, v4, v1, 1.0
	v_mul_f32_e32 v0, v0, v1
	ds_write_b32 v140, v0 offset:24576
	s_waitcnt vmcnt(8)
	v_mov_b32_e32 v0, v205
	v_mul_f32_e32 v1, 0xbfb8aa3b, v0
	v_exp_f32_e32 v1, v1
	s_nop 0
	v_add_f32_e32 v1, 1.0, v1
	v_div_scale_f32 v4, s[72:73], v1, v1, 1.0
	v_rcp_f32_e32 v5, v4
	s_nop 0
	v_fma_f32 v6, -v4, v5, 1.0
	v_fmac_f32_e32 v5, v6, v5
	v_div_scale_f32 v6, vcc, 1.0, v1, 1.0
	v_mul_f32_e32 v7, v6, v5
	v_fma_f32 v10, -v4, v7, v6
	v_fmac_f32_e32 v7, v10, v5
	v_fma_f32 v4, -v4, v7, v6
	v_div_fmas_f32 v4, v4, v5, v7
	v_div_fixup_f32 v1, v4, v1, 1.0
	v_mul_f32_e32 v0, v0, v1
	ds_write_b32 v140, v0 offset:25600
	s_waitcnt vmcnt(7)
	v_mov_b32_e32 v0, v206
	v_mul_f32_e32 v1, 0xbfb8aa3b, v0
	v_exp_f32_e32 v1, v1
	s_nop 0
	v_add_f32_e32 v1, 1.0, v1
	v_div_scale_f32 v4, s[72:73], v1, v1, 1.0
	v_rcp_f32_e32 v5, v4
	s_nop 0
	v_fma_f32 v6, -v4, v5, 1.0
	v_fmac_f32_e32 v5, v6, v5
	v_div_scale_f32 v6, vcc, 1.0, v1, 1.0
	v_mul_f32_e32 v7, v6, v5
	v_fma_f32 v10, -v4, v7, v6
	v_fmac_f32_e32 v7, v10, v5
	v_fma_f32 v4, -v4, v7, v6
	v_div_fmas_f32 v4, v4, v5, v7
	v_div_fixup_f32 v1, v4, v1, 1.0
	v_mul_f32_e32 v0, v0, v1
	ds_write_b32 v140, v0 offset:26624
	s_waitcnt vmcnt(6)
	v_mov_b32_e32 v0, v207
	v_mul_f32_e32 v1, 0xbfb8aa3b, v0
	v_exp_f32_e32 v1, v1
	s_nop 0
	v_add_f32_e32 v1, 1.0, v1
	v_div_scale_f32 v4, s[72:73], v1, v1, 1.0
	v_rcp_f32_e32 v5, v4
	s_nop 0
	v_fma_f32 v6, -v4, v5, 1.0
	v_fmac_f32_e32 v5, v6, v5
	v_div_scale_f32 v6, vcc, 1.0, v1, 1.0
	v_mul_f32_e32 v7, v6, v5
	v_fma_f32 v10, -v4, v7, v6
	v_fmac_f32_e32 v7, v10, v5
	v_fma_f32 v4, -v4, v7, v6
	v_div_fmas_f32 v4, v4, v5, v7
	v_div_fixup_f32 v1, v4, v1, 1.0
	v_mul_f32_e32 v0, v0, v1
	ds_write_b32 v140, v0 offset:27648
	s_waitcnt vmcnt(5)
	v_mov_b32_e32 v0, v208
	v_mul_f32_e32 v1, 0xbfb8aa3b, v0
	v_exp_f32_e32 v1, v1
	s_nop 0
	v_add_f32_e32 v1, 1.0, v1
	v_div_scale_f32 v4, s[72:73], v1, v1, 1.0
	v_rcp_f32_e32 v5, v4
	s_nop 0
	v_fma_f32 v6, -v4, v5, 1.0
	v_fmac_f32_e32 v5, v6, v5
	v_div_scale_f32 v6, vcc, 1.0, v1, 1.0
	v_mul_f32_e32 v7, v6, v5
	v_fma_f32 v10, -v4, v7, v6
	v_fmac_f32_e32 v7, v10, v5
	v_fma_f32 v4, -v4, v7, v6
	v_div_fmas_f32 v4, v4, v5, v7
	v_div_fixup_f32 v1, v4, v1, 1.0
	v_mul_f32_e32 v0, v0, v1
	ds_write_b32 v140, v0 offset:28672
	s_waitcnt vmcnt(4)
	v_mov_b32_e32 v0, v209
	v_mul_f32_e32 v1, 0xbfb8aa3b, v0
	v_exp_f32_e32 v1, v1
	s_nop 0
	v_add_f32_e32 v1, 1.0, v1
	v_div_scale_f32 v4, s[72:73], v1, v1, 1.0
	v_rcp_f32_e32 v5, v4
	s_nop 0
	v_fma_f32 v6, -v4, v5, 1.0
	v_fmac_f32_e32 v5, v6, v5
	v_div_scale_f32 v6, vcc, 1.0, v1, 1.0
	v_mul_f32_e32 v7, v6, v5
	v_fma_f32 v10, -v4, v7, v6
	v_fmac_f32_e32 v7, v10, v5
	v_fma_f32 v4, -v4, v7, v6
	v_div_fmas_f32 v4, v4, v5, v7
	v_div_fixup_f32 v1, v4, v1, 1.0
	v_mul_f32_e32 v0, v0, v1
	ds_write_b32 v140, v0 offset:29696
	s_waitcnt vmcnt(3)
	v_mov_b32_e32 v0, v210
	v_mul_f32_e32 v1, 0xbfb8aa3b, v0
	v_exp_f32_e32 v1, v1
	s_nop 0
	v_add_f32_e32 v1, 1.0, v1
	v_div_scale_f32 v4, s[72:73], v1, v1, 1.0
	v_rcp_f32_e32 v5, v4
	s_nop 0
	v_fma_f32 v6, -v4, v5, 1.0
	v_fmac_f32_e32 v5, v6, v5
	v_div_scale_f32 v6, vcc, 1.0, v1, 1.0
	v_mul_f32_e32 v7, v6, v5
	v_fma_f32 v10, -v4, v7, v6
	v_fmac_f32_e32 v7, v10, v5
	v_fma_f32 v4, -v4, v7, v6
	v_div_fmas_f32 v4, v4, v5, v7
	v_div_fixup_f32 v1, v4, v1, 1.0
	v_mul_f32_e32 v0, v0, v1
	ds_write_b32 v140, v0 offset:30720
	s_waitcnt vmcnt(2)
	v_mov_b32_e32 v0, v211
	v_mul_f32_e32 v1, 0xbfb8aa3b, v0
	v_exp_f32_e32 v1, v1
	s_nop 0
	v_add_f32_e32 v1, 1.0, v1
	v_div_scale_f32 v4, s[72:73], v1, v1, 1.0
	v_rcp_f32_e32 v5, v4
	s_nop 0
	v_fma_f32 v6, -v4, v5, 1.0
	v_fmac_f32_e32 v5, v6, v5
	v_div_scale_f32 v6, vcc, 1.0, v1, 1.0
	v_mul_f32_e32 v7, v6, v5
	v_fma_f32 v10, -v4, v7, v6
	v_fmac_f32_e32 v7, v10, v5
	v_fma_f32 v4, -v4, v7, v6
	v_div_fmas_f32 v4, v4, v5, v7
	v_div_fixup_f32 v1, v4, v1, 1.0
	v_mul_f32_e32 v0, v0, v1
	ds_write_b32 v140, v0 offset:31744
	s_waitcnt vmcnt(1)
	v_mov_b32_e32 v0, v212
	v_mul_f32_e32 v1, 0xbfb8aa3b, v0
	v_exp_f32_e32 v1, v1
	s_nop 0
	v_add_f32_e32 v1, 1.0, v1
	v_div_scale_f32 v4, s[72:73], v1, v1, 1.0
	v_rcp_f32_e32 v5, v4
	s_nop 0
	v_fma_f32 v6, -v4, v5, 1.0
	v_fmac_f32_e32 v5, v6, v5
	v_div_scale_f32 v6, vcc, 1.0, v1, 1.0
	v_mul_f32_e32 v7, v6, v5
	v_fma_f32 v10, -v4, v7, v6
	v_fmac_f32_e32 v7, v10, v5
	v_fma_f32 v4, -v4, v7, v6
	v_div_fmas_f32 v4, v4, v5, v7
	v_div_fixup_f32 v1, v4, v1, 1.0
	v_mul_f32_e32 v0, v0, v1
	ds_write_b32 v140, v0 offset:32768
	s_waitcnt vmcnt(0)
	v_mov_b32_e32 v0, v213
	v_mul_f32_e32 v1, 0xbfb8aa3b, v0
	v_exp_f32_e32 v1, v1
	s_nop 0
	v_add_f32_e32 v1, 1.0, v1
	v_div_scale_f32 v4, s[72:73], v1, v1, 1.0
	v_rcp_f32_e32 v5, v4
	s_nop 0
	v_fma_f32 v6, -v4, v5, 1.0
	v_fmac_f32_e32 v5, v6, v5
	v_div_scale_f32 v6, vcc, 1.0, v1, 1.0
	v_mul_f32_e32 v7, v6, v5
	v_fma_f32 v10, -v4, v7, v6
	v_fmac_f32_e32 v7, v10, v5
	v_fma_f32 v4, -v4, v7, v6
	v_div_fmas_f32 v4, v4, v5, v7
	v_div_fixup_f32 v1, v4, v1, 1.0
	v_mul_f32_e32 v0, v0, v1
	ds_write_b32 v140, v0 offset:33792

.LBB0_147:
	v_lshl_add_u64 v[106:107], v[76:77], 0, s[68:69]
	v_add_co_u32_e32 v212, vcc, 0x30000, v106
	s_nop 1
	v_addc_co_u32_e32 v213, vcc, 0, v107, vcc
	global_load_dwordx4 v[180:183], v[212:213], off
	v_add_co_u32_e32 v212, vcc, 0x36000, v106
	s_nop 1
	v_addc_co_u32_e32 v213, vcc, 0, v107, vcc
	global_load_dwordx4 v[184:187], v[212:213], off
	v_add_co_u32_e32 v212, vcc, 0x3c000, v106
	s_nop 1
	v_addc_co_u32_e32 v213, vcc, 0, v107, vcc
	global_load_dwordx4 v[188:191], v[212:213], off
	v_add_co_u32_e32 v212, vcc, 0x42000, v106
	s_nop 1
	v_addc_co_u32_e32 v213, vcc, 0, v107, vcc
	global_load_dwordx4 v[192:195], v[212:213], off
	v_add_co_u32_e32 v212, vcc, 0x48000, v106
	s_nop 1
	v_addc_co_u32_e32 v213, vcc, 0, v107, vcc
	global_load_dwordx4 v[196:199], v[212:213], off
	v_add_co_u32_e32 v212, vcc, 0x4e000, v106
	s_nop 1
	v_addc_co_u32_e32 v213, vcc, 0, v107, vcc
	global_load_dwordx4 v[200:203], v[212:213], off
	v_add_co_u32_e32 v212, vcc, 0x54000, v106
	s_nop 1
	v_addc_co_u32_e32 v213, vcc, 0, v107, vcc
	global_load_dwordx4 v[204:207], v[212:213], off
	v_add_co_u32_e32 v212, vcc, 0x5a000, v106
	s_nop 1
	v_addc_co_u32_e32 v213, vcc, 0, v107, vcc
	global_load_dwordx4 v[208:211], v[212:213], off
	ds_read_b128 v[4:7], v72
	ds_read_b128 v[0:3], v72 offset:16
	s_mov_b32 s24, 0xc000
	s_add_u32 s68, s68, 0x30000
	s_addc_u32 s69, s69, 0
	s_cmp_eq_u32 s68, 0xc0000
	s_waitcnt vmcnt(8) lgkmcnt(1)
	v_mov_b64_e32 v[112:113], v[216:217]
	v_mov_b64_e32 v[114:115], v[218:219]
	v_pk_fma_f32 v[108:109], v[114:115], v[4:5], v[8:9] op_sel_hi:[1,0,1]
	ds_read_b128 v[8:11], v72 offset:2048
	v_pk_fma_f32 v[104:105], v[112:113], v[4:5], v[104:105] op_sel_hi:[1,0,1]
	s_waitcnt lgkmcnt(0)
	v_pk_fma_f32 v[116:117], v[114:115], v[8:9], v[12:13] op_sel_hi:[1,0,1]
	ds_read_b128 v[12:15], v72 offset:4096
	v_pk_fma_f32 v[102:103], v[112:113], v[8:9], v[102:103] op_sel_hi:[1,0,1]
	s_waitcnt lgkmcnt(0)
	v_pk_fma_f32 v[118:119], v[114:115], v[12:13], v[16:17] op_sel_hi:[1,0,1]
	ds_read_b128 v[16:19], v72 offset:6144
	v_pk_fma_f32 v[100:101], v[112:113], v[12:13], v[100:101] op_sel_hi:[1,0,1]
	s_waitcnt lgkmcnt(0)
	v_pk_fma_f32 v[120:121], v[114:115], v[16:17], v[20:21] op_sel_hi:[1,0,1]
	ds_read_b128 v[20:23], v72 offset:8192
	v_pk_fma_f32 v[98:99], v[112:113], v[16:17], v[98:99] op_sel_hi:[1,0,1]
	s_waitcnt lgkmcnt(0)
	v_pk_fma_f32 v[122:123], v[114:115], v[20:21], v[24:25] op_sel_hi:[1,0,1]
	ds_read_b128 v[24:27], v72 offset:10240
	v_pk_fma_f32 v[96:97], v[112:113], v[20:21], v[96:97] op_sel_hi:[1,0,1]
	s_waitcnt lgkmcnt(0)
	v_pk_fma_f32 v[124:125], v[114:115], v[24:25], v[28:29] op_sel_hi:[1,0,1]
	ds_read_b128 v[28:31], v72 offset:12288
	v_pk_fma_f32 v[94:95], v[112:113], v[24:25], v[94:95] op_sel_hi:[1,0,1]
	s_waitcnt lgkmcnt(0)
	v_pk_fma_f32 v[126:127], v[114:115], v[28:29], v[32:33] op_sel_hi:[1,0,1]
	ds_read_b128 v[32:35], v72 offset:14336
	v_pk_fma_f32 v[92:93], v[112:113], v[28:29], v[92:93] op_sel_hi:[1,0,1]
	s_waitcnt lgkmcnt(0)
	v_pk_fma_f32 v[128:129], v[114:115], v[32:33], v[36:37] op_sel_hi:[1,0,1]
	ds_read_b128 v[36:39], v72 offset:16384
	v_pk_fma_f32 v[90:91], v[112:113], v[32:33], v[90:91] op_sel_hi:[1,0,1]
	s_waitcnt lgkmcnt(0)
	v_pk_fma_f32 v[130:131], v[114:115], v[36:37], v[40:41] op_sel_hi:[1,0,1]
	ds_read_b128 v[40:43], v72 offset:18432
	v_pk_fma_f32 v[88:89], v[112:113], v[36:37], v[88:89] op_sel_hi:[1,0,1]
	s_waitcnt lgkmcnt(0)
	v_pk_fma_f32 v[132:133], v[114:115], v[40:41], v[44:45] op_sel_hi:[1,0,1]
	ds_read_b128 v[44:47], v72 offset:20480
	v_pk_fma_f32 v[86:87], v[112:113], v[40:41], v[86:87] op_sel_hi:[1,0,1]
	s_waitcnt lgkmcnt(0)
	v_pk_fma_f32 v[134:135], v[114:115], v[44:45], v[48:49] op_sel_hi:[1,0,1]
	ds_read_b128 v[48:51], v72 offset:22528
	v_pk_fma_f32 v[84:85], v[112:113], v[44:45], v[84:85] op_sel_hi:[1,0,1]
	s_waitcnt lgkmcnt(0)
	v_pk_fma_f32 v[136:137], v[114:115], v[48:49], v[52:53] op_sel_hi:[1,0,1]
	ds_read_b128 v[52:55], v72 offset:24576
	v_pk_fma_f32 v[82:83], v[112:113], v[48:49], v[82:83] op_sel_hi:[1,0,1]
	s_waitcnt lgkmcnt(0)
	v_pk_fma_f32 v[146:147], v[112:113], v[52:53], v[58:59] op_sel_hi:[1,0,1]
	v_pk_fma_f32 v[148:149], v[114:115], v[52:53], v[56:57] op_sel_hi:[1,0,1]
	ds_read_b128 v[56:59], v72 offset:26624
	s_waitcnt lgkmcnt(0)
	v_pk_fma_f32 v[150:151], v[112:113], v[56:57], v[62:63] op_sel_hi:[1,0,1]
	v_pk_fma_f32 v[152:153], v[114:115], v[56:57], v[60:61] op_sel_hi:[1,0,1]
	ds_read_b128 v[60:63], v72 offset:28672
	s_waitcnt lgkmcnt(0)
	v_pk_fma_f32 v[154:155], v[112:113], v[60:61], v[66:67] op_sel_hi:[1,0,1]
	v_pk_fma_f32 v[156:157], v[114:115], v[60:61], v[64:65] op_sel_hi:[1,0,1]
	ds_read_b128 v[64:67], v72 offset:30720
	s_waitcnt lgkmcnt(0)
	v_pk_fma_f32 v[158:159], v[112:113], v[64:65], v[70:71] op_sel_hi:[1,0,1]
	v_pk_fma_f32 v[160:161], v[114:115], v[64:65], v[68:69] op_sel_hi:[1,0,1]
	ds_read_b128 v[68:71], v72 offset:32768
	s_waitcnt lgkmcnt(0)
	v_pk_fma_f32 v[114:115], v[114:115], v[68:69], v[78:79] op_sel_hi:[1,0,1]
	v_add_co_u32_e32 v78, vcc, s75, v106
	v_pk_fma_f32 v[112:113], v[112:113], v[68:69], v[80:81] op_sel_hi:[1,0,1]
	s_nop 0
	v_addc_co_u32_e32 v79, vcc, 0, v107, vcc
	s_waitcnt vmcnt(8)
	v_mov_b64_e32 v[78:79], v[220:221]
	v_mov_b64_e32 v[80:81], v[222:223]
	v_pk_fma_f32 v[104:105], v[78:79], v[4:5], v[104:105] op_sel:[0,1,0]
	v_pk_fma_f32 v[4:5], v[80:81], v[4:5], v[108:109] op_sel:[0,1,0]
	v_pk_fma_f32 v[102:103], v[78:79], v[8:9], v[102:103] op_sel:[0,1,0]
	v_pk_fma_f32 v[8:9], v[80:81], v[8:9], v[116:117] op_sel:[0,1,0]
	v_pk_fma_f32 v[100:101], v[78:79], v[12:13], v[100:101] op_sel:[0,1,0]
	v_pk_fma_f32 v[12:13], v[80:81], v[12:13], v[118:119] op_sel:[0,1,0]
	v_pk_fma_f32 v[98:99], v[78:79], v[16:17], v[98:99] op_sel:[0,1,0]
	v_pk_fma_f32 v[16:17], v[80:81], v[16:17], v[120:121] op_sel:[0,1,0]
	v_pk_fma_f32 v[96:97], v[78:79], v[20:21], v[96:97] op_sel:[0,1,0]
	v_pk_fma_f32 v[94:95], v[78:79], v[24:25], v[94:95] op_sel:[0,1,0]
	v_pk_fma_f32 v[92:93], v[78:79], v[28:29], v[92:93] op_sel:[0,1,0]
	v_pk_fma_f32 v[90:91], v[78:79], v[32:33], v[90:91] op_sel:[0,1,0]
	v_pk_fma_f32 v[88:89], v[78:79], v[36:37], v[88:89] op_sel:[0,1,0]
	v_pk_fma_f32 v[86:87], v[78:79], v[40:41], v[86:87] op_sel:[0,1,0]
	v_pk_fma_f32 v[84:85], v[78:79], v[44:45], v[84:85] op_sel:[0,1,0]
	v_pk_fma_f32 v[82:83], v[78:79], v[48:49], v[82:83] op_sel:[0,1,0]
	v_pk_fma_f32 v[108:109], v[78:79], v[52:53], v[146:147] op_sel:[0,1,0]
	v_pk_fma_f32 v[116:117], v[78:79], v[56:57], v[150:151] op_sel:[0,1,0]
	v_pk_fma_f32 v[118:119], v[78:79], v[60:61], v[154:155] op_sel:[0,1,0]
	v_pk_fma_f32 v[120:121], v[78:79], v[64:65], v[158:159] op_sel:[0,1,0]
	v_pk_fma_f32 v[112:113], v[78:79], v[68:69], v[112:113] op_sel:[0,1,0]
	v_add_co_u32_e32 v78, vcc, s24, v106
	v_pk_fma_f32 v[20:21], v[80:81], v[20:21], v[122:123] op_sel:[0,1,0]
	s_nop 0
	v_addc_co_u32_e32 v79, vcc, 0, v107, vcc
	v_pk_fma_f32 v[24:25], v[80:81], v[24:25], v[124:125] op_sel:[0,1,0]
	v_pk_fma_f32 v[28:29], v[80:81], v[28:29], v[126:127] op_sel:[0,1,0]
	v_pk_fma_f32 v[32:33], v[80:81], v[32:33], v[128:129] op_sel:[0,1,0]
	v_pk_fma_f32 v[36:37], v[80:81], v[36:37], v[130:131] op_sel:[0,1,0]
	v_pk_fma_f32 v[40:41], v[80:81], v[40:41], v[132:133] op_sel:[0,1,0]
	v_pk_fma_f32 v[44:45], v[80:81], v[44:45], v[134:135] op_sel:[0,1,0]
	v_pk_fma_f32 v[48:49], v[80:81], v[48:49], v[136:137] op_sel:[0,1,0]
	v_pk_fma_f32 v[52:53], v[80:81], v[52:53], v[148:149] op_sel:[0,1,0]
	v_pk_fma_f32 v[56:57], v[80:81], v[56:57], v[152:153] op_sel:[0,1,0]
	v_pk_fma_f32 v[60:61], v[80:81], v[60:61], v[156:157] op_sel:[0,1,0]
	v_pk_fma_f32 v[64:65], v[80:81], v[64:65], v[160:161] op_sel:[0,1,0]
	v_pk_fma_f32 v[68:69], v[80:81], v[68:69], v[114:115] op_sel:[0,1,0]
	s_mov_b32 s24, 0x12000
	s_waitcnt vmcnt(8)
	v_mov_b64_e32 v[78:79], v[224:225]
	v_mov_b64_e32 v[80:81], v[226:227]
	v_pk_fma_f32 v[122:123], v[80:81], v[14:15], v[12:13] op_sel_hi:[1,0,1]
	v_add_co_u32_e32 v12, vcc, s24, v106
	v_pk_fma_f32 v[156:157], v[78:79], v[70:71], v[112:113] op_sel_hi:[1,0,1]
	s_nop 0
	v_addc_co_u32_e32 v13, vcc, 0, v107, vcc
	v_pk_fma_f32 v[104:105], v[78:79], v[6:7], v[104:105] op_sel_hi:[1,0,1]
	v_pk_fma_f32 v[4:5], v[80:81], v[6:7], v[4:5] op_sel_hi:[1,0,1]
	v_mov_b32_e32 v6, v7
	v_pk_fma_f32 v[102:103], v[78:79], v[10:11], v[102:103] op_sel_hi:[1,0,1]
	v_pk_fma_f32 v[8:9], v[80:81], v[10:11], v[8:9] op_sel_hi:[1,0,1]
	v_pk_fma_f32 v[100:101], v[78:79], v[14:15], v[100:101] op_sel_hi:[1,0,1]
	v_pk_fma_f32 v[150:151], v[78:79], v[54:55], v[108:109] op_sel_hi:[1,0,1]
	v_pk_fma_f32 v[98:99], v[78:79], v[18:19], v[98:99] op_sel_hi:[1,0,1]
	v_pk_fma_f32 v[124:125], v[80:81], v[18:19], v[16:17] op_sel_hi:[1,0,1]
	v_pk_fma_f32 v[96:97], v[78:79], v[22:23], v[96:97] op_sel_hi:[1,0,1]
	v_pk_fma_f32 v[126:127], v[80:81], v[22:23], v[20:21] op_sel_hi:[1,0,1]
	v_pk_fma_f32 v[94:95], v[78:79], v[26:27], v[94:95] op_sel_hi:[1,0,1]
	v_pk_fma_f32 v[128:129], v[80:81], v[26:27], v[24:25] op_sel_hi:[1,0,1]
	v_pk_fma_f32 v[92:93], v[78:79], v[30:31], v[92:93] op_sel_hi:[1,0,1]
	v_pk_fma_f32 v[130:131], v[80:81], v[30:31], v[28:29] op_sel_hi:[1,0,1]
	v_pk_fma_f32 v[90:91], v[78:79], v[34:35], v[90:91] op_sel_hi:[1,0,1]
	v_pk_fma_f32 v[132:133], v[80:81], v[34:35], v[32:33] op_sel_hi:[1,0,1]
	v_pk_fma_f32 v[88:89], v[78:79], v[38:39], v[88:89] op_sel_hi:[1,0,1]
	v_pk_fma_f32 v[134:135], v[80:81], v[38:39], v[36:37] op_sel_hi:[1,0,1]
	v_pk_fma_f32 v[86:87], v[78:79], v[42:43], v[86:87] op_sel_hi:[1,0,1]
	v_pk_fma_f32 v[136:137], v[80:81], v[42:43], v[40:41] op_sel_hi:[1,0,1]
	v_pk_fma_f32 v[84:85], v[78:79], v[46:47], v[84:85] op_sel_hi:[1,0,1]
	v_pk_fma_f32 v[146:147], v[80:81], v[46:47], v[44:45] op_sel_hi:[1,0,1]
	v_pk_fma_f32 v[82:83], v[78:79], v[50:51], v[82:83] op_sel_hi:[1,0,1]
	v_pk_fma_f32 v[148:149], v[80:81], v[50:51], v[48:49] op_sel_hi:[1,0,1]
	v_pk_fma_f32 v[152:153], v[80:81], v[54:55], v[52:53] op_sel_hi:[1,0,1]
	v_pk_fma_f32 v[116:117], v[78:79], v[58:59], v[116:117] op_sel_hi:[1,0,1]
	v_pk_fma_f32 v[56:57], v[80:81], v[58:59], v[56:57] op_sel_hi:[1,0,1]
	v_pk_fma_f32 v[118:119], v[78:79], v[62:63], v[118:119] op_sel_hi:[1,0,1]
	v_pk_fma_f32 v[60:61], v[80:81], v[62:63], v[60:61] op_sel_hi:[1,0,1]
	v_pk_fma_f32 v[120:121], v[78:79], v[66:67], v[120:121] op_sel_hi:[1,0,1]
	v_pk_fma_f32 v[154:155], v[80:81], v[66:67], v[64:65] op_sel_hi:[1,0,1]
	v_pk_fma_f32 v[158:159], v[80:81], v[70:71], v[68:69] op_sel_hi:[1,0,1]
	s_mov_b32 s24, 0x18000
	s_waitcnt vmcnt(8)
	v_mov_b64_e32 v[112:113], v[228:229]
	v_mov_b64_e32 v[114:115], v[230:231]
	v_pk_fma_f32 v[162:163], v[114:115], v[6:7], v[4:5] op_sel_hi:[1,0,1]
	v_mov_b32_e32 v4, v11
	v_pk_fma_f32 v[12:13], v[112:113], v[4:5], v[102:103] op_sel_hi:[1,0,1]
	v_pk_fma_f32 v[108:109], v[114:115], v[4:5], v[8:9] op_sel_hi:[1,0,1]
	v_mov_b32_e32 v4, v15
	v_pk_fma_f32 v[160:161], v[112:113], v[6:7], v[104:105] op_sel_hi:[1,0,1]
	v_pk_fma_f32 v[16:17], v[112:113], v[4:5], v[100:101] op_sel_hi:[1,0,1]
	v_pk_fma_f32 v[104:105], v[114:115], v[4:5], v[122:123] op_sel_hi:[1,0,1]
	v_mov_b32_e32 v4, v19
	v_pk_fma_f32 v[20:21], v[112:113], v[4:5], v[98:99] op_sel_hi:[1,0,1]
	v_pk_fma_f32 v[102:103], v[114:115], v[4:5], v[124:125] op_sel_hi:[1,0,1]
	v_mov_b32_e32 v4, v23
	v_pk_fma_f32 v[24:25], v[112:113], v[4:5], v[96:97] op_sel_hi:[1,0,1]
	v_pk_fma_f32 v[100:101], v[114:115], v[4:5], v[126:127] op_sel_hi:[1,0,1]
	v_mov_b32_e32 v4, v27
	v_pk_fma_f32 v[28:29], v[112:113], v[4:5], v[94:95] op_sel_hi:[1,0,1]
	v_pk_fma_f32 v[98:99], v[114:115], v[4:5], v[128:129] op_sel_hi:[1,0,1]
	v_mov_b32_e32 v4, v31
	v_pk_fma_f32 v[32:33], v[112:113], v[4:5], v[92:93] op_sel_hi:[1,0,1]
	v_pk_fma_f32 v[96:97], v[114:115], v[4:5], v[130:131] op_sel_hi:[1,0,1]
	v_mov_b32_e32 v4, v35
	v_pk_fma_f32 v[36:37], v[112:113], v[4:5], v[90:91] op_sel_hi:[1,0,1]
	v_pk_fma_f32 v[94:95], v[114:115], v[4:5], v[132:133] op_sel_hi:[1,0,1]
	v_mov_b32_e32 v4, v39
	v_pk_fma_f32 v[40:41], v[112:113], v[4:5], v[88:89] op_sel_hi:[1,0,1]
	v_pk_fma_f32 v[92:93], v[114:115], v[4:5], v[134:135] op_sel_hi:[1,0,1]
	v_mov_b32_e32 v4, v43
	v_pk_fma_f32 v[44:45], v[112:113], v[4:5], v[86:87] op_sel_hi:[1,0,1]
	v_pk_fma_f32 v[90:91], v[114:115], v[4:5], v[136:137] op_sel_hi:[1,0,1]
	v_mov_b32_e32 v4, v47
	v_pk_fma_f32 v[48:49], v[112:113], v[4:5], v[84:85] op_sel_hi:[1,0,1]
	v_pk_fma_f32 v[88:89], v[114:115], v[4:5], v[146:147] op_sel_hi:[1,0,1]
	v_mov_b32_e32 v4, v51
	v_pk_fma_f32 v[52:53], v[112:113], v[4:5], v[82:83] op_sel_hi:[1,0,1]
	v_pk_fma_f32 v[86:87], v[114:115], v[4:5], v[148:149] op_sel_hi:[1,0,1]
	v_mov_b32_e32 v4, v55
	v_pk_fma_f32 v[82:83], v[112:113], v[4:5], v[150:151] op_sel_hi:[1,0,1]
	v_pk_fma_f32 v[84:85], v[114:115], v[4:5], v[152:153] op_sel_hi:[1,0,1]
	v_mov_b32_e32 v4, v59
	v_pk_fma_f32 v[78:79], v[112:113], v[4:5], v[116:117] op_sel_hi:[1,0,1]
	v_pk_fma_f32 v[80:81], v[114:115], v[4:5], v[56:57] op_sel_hi:[1,0,1]
	v_mov_b32_e32 v4, v63
	v_pk_fma_f32 v[64:65], v[112:113], v[4:5], v[118:119] op_sel_hi:[1,0,1]
	v_pk_fma_f32 v[68:69], v[114:115], v[4:5], v[60:61] op_sel_hi:[1,0,1]
	v_mov_b32_e32 v4, v67
	v_pk_fma_f32 v[60:61], v[112:113], v[4:5], v[120:121] op_sel_hi:[1,0,1]
	v_pk_fma_f32 v[62:63], v[114:115], v[4:5], v[154:155] op_sel_hi:[1,0,1]
	v_mov_b32_e32 v4, v71
	v_pk_fma_f32 v[56:57], v[112:113], v[4:5], v[156:157] op_sel_hi:[1,0,1]
	v_pk_fma_f32 v[58:59], v[114:115], v[4:5], v[158:159] op_sel_hi:[1,0,1]
	v_add_co_u32_e32 v4, vcc, s24, v106
	ds_read_b128 v[8:11], v72 offset:2064
	ds_read_b128 v[120:123], v72 offset:32784
	v_addc_co_u32_e32 v5, vcc, 0, v107, vcc
	ds_read_b128 v[112:115], v72 offset:26640
	ds_read_b128 v[116:119], v72 offset:30736
	s_mov_b32 s24, 0x1e000
	s_waitcnt vmcnt(8) lgkmcnt(3)
	v_mov_b64_e32 v[4:5], v[232:233]
	v_mov_b64_e32 v[6:7], v[234:235]
	v_pk_fma_f32 v[124:125], v[4:5], v[8:9], v[12:13] op_sel_hi:[1,0,1]
	ds_read_b128 v[12:15], v72 offset:4112
	s_waitcnt lgkmcnt(2)
	v_pk_fma_f32 v[154:155], v[4:5], v[112:113], v[78:79] op_sel_hi:[1,0,1]
	v_pk_fma_f32 v[156:157], v[6:7], v[112:113], v[80:81] op_sel_hi:[1,0,1]
	ds_read_b128 v[78:81], v72 offset:28688
	v_pk_fma_f32 v[66:67], v[4:5], v[0:1], v[160:161] op_sel_hi:[1,0,1]
	s_waitcnt lgkmcnt(1)
	v_pk_fma_f32 v[126:127], v[4:5], v[12:13], v[16:17] op_sel_hi:[1,0,1]
	ds_read_b128 v[16:19], v72 offset:6160
	v_pk_fma_f32 v[60:61], v[4:5], v[116:117], v[60:61] op_sel_hi:[1,0,1]
	s_waitcnt lgkmcnt(1)
	v_pk_fma_f32 v[64:65], v[4:5], v[78:79], v[64:65] op_sel_hi:[1,0,1]
	v_pk_fma_f32 v[56:57], v[4:5], v[120:121], v[56:57] op_sel_hi:[1,0,1]
	v_pk_fma_f32 v[70:71], v[6:7], v[0:1], v[162:163] op_sel_hi:[1,0,1]
	s_waitcnt lgkmcnt(0)
	v_pk_fma_f32 v[128:129], v[4:5], v[16:17], v[20:21] op_sel_hi:[1,0,1]
	ds_read_b128 v[20:23], v72 offset:8208
	v_pk_fma_f32 v[108:109], v[6:7], v[8:9], v[108:109] op_sel_hi:[1,0,1]
	v_pk_fma_f32 v[104:105], v[6:7], v[12:13], v[104:105] op_sel_hi:[1,0,1]
	v_pk_fma_f32 v[102:103], v[6:7], v[16:17], v[102:103] op_sel_hi:[1,0,1]
	v_pk_fma_f32 v[68:69], v[6:7], v[78:79], v[68:69] op_sel_hi:[1,0,1]
	s_waitcnt lgkmcnt(0)
	v_pk_fma_f32 v[130:131], v[4:5], v[20:21], v[24:25] op_sel_hi:[1,0,1]
	ds_read_b128 v[24:27], v72 offset:10256
	v_pk_fma_f32 v[100:101], v[6:7], v[20:21], v[100:101] op_sel_hi:[1,0,1]
	v_pk_fma_f32 v[62:63], v[6:7], v[116:117], v[62:63] op_sel_hi:[1,0,1]
	v_pk_fma_f32 v[58:59], v[6:7], v[120:121], v[58:59] op_sel_hi:[1,0,1]
	s_waitcnt lgkmcnt(0)
	v_pk_fma_f32 v[132:133], v[4:5], v[24:25], v[28:29] op_sel_hi:[1,0,1]
	ds_read_b128 v[28:31], v72 offset:12304
	v_pk_fma_f32 v[98:99], v[6:7], v[24:25], v[98:99] op_sel_hi:[1,0,1]
	s_waitcnt lgkmcnt(0)
	v_pk_fma_f32 v[134:135], v[4:5], v[28:29], v[32:33] op_sel_hi:[1,0,1]
	ds_read_b128 v[32:35], v72 offset:14352
	v_pk_fma_f32 v[96:97], v[6:7], v[28:29], v[96:97] op_sel_hi:[1,0,1]
	s_waitcnt lgkmcnt(0)
	v_pk_fma_f32 v[136:137], v[4:5], v[32:33], v[36:37] op_sel_hi:[1,0,1]
	ds_read_b128 v[36:39], v72 offset:16400
	v_pk_fma_f32 v[94:95], v[6:7], v[32:33], v[94:95] op_sel_hi:[1,0,1]
	s_waitcnt lgkmcnt(0)
	v_pk_fma_f32 v[146:147], v[4:5], v[36:37], v[40:41] op_sel_hi:[1,0,1]
	ds_read_b128 v[40:43], v72 offset:18448
	v_pk_fma_f32 v[92:93], v[6:7], v[36:37], v[92:93] op_sel_hi:[1,0,1]
	s_waitcnt lgkmcnt(0)
	v_pk_fma_f32 v[148:149], v[4:5], v[40:41], v[44:45] op_sel_hi:[1,0,1]
	ds_read_b128 v[44:47], v72 offset:20496
	v_pk_fma_f32 v[90:91], v[6:7], v[40:41], v[90:91] op_sel_hi:[1,0,1]
	s_waitcnt lgkmcnt(0)
	v_pk_fma_f32 v[150:151], v[4:5], v[44:45], v[48:49] op_sel_hi:[1,0,1]
	ds_read_b128 v[48:51], v72 offset:22544
	v_pk_fma_f32 v[88:89], v[6:7], v[44:45], v[88:89] op_sel_hi:[1,0,1]
	s_waitcnt lgkmcnt(0)
	v_pk_fma_f32 v[152:153], v[4:5], v[48:49], v[52:53] op_sel_hi:[1,0,1]
	ds_read_b128 v[52:55], v72 offset:24592
	v_pk_fma_f32 v[86:87], v[6:7], v[48:49], v[86:87] op_sel_hi:[1,0,1]
	v_add_u32_e32 v72, 32, v72
	s_waitcnt lgkmcnt(0)
	v_pk_fma_f32 v[82:83], v[4:5], v[52:53], v[82:83] op_sel_hi:[1,0,1]
	v_add_co_u32_e32 v4, vcc, s24, v106
	v_pk_fma_f32 v[84:85], v[6:7], v[52:53], v[84:85] op_sel_hi:[1,0,1]
	s_nop 0
	v_addc_co_u32_e32 v5, vcc, 0, v107, vcc
	s_mov_b32 s24, 0x24000
	s_waitcnt vmcnt(8)
	v_mov_b64_e32 v[4:5], v[236:237]
	v_mov_b64_e32 v[6:7], v[238:239]
	v_pk_fma_f32 v[66:67], v[4:5], v[0:1], v[66:67] op_sel:[0,1,0]
	v_pk_fma_f32 v[0:1], v[6:7], v[0:1], v[70:71] op_sel:[0,1,0]
	v_pk_fma_f32 v[70:71], v[4:5], v[8:9], v[124:125] op_sel:[0,1,0]
	v_pk_fma_f32 v[8:9], v[6:7], v[8:9], v[108:109] op_sel:[0,1,0]
	v_pk_fma_f32 v[108:109], v[4:5], v[12:13], v[126:127] op_sel:[0,1,0]
	v_pk_fma_f32 v[12:13], v[6:7], v[12:13], v[104:105] op_sel:[0,1,0]
	v_pk_fma_f32 v[104:105], v[4:5], v[16:17], v[128:129] op_sel:[0,1,0]
	v_pk_fma_f32 v[16:17], v[6:7], v[16:17], v[102:103] op_sel:[0,1,0]
	v_pk_fma_f32 v[102:103], v[4:5], v[20:21], v[130:131] op_sel:[0,1,0]
	v_pk_fma_f32 v[20:21], v[6:7], v[20:21], v[100:101] op_sel:[0,1,0]
	v_pk_fma_f32 v[100:101], v[4:5], v[24:25], v[132:133] op_sel:[0,1,0]
	v_pk_fma_f32 v[24:25], v[6:7], v[24:25], v[98:99] op_sel:[0,1,0]
	v_pk_fma_f32 v[98:99], v[4:5], v[28:29], v[134:135] op_sel:[0,1,0]
	v_pk_fma_f32 v[28:29], v[6:7], v[28:29], v[96:97] op_sel:[0,1,0]
	v_pk_fma_f32 v[96:97], v[4:5], v[32:33], v[136:137] op_sel:[0,1,0]
	v_pk_fma_f32 v[32:33], v[6:7], v[32:33], v[94:95] op_sel:[0,1,0]
	v_pk_fma_f32 v[94:95], v[4:5], v[36:37], v[146:147] op_sel:[0,1,0]
	v_pk_fma_f32 v[36:37], v[6:7], v[36:37], v[92:93] op_sel:[0,1,0]
	v_pk_fma_f32 v[92:93], v[4:5], v[40:41], v[148:149] op_sel:[0,1,0]
	v_pk_fma_f32 v[40:41], v[6:7], v[40:41], v[90:91] op_sel:[0,1,0]
	v_pk_fma_f32 v[90:91], v[4:5], v[44:45], v[150:151] op_sel:[0,1,0]
	v_pk_fma_f32 v[44:45], v[6:7], v[44:45], v[88:89] op_sel:[0,1,0]
	v_pk_fma_f32 v[88:89], v[4:5], v[48:49], v[152:153] op_sel:[0,1,0]
	v_pk_fma_f32 v[82:83], v[4:5], v[52:53], v[82:83] op_sel:[0,1,0]
	v_pk_fma_f32 v[52:53], v[6:7], v[52:53], v[84:85] op_sel:[0,1,0]
	v_pk_fma_f32 v[84:85], v[4:5], v[112:113], v[154:155] op_sel:[0,1,0]
	v_pk_fma_f32 v[64:65], v[4:5], v[78:79], v[64:65] op_sel:[0,1,0]
	v_pk_fma_f32 v[60:61], v[4:5], v[116:117], v[60:61] op_sel:[0,1,0]
	v_pk_fma_f32 v[56:57], v[4:5], v[120:121], v[56:57] op_sel:[0,1,0]
	v_add_co_u32_e32 v4, vcc, s24, v106
	v_pk_fma_f32 v[48:49], v[6:7], v[48:49], v[86:87] op_sel:[0,1,0]
	s_nop 0
	v_addc_co_u32_e32 v5, vcc, 0, v107, vcc
	v_pk_fma_f32 v[86:87], v[6:7], v[112:113], v[156:157] op_sel:[0,1,0]
	v_pk_fma_f32 v[68:69], v[6:7], v[78:79], v[68:69] op_sel:[0,1,0]
	v_pk_fma_f32 v[62:63], v[6:7], v[116:117], v[62:63] op_sel:[0,1,0]
	v_pk_fma_f32 v[58:59], v[6:7], v[120:121], v[58:59] op_sel:[0,1,0]
	s_mov_b32 s24, 0x2a000
	s_waitcnt vmcnt(8)
	v_mov_b64_e32 v[4:5], v[240:241]
	v_mov_b64_e32 v[6:7], v[242:243]
	v_pk_fma_f32 v[66:67], v[4:5], v[2:3], v[66:67] op_sel_hi:[1,0,1]
	v_pk_fma_f32 v[70:71], v[4:5], v[10:11], v[70:71] op_sel_hi:[1,0,1]
	v_pk_fma_f32 v[108:109], v[4:5], v[14:15], v[108:109] op_sel_hi:[1,0,1]
	v_pk_fma_f32 v[116:117], v[4:5], v[18:19], v[104:105] op_sel_hi:[1,0,1]
	v_pk_fma_f32 v[124:125], v[4:5], v[22:23], v[102:103] op_sel_hi:[1,0,1]
	v_pk_fma_f32 v[128:129], v[4:5], v[26:27], v[100:101] op_sel_hi:[1,0,1]
	v_pk_fma_f32 v[132:133], v[4:5], v[30:31], v[98:99] op_sel_hi:[1,0,1]
	v_pk_fma_f32 v[136:137], v[4:5], v[34:35], v[96:97] op_sel_hi:[1,0,1]
	v_pk_fma_f32 v[148:149], v[4:5], v[38:39], v[94:95] op_sel_hi:[1,0,1]
	v_pk_fma_f32 v[152:153], v[4:5], v[42:43], v[92:93] op_sel_hi:[1,0,1]
	v_pk_fma_f32 v[156:157], v[4:5], v[46:47], v[90:91] op_sel_hi:[1,0,1]
	v_pk_fma_f32 v[160:161], v[4:5], v[50:51], v[88:89] op_sel_hi:[1,0,1]
	v_pk_fma_f32 v[164:165], v[4:5], v[54:55], v[82:83] op_sel_hi:[1,0,1]
	v_pk_fma_f32 v[168:169], v[4:5], v[114:115], v[84:85] op_sel_hi:[1,0,1]
	v_pk_fma_f32 v[64:65], v[4:5], v[80:81], v[64:65] op_sel_hi:[1,0,1]
	v_pk_fma_f32 v[172:173], v[4:5], v[118:119], v[60:61] op_sel_hi:[1,0,1]
	v_pk_fma_f32 v[176:177], v[4:5], v[122:123], v[56:57] op_sel_hi:[1,0,1]
	v_add_co_u32_e32 v4, vcc, s24, v106
	v_pk_fma_f32 v[0:1], v[6:7], v[2:3], v[0:1] op_sel_hi:[1,0,1]
	s_nop 0
	v_addc_co_u32_e32 v5, vcc, 0, v107, vcc
	v_pk_fma_f32 v[78:79], v[6:7], v[10:11], v[8:9] op_sel_hi:[1,0,1]
	v_pk_fma_f32 v[112:113], v[6:7], v[14:15], v[12:13] op_sel_hi:[1,0,1]
	v_pk_fma_f32 v[120:121], v[6:7], v[18:19], v[16:17] op_sel_hi:[1,0,1]
	v_pk_fma_f32 v[126:127], v[6:7], v[22:23], v[20:21] op_sel_hi:[1,0,1]
	v_pk_fma_f32 v[130:131], v[6:7], v[26:27], v[24:25] op_sel_hi:[1,0,1]
	v_pk_fma_f32 v[134:135], v[6:7], v[30:31], v[28:29] op_sel_hi:[1,0,1]
	v_pk_fma_f32 v[146:147], v[6:7], v[34:35], v[32:33] op_sel_hi:[1,0,1]
	v_pk_fma_f32 v[150:151], v[6:7], v[38:39], v[36:37] op_sel_hi:[1,0,1]
	v_pk_fma_f32 v[154:155], v[6:7], v[42:43], v[40:41] op_sel_hi:[1,0,1]
	v_pk_fma_f32 v[158:159], v[6:7], v[46:47], v[44:45] op_sel_hi:[1,0,1]
	v_pk_fma_f32 v[162:163], v[6:7], v[50:51], v[48:49] op_sel_hi:[1,0,1]
	v_pk_fma_f32 v[166:167], v[6:7], v[54:55], v[52:53] op_sel_hi:[1,0,1]
	v_pk_fma_f32 v[170:171], v[6:7], v[114:115], v[86:87] op_sel_hi:[1,0,1]
	v_pk_fma_f32 v[68:69], v[6:7], v[80:81], v[68:69] op_sel_hi:[1,0,1]
	v_pk_fma_f32 v[174:175], v[6:7], v[118:119], v[62:63] op_sel_hi:[1,0,1]
	v_pk_fma_f32 v[178:179], v[6:7], v[122:123], v[58:59] op_sel_hi:[1,0,1]
	v_mov_b32_e32 v2, v3
	s_waitcnt vmcnt(8)
	v_mov_b64_e32 v[4:5], v[244:245]
	v_mov_b64_e32 v[6:7], v[246:247]
	v_pk_fma_f32 v[8:9], v[6:7], v[2:3], v[0:1] op_sel_hi:[1,0,1]
	v_mov_b32_e32 v0, v11
	v_pk_fma_f32 v[102:103], v[4:5], v[0:1], v[70:71] op_sel_hi:[1,0,1]
	v_pk_fma_f32 v[12:13], v[6:7], v[0:1], v[78:79] op_sel_hi:[1,0,1]
	v_mov_b32_e32 v0, v15
	v_pk_fma_f32 v[100:101], v[4:5], v[0:1], v[108:109] op_sel_hi:[1,0,1]
	v_pk_fma_f32 v[16:17], v[6:7], v[0:1], v[112:113] op_sel_hi:[1,0,1]
	v_mov_b32_e32 v0, v19
	v_pk_fma_f32 v[98:99], v[4:5], v[0:1], v[116:117] op_sel_hi:[1,0,1]
	v_pk_fma_f32 v[20:21], v[6:7], v[0:1], v[120:121] op_sel_hi:[1,0,1]
	v_mov_b32_e32 v0, v23
	v_pk_fma_f32 v[96:97], v[4:5], v[0:1], v[124:125] op_sel_hi:[1,0,1]
	v_pk_fma_f32 v[24:25], v[6:7], v[0:1], v[126:127] op_sel_hi:[1,0,1]
	v_mov_b32_e32 v0, v27
	v_pk_fma_f32 v[94:95], v[4:5], v[0:1], v[128:129] op_sel_hi:[1,0,1]
	v_pk_fma_f32 v[28:29], v[6:7], v[0:1], v[130:131] op_sel_hi:[1,0,1]
	v_mov_b32_e32 v0, v31
	v_pk_fma_f32 v[92:93], v[4:5], v[0:1], v[132:133] op_sel_hi:[1,0,1]
	v_pk_fma_f32 v[32:33], v[6:7], v[0:1], v[134:135] op_sel_hi:[1,0,1]
	v_mov_b32_e32 v0, v35
	v_pk_fma_f32 v[90:91], v[4:5], v[0:1], v[136:137] op_sel_hi:[1,0,1]
	v_pk_fma_f32 v[36:37], v[6:7], v[0:1], v[146:147] op_sel_hi:[1,0,1]
	v_mov_b32_e32 v0, v39
	v_pk_fma_f32 v[88:89], v[4:5], v[0:1], v[148:149] op_sel_hi:[1,0,1]
	v_pk_fma_f32 v[40:41], v[6:7], v[0:1], v[150:151] op_sel_hi:[1,0,1]
	v_mov_b32_e32 v0, v43
	v_pk_fma_f32 v[86:87], v[4:5], v[0:1], v[152:153] op_sel_hi:[1,0,1]
	v_pk_fma_f32 v[44:45], v[6:7], v[0:1], v[154:155] op_sel_hi:[1,0,1]
	v_mov_b32_e32 v0, v47
	v_pk_fma_f32 v[84:85], v[4:5], v[0:1], v[156:157] op_sel_hi:[1,0,1]
	v_pk_fma_f32 v[48:49], v[6:7], v[0:1], v[158:159] op_sel_hi:[1,0,1]
	v_mov_b32_e32 v0, v51
	v_pk_fma_f32 v[82:83], v[4:5], v[0:1], v[160:161] op_sel_hi:[1,0,1]
	v_pk_fma_f32 v[52:53], v[6:7], v[0:1], v[162:163] op_sel_hi:[1,0,1]
	v_mov_b32_e32 v0, v55
	v_pk_fma_f32 v[58:59], v[4:5], v[0:1], v[164:165] op_sel_hi:[1,0,1]
	v_pk_fma_f32 v[56:57], v[6:7], v[0:1], v[166:167] op_sel_hi:[1,0,1]
	v_mov_b32_e32 v0, v115
	v_pk_fma_f32 v[62:63], v[4:5], v[0:1], v[168:169] op_sel_hi:[1,0,1]
	v_pk_fma_f32 v[60:61], v[6:7], v[0:1], v[170:171] op_sel_hi:[1,0,1]
	v_mov_b32_e32 v0, v81
	v_pk_fma_f32 v[104:105], v[4:5], v[2:3], v[66:67] op_sel_hi:[1,0,1]
	v_pk_fma_f32 v[66:67], v[4:5], v[0:1], v[64:65] op_sel_hi:[1,0,1]
	v_pk_fma_f32 v[64:65], v[6:7], v[0:1], v[68:69] op_sel_hi:[1,0,1]
	v_mov_b32_e32 v0, v119
	v_pk_fma_f32 v[70:71], v[4:5], v[0:1], v[172:173] op_sel_hi:[1,0,1]
	v_pk_fma_f32 v[68:69], v[6:7], v[0:1], v[174:175] op_sel_hi:[1,0,1]
	v_mov_b32_e32 v0, v123
	v_pk_fma_f32 v[80:81], v[4:5], v[0:1], v[176:177] op_sel_hi:[1,0,1]
	v_pk_fma_f32 v[78:79], v[6:7], v[0:1], v[178:179] op_sel_hi:[1,0,1]
	v_lshl_add_u64 v[106:107], v[76:77], 0, s[68:69]
	v_add_co_u32_e32 v212, vcc, 0x30000, v106
	s_nop 1
	v_addc_co_u32_e32 v213, vcc, 0, v107, vcc
	global_load_dwordx4 v[216:219], v[212:213], off
	v_add_co_u32_e32 v212, vcc, 0x36000, v106
	s_nop 1
	v_addc_co_u32_e32 v213, vcc, 0, v107, vcc
	global_load_dwordx4 v[220:223], v[212:213], off
	v_add_co_u32_e32 v212, vcc, 0x3c000, v106
	s_nop 1
	v_addc_co_u32_e32 v213, vcc, 0, v107, vcc
	global_load_dwordx4 v[224:227], v[212:213], off
	v_add_co_u32_e32 v212, vcc, 0x42000, v106
	s_nop 1
	v_addc_co_u32_e32 v213, vcc, 0, v107, vcc
	global_load_dwordx4 v[228:231], v[212:213], off
	v_add_co_u32_e32 v212, vcc, 0x48000, v106
	s_nop 1
	v_addc_co_u32_e32 v213, vcc, 0, v107, vcc
	global_load_dwordx4 v[232:235], v[212:213], off
	v_add_co_u32_e32 v212, vcc, 0x4e000, v106
	s_nop 1
	v_addc_co_u32_e32 v213, vcc, 0, v107, vcc
	global_load_dwordx4 v[236:239], v[212:213], off
	v_add_co_u32_e32 v212, vcc, 0x54000, v106
	s_nop 1
	v_addc_co_u32_e32 v213, vcc, 0, v107, vcc
	global_load_dwordx4 v[240:243], v[212:213], off
	v_add_co_u32_e32 v212, vcc, 0x5a000, v106
	s_nop 1
	v_addc_co_u32_e32 v213, vcc, 0, v107, vcc
	global_load_dwordx4 v[244:247], v[212:213], off
	ds_read_b128 v[4:7], v72
	ds_read_b128 v[0:3], v72 offset:16
	s_mov_b32 s24, 0xc000
	s_add_u32 s68, s68, 0x30000
	s_addc_u32 s69, s69, 0
	s_cmp_eq_u32 s68, 0xc0000
	s_waitcnt vmcnt(8) lgkmcnt(1)
	v_mov_b64_e32 v[112:113], v[180:181]
	v_mov_b64_e32 v[114:115], v[182:183]
	v_pk_fma_f32 v[108:109], v[114:115], v[4:5], v[8:9] op_sel_hi:[1,0,1]
	ds_read_b128 v[8:11], v72 offset:2048
	v_pk_fma_f32 v[104:105], v[112:113], v[4:5], v[104:105] op_sel_hi:[1,0,1]
	s_waitcnt lgkmcnt(0)
	v_pk_fma_f32 v[116:117], v[114:115], v[8:9], v[12:13] op_sel_hi:[1,0,1]
	ds_read_b128 v[12:15], v72 offset:4096
	v_pk_fma_f32 v[102:103], v[112:113], v[8:9], v[102:103] op_sel_hi:[1,0,1]
	s_waitcnt lgkmcnt(0)
	v_pk_fma_f32 v[118:119], v[114:115], v[12:13], v[16:17] op_sel_hi:[1,0,1]
	ds_read_b128 v[16:19], v72 offset:6144
	v_pk_fma_f32 v[100:101], v[112:113], v[12:13], v[100:101] op_sel_hi:[1,0,1]
	s_waitcnt lgkmcnt(0)
	v_pk_fma_f32 v[120:121], v[114:115], v[16:17], v[20:21] op_sel_hi:[1,0,1]
	ds_read_b128 v[20:23], v72 offset:8192
	v_pk_fma_f32 v[98:99], v[112:113], v[16:17], v[98:99] op_sel_hi:[1,0,1]
	s_waitcnt lgkmcnt(0)
	v_pk_fma_f32 v[122:123], v[114:115], v[20:21], v[24:25] op_sel_hi:[1,0,1]
	ds_read_b128 v[24:27], v72 offset:10240
	v_pk_fma_f32 v[96:97], v[112:113], v[20:21], v[96:97] op_sel_hi:[1,0,1]
	s_waitcnt lgkmcnt(0)
	v_pk_fma_f32 v[124:125], v[114:115], v[24:25], v[28:29] op_sel_hi:[1,0,1]
	ds_read_b128 v[28:31], v72 offset:12288
	v_pk_fma_f32 v[94:95], v[112:113], v[24:25], v[94:95] op_sel_hi:[1,0,1]
	s_waitcnt lgkmcnt(0)
	v_pk_fma_f32 v[126:127], v[114:115], v[28:29], v[32:33] op_sel_hi:[1,0,1]
	ds_read_b128 v[32:35], v72 offset:14336
	v_pk_fma_f32 v[92:93], v[112:113], v[28:29], v[92:93] op_sel_hi:[1,0,1]
	s_waitcnt lgkmcnt(0)
	v_pk_fma_f32 v[128:129], v[114:115], v[32:33], v[36:37] op_sel_hi:[1,0,1]
	ds_read_b128 v[36:39], v72 offset:16384
	v_pk_fma_f32 v[90:91], v[112:113], v[32:33], v[90:91] op_sel_hi:[1,0,1]
	s_waitcnt lgkmcnt(0)
	v_pk_fma_f32 v[130:131], v[114:115], v[36:37], v[40:41] op_sel_hi:[1,0,1]
	ds_read_b128 v[40:43], v72 offset:18432
	v_pk_fma_f32 v[88:89], v[112:113], v[36:37], v[88:89] op_sel_hi:[1,0,1]
	s_waitcnt lgkmcnt(0)
	v_pk_fma_f32 v[132:133], v[114:115], v[40:41], v[44:45] op_sel_hi:[1,0,1]
	ds_read_b128 v[44:47], v72 offset:20480
	v_pk_fma_f32 v[86:87], v[112:113], v[40:41], v[86:87] op_sel_hi:[1,0,1]
	s_waitcnt lgkmcnt(0)
	v_pk_fma_f32 v[134:135], v[114:115], v[44:45], v[48:49] op_sel_hi:[1,0,1]
	ds_read_b128 v[48:51], v72 offset:22528
	v_pk_fma_f32 v[84:85], v[112:113], v[44:45], v[84:85] op_sel_hi:[1,0,1]
	s_waitcnt lgkmcnt(0)
	v_pk_fma_f32 v[136:137], v[114:115], v[48:49], v[52:53] op_sel_hi:[1,0,1]
	ds_read_b128 v[52:55], v72 offset:24576
	v_pk_fma_f32 v[82:83], v[112:113], v[48:49], v[82:83] op_sel_hi:[1,0,1]
	s_waitcnt lgkmcnt(0)
	v_pk_fma_f32 v[146:147], v[112:113], v[52:53], v[58:59] op_sel_hi:[1,0,1]
	v_pk_fma_f32 v[148:149], v[114:115], v[52:53], v[56:57] op_sel_hi:[1,0,1]
	ds_read_b128 v[56:59], v72 offset:26624
	s_waitcnt lgkmcnt(0)
	v_pk_fma_f32 v[150:151], v[112:113], v[56:57], v[62:63] op_sel_hi:[1,0,1]
	v_pk_fma_f32 v[152:153], v[114:115], v[56:57], v[60:61] op_sel_hi:[1,0,1]
	ds_read_b128 v[60:63], v72 offset:28672
	s_waitcnt lgkmcnt(0)
	v_pk_fma_f32 v[154:155], v[112:113], v[60:61], v[66:67] op_sel_hi:[1,0,1]
	v_pk_fma_f32 v[156:157], v[114:115], v[60:61], v[64:65] op_sel_hi:[1,0,1]
	ds_read_b128 v[64:67], v72 offset:30720
	s_waitcnt lgkmcnt(0)
	v_pk_fma_f32 v[158:159], v[112:113], v[64:65], v[70:71] op_sel_hi:[1,0,1]
	v_pk_fma_f32 v[160:161], v[114:115], v[64:65], v[68:69] op_sel_hi:[1,0,1]
	ds_read_b128 v[68:71], v72 offset:32768
	s_waitcnt lgkmcnt(0)
	v_pk_fma_f32 v[114:115], v[114:115], v[68:69], v[78:79] op_sel_hi:[1,0,1]
	v_add_co_u32_e32 v78, vcc, s75, v106
	v_pk_fma_f32 v[112:113], v[112:113], v[68:69], v[80:81] op_sel_hi:[1,0,1]
	s_nop 0
	v_addc_co_u32_e32 v79, vcc, 0, v107, vcc
	s_waitcnt vmcnt(8)
	v_mov_b64_e32 v[78:79], v[184:185]
	v_mov_b64_e32 v[80:81], v[186:187]
	v_pk_fma_f32 v[104:105], v[78:79], v[4:5], v[104:105] op_sel:[0,1,0]
	v_pk_fma_f32 v[4:5], v[80:81], v[4:5], v[108:109] op_sel:[0,1,0]
	v_pk_fma_f32 v[102:103], v[78:79], v[8:9], v[102:103] op_sel:[0,1,0]
	v_pk_fma_f32 v[8:9], v[80:81], v[8:9], v[116:117] op_sel:[0,1,0]
	v_pk_fma_f32 v[100:101], v[78:79], v[12:13], v[100:101] op_sel:[0,1,0]
	v_pk_fma_f32 v[12:13], v[80:81], v[12:13], v[118:119] op_sel:[0,1,0]
	v_pk_fma_f32 v[98:99], v[78:79], v[16:17], v[98:99] op_sel:[0,1,0]
	v_pk_fma_f32 v[16:17], v[80:81], v[16:17], v[120:121] op_sel:[0,1,0]
	v_pk_fma_f32 v[96:97], v[78:79], v[20:21], v[96:97] op_sel:[0,1,0]
	v_pk_fma_f32 v[94:95], v[78:79], v[24:25], v[94:95] op_sel:[0,1,0]
	v_pk_fma_f32 v[92:93], v[78:79], v[28:29], v[92:93] op_sel:[0,1,0]
	v_pk_fma_f32 v[90:91], v[78:79], v[32:33], v[90:91] op_sel:[0,1,0]
	v_pk_fma_f32 v[88:89], v[78:79], v[36:37], v[88:89] op_sel:[0,1,0]
	v_pk_fma_f32 v[86:87], v[78:79], v[40:41], v[86:87] op_sel:[0,1,0]
	v_pk_fma_f32 v[84:85], v[78:79], v[44:45], v[84:85] op_sel:[0,1,0]
	v_pk_fma_f32 v[82:83], v[78:79], v[48:49], v[82:83] op_sel:[0,1,0]
	v_pk_fma_f32 v[108:109], v[78:79], v[52:53], v[146:147] op_sel:[0,1,0]
	v_pk_fma_f32 v[116:117], v[78:79], v[56:57], v[150:151] op_sel:[0,1,0]
	v_pk_fma_f32 v[118:119], v[78:79], v[60:61], v[154:155] op_sel:[0,1,0]
	v_pk_fma_f32 v[120:121], v[78:79], v[64:65], v[158:159] op_sel:[0,1,0]
	v_pk_fma_f32 v[112:113], v[78:79], v[68:69], v[112:113] op_sel:[0,1,0]
	v_add_co_u32_e32 v78, vcc, s24, v106
	v_pk_fma_f32 v[20:21], v[80:81], v[20:21], v[122:123] op_sel:[0,1,0]
	s_nop 0
	v_addc_co_u32_e32 v79, vcc, 0, v107, vcc
	v_pk_fma_f32 v[24:25], v[80:81], v[24:25], v[124:125] op_sel:[0,1,0]
	v_pk_fma_f32 v[28:29], v[80:81], v[28:29], v[126:127] op_sel:[0,1,0]
	v_pk_fma_f32 v[32:33], v[80:81], v[32:33], v[128:129] op_sel:[0,1,0]
	v_pk_fma_f32 v[36:37], v[80:81], v[36:37], v[130:131] op_sel:[0,1,0]
	v_pk_fma_f32 v[40:41], v[80:81], v[40:41], v[132:133] op_sel:[0,1,0]
	v_pk_fma_f32 v[44:45], v[80:81], v[44:45], v[134:135] op_sel:[0,1,0]
	v_pk_fma_f32 v[48:49], v[80:81], v[48:49], v[136:137] op_sel:[0,1,0]
	v_pk_fma_f32 v[52:53], v[80:81], v[52:53], v[148:149] op_sel:[0,1,0]
	v_pk_fma_f32 v[56:57], v[80:81], v[56:57], v[152:153] op_sel:[0,1,0]
	v_pk_fma_f32 v[60:61], v[80:81], v[60:61], v[156:157] op_sel:[0,1,0]
	v_pk_fma_f32 v[64:65], v[80:81], v[64:65], v[160:161] op_sel:[0,1,0]
	v_pk_fma_f32 v[68:69], v[80:81], v[68:69], v[114:115] op_sel:[0,1,0]
	s_mov_b32 s24, 0x12000
	s_waitcnt vmcnt(8)
	v_mov_b64_e32 v[78:79], v[188:189]
	v_mov_b64_e32 v[80:81], v[190:191]
	v_pk_fma_f32 v[122:123], v[80:81], v[14:15], v[12:13] op_sel_hi:[1,0,1]
	v_add_co_u32_e32 v12, vcc, s24, v106
	v_pk_fma_f32 v[156:157], v[78:79], v[70:71], v[112:113] op_sel_hi:[1,0,1]
	s_nop 0
	v_addc_co_u32_e32 v13, vcc, 0, v107, vcc
	v_pk_fma_f32 v[104:105], v[78:79], v[6:7], v[104:105] op_sel_hi:[1,0,1]
	v_pk_fma_f32 v[4:5], v[80:81], v[6:7], v[4:5] op_sel_hi:[1,0,1]
	v_mov_b32_e32 v6, v7
	v_pk_fma_f32 v[102:103], v[78:79], v[10:11], v[102:103] op_sel_hi:[1,0,1]
	v_pk_fma_f32 v[8:9], v[80:81], v[10:11], v[8:9] op_sel_hi:[1,0,1]
	v_pk_fma_f32 v[100:101], v[78:79], v[14:15], v[100:101] op_sel_hi:[1,0,1]
	v_pk_fma_f32 v[150:151], v[78:79], v[54:55], v[108:109] op_sel_hi:[1,0,1]
	v_pk_fma_f32 v[98:99], v[78:79], v[18:19], v[98:99] op_sel_hi:[1,0,1]
	v_pk_fma_f32 v[124:125], v[80:81], v[18:19], v[16:17] op_sel_hi:[1,0,1]
	v_pk_fma_f32 v[96:97], v[78:79], v[22:23], v[96:97] op_sel_hi:[1,0,1]
	v_pk_fma_f32 v[126:127], v[80:81], v[22:23], v[20:21] op_sel_hi:[1,0,1]
	v_pk_fma_f32 v[94:95], v[78:79], v[26:27], v[94:95] op_sel_hi:[1,0,1]
	v_pk_fma_f32 v[128:129], v[80:81], v[26:27], v[24:25] op_sel_hi:[1,0,1]
	v_pk_fma_f32 v[92:93], v[78:79], v[30:31], v[92:93] op_sel_hi:[1,0,1]
	v_pk_fma_f32 v[130:131], v[80:81], v[30:31], v[28:29] op_sel_hi:[1,0,1]
	v_pk_fma_f32 v[90:91], v[78:79], v[34:35], v[90:91] op_sel_hi:[1,0,1]
	v_pk_fma_f32 v[132:133], v[80:81], v[34:35], v[32:33] op_sel_hi:[1,0,1]
	v_pk_fma_f32 v[88:89], v[78:79], v[38:39], v[88:89] op_sel_hi:[1,0,1]
	v_pk_fma_f32 v[134:135], v[80:81], v[38:39], v[36:37] op_sel_hi:[1,0,1]
	v_pk_fma_f32 v[86:87], v[78:79], v[42:43], v[86:87] op_sel_hi:[1,0,1]
	v_pk_fma_f32 v[136:137], v[80:81], v[42:43], v[40:41] op_sel_hi:[1,0,1]
	v_pk_fma_f32 v[84:85], v[78:79], v[46:47], v[84:85] op_sel_hi:[1,0,1]
	v_pk_fma_f32 v[146:147], v[80:81], v[46:47], v[44:45] op_sel_hi:[1,0,1]
	v_pk_fma_f32 v[82:83], v[78:79], v[50:51], v[82:83] op_sel_hi:[1,0,1]
	v_pk_fma_f32 v[148:149], v[80:81], v[50:51], v[48:49] op_sel_hi:[1,0,1]
	v_pk_fma_f32 v[152:153], v[80:81], v[54:55], v[52:53] op_sel_hi:[1,0,1]
	v_pk_fma_f32 v[116:117], v[78:79], v[58:59], v[116:117] op_sel_hi:[1,0,1]
	v_pk_fma_f32 v[56:57], v[80:81], v[58:59], v[56:57] op_sel_hi:[1,0,1]
	v_pk_fma_f32 v[118:119], v[78:79], v[62:63], v[118:119] op_sel_hi:[1,0,1]
	v_pk_fma_f32 v[60:61], v[80:81], v[62:63], v[60:61] op_sel_hi:[1,0,1]
	v_pk_fma_f32 v[120:121], v[78:79], v[66:67], v[120:121] op_sel_hi:[1,0,1]
	v_pk_fma_f32 v[154:155], v[80:81], v[66:67], v[64:65] op_sel_hi:[1,0,1]
	v_pk_fma_f32 v[158:159], v[80:81], v[70:71], v[68:69] op_sel_hi:[1,0,1]
	s_mov_b32 s24, 0x18000
	s_waitcnt vmcnt(8)
	v_mov_b64_e32 v[112:113], v[192:193]
	v_mov_b64_e32 v[114:115], v[194:195]
	v_pk_fma_f32 v[162:163], v[114:115], v[6:7], v[4:5] op_sel_hi:[1,0,1]
	v_mov_b32_e32 v4, v11
	v_pk_fma_f32 v[12:13], v[112:113], v[4:5], v[102:103] op_sel_hi:[1,0,1]
	v_pk_fma_f32 v[108:109], v[114:115], v[4:5], v[8:9] op_sel_hi:[1,0,1]
	v_mov_b32_e32 v4, v15
	v_pk_fma_f32 v[160:161], v[112:113], v[6:7], v[104:105] op_sel_hi:[1,0,1]
	v_pk_fma_f32 v[16:17], v[112:113], v[4:5], v[100:101] op_sel_hi:[1,0,1]
	v_pk_fma_f32 v[104:105], v[114:115], v[4:5], v[122:123] op_sel_hi:[1,0,1]
	v_mov_b32_e32 v4, v19
	v_pk_fma_f32 v[20:21], v[112:113], v[4:5], v[98:99] op_sel_hi:[1,0,1]
	v_pk_fma_f32 v[102:103], v[114:115], v[4:5], v[124:125] op_sel_hi:[1,0,1]
	v_mov_b32_e32 v4, v23
	v_pk_fma_f32 v[24:25], v[112:113], v[4:5], v[96:97] op_sel_hi:[1,0,1]
	v_pk_fma_f32 v[100:101], v[114:115], v[4:5], v[126:127] op_sel_hi:[1,0,1]
	v_mov_b32_e32 v4, v27
	v_pk_fma_f32 v[28:29], v[112:113], v[4:5], v[94:95] op_sel_hi:[1,0,1]
	v_pk_fma_f32 v[98:99], v[114:115], v[4:5], v[128:129] op_sel_hi:[1,0,1]
	v_mov_b32_e32 v4, v31
	v_pk_fma_f32 v[32:33], v[112:113], v[4:5], v[92:93] op_sel_hi:[1,0,1]
	v_pk_fma_f32 v[96:97], v[114:115], v[4:5], v[130:131] op_sel_hi:[1,0,1]
	v_mov_b32_e32 v4, v35
	v_pk_fma_f32 v[36:37], v[112:113], v[4:5], v[90:91] op_sel_hi:[1,0,1]
	v_pk_fma_f32 v[94:95], v[114:115], v[4:5], v[132:133] op_sel_hi:[1,0,1]
	v_mov_b32_e32 v4, v39
	v_pk_fma_f32 v[40:41], v[112:113], v[4:5], v[88:89] op_sel_hi:[1,0,1]
	v_pk_fma_f32 v[92:93], v[114:115], v[4:5], v[134:135] op_sel_hi:[1,0,1]
	v_mov_b32_e32 v4, v43
	v_pk_fma_f32 v[44:45], v[112:113], v[4:5], v[86:87] op_sel_hi:[1,0,1]
	v_pk_fma_f32 v[90:91], v[114:115], v[4:5], v[136:137] op_sel_hi:[1,0,1]
	v_mov_b32_e32 v4, v47
	v_pk_fma_f32 v[48:49], v[112:113], v[4:5], v[84:85] op_sel_hi:[1,0,1]
	v_pk_fma_f32 v[88:89], v[114:115], v[4:5], v[146:147] op_sel_hi:[1,0,1]
	v_mov_b32_e32 v4, v51
	v_pk_fma_f32 v[52:53], v[112:113], v[4:5], v[82:83] op_sel_hi:[1,0,1]
	v_pk_fma_f32 v[86:87], v[114:115], v[4:5], v[148:149] op_sel_hi:[1,0,1]
	v_mov_b32_e32 v4, v55
	v_pk_fma_f32 v[82:83], v[112:113], v[4:5], v[150:151] op_sel_hi:[1,0,1]
	v_pk_fma_f32 v[84:85], v[114:115], v[4:5], v[152:153] op_sel_hi:[1,0,1]
	v_mov_b32_e32 v4, v59
	v_pk_fma_f32 v[78:79], v[112:113], v[4:5], v[116:117] op_sel_hi:[1,0,1]
	v_pk_fma_f32 v[80:81], v[114:115], v[4:5], v[56:57] op_sel_hi:[1,0,1]
	v_mov_b32_e32 v4, v63
	v_pk_fma_f32 v[64:65], v[112:113], v[4:5], v[118:119] op_sel_hi:[1,0,1]
	v_pk_fma_f32 v[68:69], v[114:115], v[4:5], v[60:61] op_sel_hi:[1,0,1]
	v_mov_b32_e32 v4, v67
	v_pk_fma_f32 v[60:61], v[112:113], v[4:5], v[120:121] op_sel_hi:[1,0,1]
	v_pk_fma_f32 v[62:63], v[114:115], v[4:5], v[154:155] op_sel_hi:[1,0,1]
	v_mov_b32_e32 v4, v71
	v_pk_fma_f32 v[56:57], v[112:113], v[4:5], v[156:157] op_sel_hi:[1,0,1]
	v_pk_fma_f32 v[58:59], v[114:115], v[4:5], v[158:159] op_sel_hi:[1,0,1]
	v_add_co_u32_e32 v4, vcc, s24, v106
	ds_read_b128 v[8:11], v72 offset:2064
	ds_read_b128 v[120:123], v72 offset:32784
	v_addc_co_u32_e32 v5, vcc, 0, v107, vcc
	ds_read_b128 v[112:115], v72 offset:26640
	ds_read_b128 v[116:119], v72 offset:30736
	s_mov_b32 s24, 0x1e000
	s_waitcnt vmcnt(8) lgkmcnt(3)
	v_mov_b64_e32 v[4:5], v[196:197]
	v_mov_b64_e32 v[6:7], v[198:199]
	v_pk_fma_f32 v[124:125], v[4:5], v[8:9], v[12:13] op_sel_hi:[1,0,1]
	ds_read_b128 v[12:15], v72 offset:4112
	s_waitcnt lgkmcnt(2)
	v_pk_fma_f32 v[154:155], v[4:5], v[112:113], v[78:79] op_sel_hi:[1,0,1]
	v_pk_fma_f32 v[156:157], v[6:7], v[112:113], v[80:81] op_sel_hi:[1,0,1]
	ds_read_b128 v[78:81], v72 offset:28688
	v_pk_fma_f32 v[66:67], v[4:5], v[0:1], v[160:161] op_sel_hi:[1,0,1]
	s_waitcnt lgkmcnt(1)
	v_pk_fma_f32 v[126:127], v[4:5], v[12:13], v[16:17] op_sel_hi:[1,0,1]
	ds_read_b128 v[16:19], v72 offset:6160
	v_pk_fma_f32 v[60:61], v[4:5], v[116:117], v[60:61] op_sel_hi:[1,0,1]
	s_waitcnt lgkmcnt(1)
	v_pk_fma_f32 v[64:65], v[4:5], v[78:79], v[64:65] op_sel_hi:[1,0,1]
	v_pk_fma_f32 v[56:57], v[4:5], v[120:121], v[56:57] op_sel_hi:[1,0,1]
	v_pk_fma_f32 v[70:71], v[6:7], v[0:1], v[162:163] op_sel_hi:[1,0,1]
	s_waitcnt lgkmcnt(0)
	v_pk_fma_f32 v[128:129], v[4:5], v[16:17], v[20:21] op_sel_hi:[1,0,1]
	ds_read_b128 v[20:23], v72 offset:8208
	v_pk_fma_f32 v[108:109], v[6:7], v[8:9], v[108:109] op_sel_hi:[1,0,1]
	v_pk_fma_f32 v[104:105], v[6:7], v[12:13], v[104:105] op_sel_hi:[1,0,1]
	v_pk_fma_f32 v[102:103], v[6:7], v[16:17], v[102:103] op_sel_hi:[1,0,1]
	v_pk_fma_f32 v[68:69], v[6:7], v[78:79], v[68:69] op_sel_hi:[1,0,1]
	s_waitcnt lgkmcnt(0)
	v_pk_fma_f32 v[130:131], v[4:5], v[20:21], v[24:25] op_sel_hi:[1,0,1]
	ds_read_b128 v[24:27], v72 offset:10256
	v_pk_fma_f32 v[100:101], v[6:7], v[20:21], v[100:101] op_sel_hi:[1,0,1]
	v_pk_fma_f32 v[62:63], v[6:7], v[116:117], v[62:63] op_sel_hi:[1,0,1]
	v_pk_fma_f32 v[58:59], v[6:7], v[120:121], v[58:59] op_sel_hi:[1,0,1]
	s_waitcnt lgkmcnt(0)
	v_pk_fma_f32 v[132:133], v[4:5], v[24:25], v[28:29] op_sel_hi:[1,0,1]
	ds_read_b128 v[28:31], v72 offset:12304
	v_pk_fma_f32 v[98:99], v[6:7], v[24:25], v[98:99] op_sel_hi:[1,0,1]
	s_waitcnt lgkmcnt(0)
	v_pk_fma_f32 v[134:135], v[4:5], v[28:29], v[32:33] op_sel_hi:[1,0,1]
	ds_read_b128 v[32:35], v72 offset:14352
	v_pk_fma_f32 v[96:97], v[6:7], v[28:29], v[96:97] op_sel_hi:[1,0,1]
	s_waitcnt lgkmcnt(0)
	v_pk_fma_f32 v[136:137], v[4:5], v[32:33], v[36:37] op_sel_hi:[1,0,1]
	ds_read_b128 v[36:39], v72 offset:16400
	v_pk_fma_f32 v[94:95], v[6:7], v[32:33], v[94:95] op_sel_hi:[1,0,1]
	s_waitcnt lgkmcnt(0)
	v_pk_fma_f32 v[146:147], v[4:5], v[36:37], v[40:41] op_sel_hi:[1,0,1]
	ds_read_b128 v[40:43], v72 offset:18448
	v_pk_fma_f32 v[92:93], v[6:7], v[36:37], v[92:93] op_sel_hi:[1,0,1]
	s_waitcnt lgkmcnt(0)
	v_pk_fma_f32 v[148:149], v[4:5], v[40:41], v[44:45] op_sel_hi:[1,0,1]
	ds_read_b128 v[44:47], v72 offset:20496
	v_pk_fma_f32 v[90:91], v[6:7], v[40:41], v[90:91] op_sel_hi:[1,0,1]
	s_waitcnt lgkmcnt(0)
	v_pk_fma_f32 v[150:151], v[4:5], v[44:45], v[48:49] op_sel_hi:[1,0,1]
	ds_read_b128 v[48:51], v72 offset:22544
	v_pk_fma_f32 v[88:89], v[6:7], v[44:45], v[88:89] op_sel_hi:[1,0,1]
	s_waitcnt lgkmcnt(0)
	v_pk_fma_f32 v[152:153], v[4:5], v[48:49], v[52:53] op_sel_hi:[1,0,1]
	ds_read_b128 v[52:55], v72 offset:24592
	v_pk_fma_f32 v[86:87], v[6:7], v[48:49], v[86:87] op_sel_hi:[1,0,1]
	v_add_u32_e32 v72, 32, v72
	s_waitcnt lgkmcnt(0)
	v_pk_fma_f32 v[82:83], v[4:5], v[52:53], v[82:83] op_sel_hi:[1,0,1]
	v_add_co_u32_e32 v4, vcc, s24, v106
	v_pk_fma_f32 v[84:85], v[6:7], v[52:53], v[84:85] op_sel_hi:[1,0,1]
	s_nop 0
	v_addc_co_u32_e32 v5, vcc, 0, v107, vcc
	s_mov_b32 s24, 0x24000
	s_waitcnt vmcnt(8)
	v_mov_b64_e32 v[4:5], v[200:201]
	v_mov_b64_e32 v[6:7], v[202:203]
	v_pk_fma_f32 v[66:67], v[4:5], v[0:1], v[66:67] op_sel:[0,1,0]
	v_pk_fma_f32 v[0:1], v[6:7], v[0:1], v[70:71] op_sel:[0,1,0]
	v_pk_fma_f32 v[70:71], v[4:5], v[8:9], v[124:125] op_sel:[0,1,0]
	v_pk_fma_f32 v[8:9], v[6:7], v[8:9], v[108:109] op_sel:[0,1,0]
	v_pk_fma_f32 v[108:109], v[4:5], v[12:13], v[126:127] op_sel:[0,1,0]
	v_pk_fma_f32 v[12:13], v[6:7], v[12:13], v[104:105] op_sel:[0,1,0]
	v_pk_fma_f32 v[104:105], v[4:5], v[16:17], v[128:129] op_sel:[0,1,0]
	v_pk_fma_f32 v[16:17], v[6:7], v[16:17], v[102:103] op_sel:[0,1,0]
	v_pk_fma_f32 v[102:103], v[4:5], v[20:21], v[130:131] op_sel:[0,1,0]
	v_pk_fma_f32 v[20:21], v[6:7], v[20:21], v[100:101] op_sel:[0,1,0]
	v_pk_fma_f32 v[100:101], v[4:5], v[24:25], v[132:133] op_sel:[0,1,0]
	v_pk_fma_f32 v[24:25], v[6:7], v[24:25], v[98:99] op_sel:[0,1,0]
	v_pk_fma_f32 v[98:99], v[4:5], v[28:29], v[134:135] op_sel:[0,1,0]
	v_pk_fma_f32 v[28:29], v[6:7], v[28:29], v[96:97] op_sel:[0,1,0]
	v_pk_fma_f32 v[96:97], v[4:5], v[32:33], v[136:137] op_sel:[0,1,0]
	v_pk_fma_f32 v[32:33], v[6:7], v[32:33], v[94:95] op_sel:[0,1,0]
	v_pk_fma_f32 v[94:95], v[4:5], v[36:37], v[146:147] op_sel:[0,1,0]
	v_pk_fma_f32 v[36:37], v[6:7], v[36:37], v[92:93] op_sel:[0,1,0]
	v_pk_fma_f32 v[92:93], v[4:5], v[40:41], v[148:149] op_sel:[0,1,0]
	v_pk_fma_f32 v[40:41], v[6:7], v[40:41], v[90:91] op_sel:[0,1,0]
	v_pk_fma_f32 v[90:91], v[4:5], v[44:45], v[150:151] op_sel:[0,1,0]
	v_pk_fma_f32 v[44:45], v[6:7], v[44:45], v[88:89] op_sel:[0,1,0]
	v_pk_fma_f32 v[88:89], v[4:5], v[48:49], v[152:153] op_sel:[0,1,0]
	v_pk_fma_f32 v[82:83], v[4:5], v[52:53], v[82:83] op_sel:[0,1,0]
	v_pk_fma_f32 v[52:53], v[6:7], v[52:53], v[84:85] op_sel:[0,1,0]
	v_pk_fma_f32 v[84:85], v[4:5], v[112:113], v[154:155] op_sel:[0,1,0]
	v_pk_fma_f32 v[64:65], v[4:5], v[78:79], v[64:65] op_sel:[0,1,0]
	v_pk_fma_f32 v[60:61], v[4:5], v[116:117], v[60:61] op_sel:[0,1,0]
	v_pk_fma_f32 v[56:57], v[4:5], v[120:121], v[56:57] op_sel:[0,1,0]
	v_add_co_u32_e32 v4, vcc, s24, v106
	v_pk_fma_f32 v[48:49], v[6:7], v[48:49], v[86:87] op_sel:[0,1,0]
	s_nop 0
	v_addc_co_u32_e32 v5, vcc, 0, v107, vcc
	v_pk_fma_f32 v[86:87], v[6:7], v[112:113], v[156:157] op_sel:[0,1,0]
	v_pk_fma_f32 v[68:69], v[6:7], v[78:79], v[68:69] op_sel:[0,1,0]
	v_pk_fma_f32 v[62:63], v[6:7], v[116:117], v[62:63] op_sel:[0,1,0]
	v_pk_fma_f32 v[58:59], v[6:7], v[120:121], v[58:59] op_sel:[0,1,0]
	s_mov_b32 s24, 0x2a000
	s_waitcnt vmcnt(8)
	v_mov_b64_e32 v[4:5], v[204:205]
	v_mov_b64_e32 v[6:7], v[206:207]
	v_pk_fma_f32 v[66:67], v[4:5], v[2:3], v[66:67] op_sel_hi:[1,0,1]
	v_pk_fma_f32 v[70:71], v[4:5], v[10:11], v[70:71] op_sel_hi:[1,0,1]
	v_pk_fma_f32 v[108:109], v[4:5], v[14:15], v[108:109] op_sel_hi:[1,0,1]
	v_pk_fma_f32 v[116:117], v[4:5], v[18:19], v[104:105] op_sel_hi:[1,0,1]
	v_pk_fma_f32 v[124:125], v[4:5], v[22:23], v[102:103] op_sel_hi:[1,0,1]
	v_pk_fma_f32 v[128:129], v[4:5], v[26:27], v[100:101] op_sel_hi:[1,0,1]
	v_pk_fma_f32 v[132:133], v[4:5], v[30:31], v[98:99] op_sel_hi:[1,0,1]
	v_pk_fma_f32 v[136:137], v[4:5], v[34:35], v[96:97] op_sel_hi:[1,0,1]
	v_pk_fma_f32 v[148:149], v[4:5], v[38:39], v[94:95] op_sel_hi:[1,0,1]
	v_pk_fma_f32 v[152:153], v[4:5], v[42:43], v[92:93] op_sel_hi:[1,0,1]
	v_pk_fma_f32 v[156:157], v[4:5], v[46:47], v[90:91] op_sel_hi:[1,0,1]
	v_pk_fma_f32 v[160:161], v[4:5], v[50:51], v[88:89] op_sel_hi:[1,0,1]
	v_pk_fma_f32 v[164:165], v[4:5], v[54:55], v[82:83] op_sel_hi:[1,0,1]
	v_pk_fma_f32 v[168:169], v[4:5], v[114:115], v[84:85] op_sel_hi:[1,0,1]
	v_pk_fma_f32 v[64:65], v[4:5], v[80:81], v[64:65] op_sel_hi:[1,0,1]
	v_pk_fma_f32 v[172:173], v[4:5], v[118:119], v[60:61] op_sel_hi:[1,0,1]
	v_pk_fma_f32 v[176:177], v[4:5], v[122:123], v[56:57] op_sel_hi:[1,0,1]
	v_add_co_u32_e32 v4, vcc, s24, v106
	v_pk_fma_f32 v[0:1], v[6:7], v[2:3], v[0:1] op_sel_hi:[1,0,1]
	s_nop 0
	v_addc_co_u32_e32 v5, vcc, 0, v107, vcc
	v_pk_fma_f32 v[78:79], v[6:7], v[10:11], v[8:9] op_sel_hi:[1,0,1]
	v_pk_fma_f32 v[112:113], v[6:7], v[14:15], v[12:13] op_sel_hi:[1,0,1]
	v_pk_fma_f32 v[120:121], v[6:7], v[18:19], v[16:17] op_sel_hi:[1,0,1]
	v_pk_fma_f32 v[126:127], v[6:7], v[22:23], v[20:21] op_sel_hi:[1,0,1]
	v_pk_fma_f32 v[130:131], v[6:7], v[26:27], v[24:25] op_sel_hi:[1,0,1]
	v_pk_fma_f32 v[134:135], v[6:7], v[30:31], v[28:29] op_sel_hi:[1,0,1]
	v_pk_fma_f32 v[146:147], v[6:7], v[34:35], v[32:33] op_sel_hi:[1,0,1]
	v_pk_fma_f32 v[150:151], v[6:7], v[38:39], v[36:37] op_sel_hi:[1,0,1]
	v_pk_fma_f32 v[154:155], v[6:7], v[42:43], v[40:41] op_sel_hi:[1,0,1]
	v_pk_fma_f32 v[158:159], v[6:7], v[46:47], v[44:45] op_sel_hi:[1,0,1]
	v_pk_fma_f32 v[162:163], v[6:7], v[50:51], v[48:49] op_sel_hi:[1,0,1]
	v_pk_fma_f32 v[166:167], v[6:7], v[54:55], v[52:53] op_sel_hi:[1,0,1]
	v_pk_fma_f32 v[170:171], v[6:7], v[114:115], v[86:87] op_sel_hi:[1,0,1]
	v_pk_fma_f32 v[68:69], v[6:7], v[80:81], v[68:69] op_sel_hi:[1,0,1]
	v_pk_fma_f32 v[174:175], v[6:7], v[118:119], v[62:63] op_sel_hi:[1,0,1]
	v_pk_fma_f32 v[178:179], v[6:7], v[122:123], v[58:59] op_sel_hi:[1,0,1]
	v_mov_b32_e32 v2, v3
	s_waitcnt vmcnt(8)
	v_mov_b64_e32 v[4:5], v[208:209]
	v_mov_b64_e32 v[6:7], v[210:211]
	v_pk_fma_f32 v[8:9], v[6:7], v[2:3], v[0:1] op_sel_hi:[1,0,1]
	v_mov_b32_e32 v0, v11
	v_pk_fma_f32 v[102:103], v[4:5], v[0:1], v[70:71] op_sel_hi:[1,0,1]
	v_pk_fma_f32 v[12:13], v[6:7], v[0:1], v[78:79] op_sel_hi:[1,0,1]
	v_mov_b32_e32 v0, v15
	v_pk_fma_f32 v[100:101], v[4:5], v[0:1], v[108:109] op_sel_hi:[1,0,1]
	v_pk_fma_f32 v[16:17], v[6:7], v[0:1], v[112:113] op_sel_hi:[1,0,1]
	v_mov_b32_e32 v0, v19
	v_pk_fma_f32 v[98:99], v[4:5], v[0:1], v[116:117] op_sel_hi:[1,0,1]
	v_pk_fma_f32 v[20:21], v[6:7], v[0:1], v[120:121] op_sel_hi:[1,0,1]
	v_mov_b32_e32 v0, v23
	v_pk_fma_f32 v[96:97], v[4:5], v[0:1], v[124:125] op_sel_hi:[1,0,1]
	v_pk_fma_f32 v[24:25], v[6:7], v[0:1], v[126:127] op_sel_hi:[1,0,1]
	v_mov_b32_e32 v0, v27
	v_pk_fma_f32 v[94:95], v[4:5], v[0:1], v[128:129] op_sel_hi:[1,0,1]
	v_pk_fma_f32 v[28:29], v[6:7], v[0:1], v[130:131] op_sel_hi:[1,0,1]
	v_mov_b32_e32 v0, v31
	v_pk_fma_f32 v[92:93], v[4:5], v[0:1], v[132:133] op_sel_hi:[1,0,1]
	v_pk_fma_f32 v[32:33], v[6:7], v[0:1], v[134:135] op_sel_hi:[1,0,1]
	v_mov_b32_e32 v0, v35
	v_pk_fma_f32 v[90:91], v[4:5], v[0:1], v[136:137] op_sel_hi:[1,0,1]
	v_pk_fma_f32 v[36:37], v[6:7], v[0:1], v[146:147] op_sel_hi:[1,0,1]
	v_mov_b32_e32 v0, v39
	v_pk_fma_f32 v[88:89], v[4:5], v[0:1], v[148:149] op_sel_hi:[1,0,1]
	v_pk_fma_f32 v[40:41], v[6:7], v[0:1], v[150:151] op_sel_hi:[1,0,1]
	v_mov_b32_e32 v0, v43
	v_pk_fma_f32 v[86:87], v[4:5], v[0:1], v[152:153] op_sel_hi:[1,0,1]
	v_pk_fma_f32 v[44:45], v[6:7], v[0:1], v[154:155] op_sel_hi:[1,0,1]
	v_mov_b32_e32 v0, v47
	v_pk_fma_f32 v[84:85], v[4:5], v[0:1], v[156:157] op_sel_hi:[1,0,1]
	v_pk_fma_f32 v[48:49], v[6:7], v[0:1], v[158:159] op_sel_hi:[1,0,1]
	v_mov_b32_e32 v0, v51
	v_pk_fma_f32 v[82:83], v[4:5], v[0:1], v[160:161] op_sel_hi:[1,0,1]
	v_pk_fma_f32 v[52:53], v[6:7], v[0:1], v[162:163] op_sel_hi:[1,0,1]
	v_mov_b32_e32 v0, v55
	v_pk_fma_f32 v[58:59], v[4:5], v[0:1], v[164:165] op_sel_hi:[1,0,1]
	v_pk_fma_f32 v[56:57], v[6:7], v[0:1], v[166:167] op_sel_hi:[1,0,1]
	v_mov_b32_e32 v0, v115
	v_pk_fma_f32 v[62:63], v[4:5], v[0:1], v[168:169] op_sel_hi:[1,0,1]
	v_pk_fma_f32 v[60:61], v[6:7], v[0:1], v[170:171] op_sel_hi:[1,0,1]
	v_mov_b32_e32 v0, v81
	v_pk_fma_f32 v[104:105], v[4:5], v[2:3], v[66:67] op_sel_hi:[1,0,1]
	v_pk_fma_f32 v[66:67], v[4:5], v[0:1], v[64:65] op_sel_hi:[1,0,1]
	v_pk_fma_f32 v[64:65], v[6:7], v[0:1], v[68:69] op_sel_hi:[1,0,1]
	v_mov_b32_e32 v0, v119
	v_pk_fma_f32 v[70:71], v[4:5], v[0:1], v[172:173] op_sel_hi:[1,0,1]
	v_pk_fma_f32 v[68:69], v[6:7], v[0:1], v[174:175] op_sel_hi:[1,0,1]
	v_mov_b32_e32 v0, v123
	v_pk_fma_f32 v[80:81], v[4:5], v[0:1], v[176:177] op_sel_hi:[1,0,1]
	v_pk_fma_f32 v[78:79], v[6:7], v[0:1], v[178:179] op_sel_hi:[1,0,1]
	v_lshl_add_u64 v[106:107], v[76:77], 0, s[68:69]
	v_add_co_u32_e32 v212, vcc, 0x30000, v106
	s_nop 1
	v_addc_co_u32_e32 v213, vcc, 0, v107, vcc
	global_load_dwordx4 v[180:183], v[212:213], off
	v_add_co_u32_e32 v212, vcc, 0x36000, v106
	s_nop 1
	v_addc_co_u32_e32 v213, vcc, 0, v107, vcc
	global_load_dwordx4 v[184:187], v[212:213], off
	v_add_co_u32_e32 v212, vcc, 0x3c000, v106
	s_nop 1
	v_addc_co_u32_e32 v213, vcc, 0, v107, vcc
	global_load_dwordx4 v[188:191], v[212:213], off
	v_add_co_u32_e32 v212, vcc, 0x42000, v106
	s_nop 1
	v_addc_co_u32_e32 v213, vcc, 0, v107, vcc
	global_load_dwordx4 v[192:195], v[212:213], off
	v_add_co_u32_e32 v212, vcc, 0x48000, v106
	s_nop 1
	v_addc_co_u32_e32 v213, vcc, 0, v107, vcc
	global_load_dwordx4 v[196:199], v[212:213], off
	v_add_co_u32_e32 v212, vcc, 0x4e000, v106
	s_nop 1
	v_addc_co_u32_e32 v213, vcc, 0, v107, vcc
	global_load_dwordx4 v[200:203], v[212:213], off
	v_add_co_u32_e32 v212, vcc, 0x54000, v106
	s_nop 1
	v_addc_co_u32_e32 v213, vcc, 0, v107, vcc
	global_load_dwordx4 v[204:207], v[212:213], off
	v_add_co_u32_e32 v212, vcc, 0x5a000, v106
	s_nop 1
	v_addc_co_u32_e32 v213, vcc, 0, v107, vcc
	global_load_dwordx4 v[208:211], v[212:213], off
	ds_read_b128 v[4:7], v72
	ds_read_b128 v[0:3], v72 offset:16
	s_mov_b32 s24, 0xc000
	s_add_u32 s68, s68, 0x30000
	s_addc_u32 s69, s69, 0
	s_cmp_eq_u32 s68, 0xc0000
	s_waitcnt vmcnt(8) lgkmcnt(1)
	v_mov_b64_e32 v[112:113], v[216:217]
	v_mov_b64_e32 v[114:115], v[218:219]
	v_pk_fma_f32 v[108:109], v[114:115], v[4:5], v[8:9] op_sel_hi:[1,0,1]
	ds_read_b128 v[8:11], v72 offset:2048
	v_pk_fma_f32 v[104:105], v[112:113], v[4:5], v[104:105] op_sel_hi:[1,0,1]
	s_waitcnt lgkmcnt(0)
	v_pk_fma_f32 v[116:117], v[114:115], v[8:9], v[12:13] op_sel_hi:[1,0,1]
	ds_read_b128 v[12:15], v72 offset:4096
	v_pk_fma_f32 v[102:103], v[112:113], v[8:9], v[102:103] op_sel_hi:[1,0,1]
	s_waitcnt lgkmcnt(0)
	v_pk_fma_f32 v[118:119], v[114:115], v[12:13], v[16:17] op_sel_hi:[1,0,1]
	ds_read_b128 v[16:19], v72 offset:6144
	v_pk_fma_f32 v[100:101], v[112:113], v[12:13], v[100:101] op_sel_hi:[1,0,1]
	s_waitcnt lgkmcnt(0)
	v_pk_fma_f32 v[120:121], v[114:115], v[16:17], v[20:21] op_sel_hi:[1,0,1]
	ds_read_b128 v[20:23], v72 offset:8192
	v_pk_fma_f32 v[98:99], v[112:113], v[16:17], v[98:99] op_sel_hi:[1,0,1]
	s_waitcnt lgkmcnt(0)
	v_pk_fma_f32 v[122:123], v[114:115], v[20:21], v[24:25] op_sel_hi:[1,0,1]
	ds_read_b128 v[24:27], v72 offset:10240
	v_pk_fma_f32 v[96:97], v[112:113], v[20:21], v[96:97] op_sel_hi:[1,0,1]
	s_waitcnt lgkmcnt(0)
	v_pk_fma_f32 v[124:125], v[114:115], v[24:25], v[28:29] op_sel_hi:[1,0,1]
	ds_read_b128 v[28:31], v72 offset:12288
	v_pk_fma_f32 v[94:95], v[112:113], v[24:25], v[94:95] op_sel_hi:[1,0,1]
	s_waitcnt lgkmcnt(0)
	v_pk_fma_f32 v[126:127], v[114:115], v[28:29], v[32:33] op_sel_hi:[1,0,1]
	ds_read_b128 v[32:35], v72 offset:14336
	v_pk_fma_f32 v[92:93], v[112:113], v[28:29], v[92:93] op_sel_hi:[1,0,1]
	s_waitcnt lgkmcnt(0)
	v_pk_fma_f32 v[128:129], v[114:115], v[32:33], v[36:37] op_sel_hi:[1,0,1]
	ds_read_b128 v[36:39], v72 offset:16384
	v_pk_fma_f32 v[90:91], v[112:113], v[32:33], v[90:91] op_sel_hi:[1,0,1]
	s_waitcnt lgkmcnt(0)
	v_pk_fma_f32 v[130:131], v[114:115], v[36:37], v[40:41] op_sel_hi:[1,0,1]
	ds_read_b128 v[40:43], v72 offset:18432
	v_pk_fma_f32 v[88:89], v[112:113], v[36:37], v[88:89] op_sel_hi:[1,0,1]
	s_waitcnt lgkmcnt(0)
	v_pk_fma_f32 v[132:133], v[114:115], v[40:41], v[44:45] op_sel_hi:[1,0,1]
	ds_read_b128 v[44:47], v72 offset:20480
	v_pk_fma_f32 v[86:87], v[112:113], v[40:41], v[86:87] op_sel_hi:[1,0,1]
	s_waitcnt lgkmcnt(0)
	v_pk_fma_f32 v[134:135], v[114:115], v[44:45], v[48:49] op_sel_hi:[1,0,1]
	ds_read_b128 v[48:51], v72 offset:22528
	v_pk_fma_f32 v[84:85], v[112:113], v[44:45], v[84:85] op_sel_hi:[1,0,1]
	s_waitcnt lgkmcnt(0)
	v_pk_fma_f32 v[136:137], v[114:115], v[48:49], v[52:53] op_sel_hi:[1,0,1]
	ds_read_b128 v[52:55], v72 offset:24576
	v_pk_fma_f32 v[82:83], v[112:113], v[48:49], v[82:83] op_sel_hi:[1,0,1]
	s_waitcnt lgkmcnt(0)
	v_pk_fma_f32 v[146:147], v[112:113], v[52:53], v[58:59] op_sel_hi:[1,0,1]
	v_pk_fma_f32 v[148:149], v[114:115], v[52:53], v[56:57] op_sel_hi:[1,0,1]
	ds_read_b128 v[56:59], v72 offset:26624
	s_waitcnt lgkmcnt(0)
	v_pk_fma_f32 v[150:151], v[112:113], v[56:57], v[62:63] op_sel_hi:[1,0,1]
	v_pk_fma_f32 v[152:153], v[114:115], v[56:57], v[60:61] op_sel_hi:[1,0,1]
	ds_read_b128 v[60:63], v72 offset:28672
	s_waitcnt lgkmcnt(0)
	v_pk_fma_f32 v[154:155], v[112:113], v[60:61], v[66:67] op_sel_hi:[1,0,1]
	v_pk_fma_f32 v[156:157], v[114:115], v[60:61], v[64:65] op_sel_hi:[1,0,1]
	ds_read_b128 v[64:67], v72 offset:30720
	s_waitcnt lgkmcnt(0)
	v_pk_fma_f32 v[158:159], v[112:113], v[64:65], v[70:71] op_sel_hi:[1,0,1]
	v_pk_fma_f32 v[160:161], v[114:115], v[64:65], v[68:69] op_sel_hi:[1,0,1]
	ds_read_b128 v[68:71], v72 offset:32768
	s_waitcnt lgkmcnt(0)
	v_pk_fma_f32 v[114:115], v[114:115], v[68:69], v[78:79] op_sel_hi:[1,0,1]
	v_add_co_u32_e32 v78, vcc, s75, v106
	v_pk_fma_f32 v[112:113], v[112:113], v[68:69], v[80:81] op_sel_hi:[1,0,1]
	s_nop 0
	v_addc_co_u32_e32 v79, vcc, 0, v107, vcc
	s_waitcnt vmcnt(8)
	v_mov_b64_e32 v[78:79], v[220:221]
	v_mov_b64_e32 v[80:81], v[222:223]
	v_pk_fma_f32 v[104:105], v[78:79], v[4:5], v[104:105] op_sel:[0,1,0]
	v_pk_fma_f32 v[4:5], v[80:81], v[4:5], v[108:109] op_sel:[0,1,0]
	v_pk_fma_f32 v[102:103], v[78:79], v[8:9], v[102:103] op_sel:[0,1,0]
	v_pk_fma_f32 v[8:9], v[80:81], v[8:9], v[116:117] op_sel:[0,1,0]
	v_pk_fma_f32 v[100:101], v[78:79], v[12:13], v[100:101] op_sel:[0,1,0]
	v_pk_fma_f32 v[12:13], v[80:81], v[12:13], v[118:119] op_sel:[0,1,0]
	v_pk_fma_f32 v[98:99], v[78:79], v[16:17], v[98:99] op_sel:[0,1,0]
	v_pk_fma_f32 v[16:17], v[80:81], v[16:17], v[120:121] op_sel:[0,1,0]
	v_pk_fma_f32 v[96:97], v[78:79], v[20:21], v[96:97] op_sel:[0,1,0]
	v_pk_fma_f32 v[94:95], v[78:79], v[24:25], v[94:95] op_sel:[0,1,0]
	v_pk_fma_f32 v[92:93], v[78:79], v[28:29], v[92:93] op_sel:[0,1,0]
	v_pk_fma_f32 v[90:91], v[78:79], v[32:33], v[90:91] op_sel:[0,1,0]
	v_pk_fma_f32 v[88:89], v[78:79], v[36:37], v[88:89] op_sel:[0,1,0]
	v_pk_fma_f32 v[86:87], v[78:79], v[40:41], v[86:87] op_sel:[0,1,0]
	v_pk_fma_f32 v[84:85], v[78:79], v[44:45], v[84:85] op_sel:[0,1,0]
	v_pk_fma_f32 v[82:83], v[78:79], v[48:49], v[82:83] op_sel:[0,1,0]
	v_pk_fma_f32 v[108:109], v[78:79], v[52:53], v[146:147] op_sel:[0,1,0]
	v_pk_fma_f32 v[116:117], v[78:79], v[56:57], v[150:151] op_sel:[0,1,0]
	v_pk_fma_f32 v[118:119], v[78:79], v[60:61], v[154:155] op_sel:[0,1,0]
	v_pk_fma_f32 v[120:121], v[78:79], v[64:65], v[158:159] op_sel:[0,1,0]
	v_pk_fma_f32 v[112:113], v[78:79], v[68:69], v[112:113] op_sel:[0,1,0]
	v_add_co_u32_e32 v78, vcc, s24, v106
	v_pk_fma_f32 v[20:21], v[80:81], v[20:21], v[122:123] op_sel:[0,1,0]
	s_nop 0
	v_addc_co_u32_e32 v79, vcc, 0, v107, vcc
	v_pk_fma_f32 v[24:25], v[80:81], v[24:25], v[124:125] op_sel:[0,1,0]
	v_pk_fma_f32 v[28:29], v[80:81], v[28:29], v[126:127] op_sel:[0,1,0]
	v_pk_fma_f32 v[32:33], v[80:81], v[32:33], v[128:129] op_sel:[0,1,0]
	v_pk_fma_f32 v[36:37], v[80:81], v[36:37], v[130:131] op_sel:[0,1,0]
	v_pk_fma_f32 v[40:41], v[80:81], v[40:41], v[132:133] op_sel:[0,1,0]
	v_pk_fma_f32 v[44:45], v[80:81], v[44:45], v[134:135] op_sel:[0,1,0]
	v_pk_fma_f32 v[48:49], v[80:81], v[48:49], v[136:137] op_sel:[0,1,0]
	v_pk_fma_f32 v[52:53], v[80:81], v[52:53], v[148:149] op_sel:[0,1,0]
	v_pk_fma_f32 v[56:57], v[80:81], v[56:57], v[152:153] op_sel:[0,1,0]
	v_pk_fma_f32 v[60:61], v[80:81], v[60:61], v[156:157] op_sel:[0,1,0]
	v_pk_fma_f32 v[64:65], v[80:81], v[64:65], v[160:161] op_sel:[0,1,0]
	v_pk_fma_f32 v[68:69], v[80:81], v[68:69], v[114:115] op_sel:[0,1,0]
	s_mov_b32 s24, 0x12000
	s_waitcnt vmcnt(8)
	v_mov_b64_e32 v[78:79], v[224:225]
	v_mov_b64_e32 v[80:81], v[226:227]
	v_pk_fma_f32 v[122:123], v[80:81], v[14:15], v[12:13] op_sel_hi:[1,0,1]
	v_add_co_u32_e32 v12, vcc, s24, v106
	v_pk_fma_f32 v[156:157], v[78:79], v[70:71], v[112:113] op_sel_hi:[1,0,1]
	s_nop 0
	v_addc_co_u32_e32 v13, vcc, 0, v107, vcc
	v_pk_fma_f32 v[104:105], v[78:79], v[6:7], v[104:105] op_sel_hi:[1,0,1]
	v_pk_fma_f32 v[4:5], v[80:81], v[6:7], v[4:5] op_sel_hi:[1,0,1]
	v_mov_b32_e32 v6, v7
	v_pk_fma_f32 v[102:103], v[78:79], v[10:11], v[102:103] op_sel_hi:[1,0,1]
	v_pk_fma_f32 v[8:9], v[80:81], v[10:11], v[8:9] op_sel_hi:[1,0,1]
	v_pk_fma_f32 v[100:101], v[78:79], v[14:15], v[100:101] op_sel_hi:[1,0,1]
	v_pk_fma_f32 v[150:151], v[78:79], v[54:55], v[108:109] op_sel_hi:[1,0,1]
	v_pk_fma_f32 v[98:99], v[78:79], v[18:19], v[98:99] op_sel_hi:[1,0,1]
	v_pk_fma_f32 v[124:125], v[80:81], v[18:19], v[16:17] op_sel_hi:[1,0,1]
	v_pk_fma_f32 v[96:97], v[78:79], v[22:23], v[96:97] op_sel_hi:[1,0,1]
	v_pk_fma_f32 v[126:127], v[80:81], v[22:23], v[20:21] op_sel_hi:[1,0,1]
	v_pk_fma_f32 v[94:95], v[78:79], v[26:27], v[94:95] op_sel_hi:[1,0,1]
	v_pk_fma_f32 v[128:129], v[80:81], v[26:27], v[24:25] op_sel_hi:[1,0,1]
	v_pk_fma_f32 v[92:93], v[78:79], v[30:31], v[92:93] op_sel_hi:[1,0,1]
	v_pk_fma_f32 v[130:131], v[80:81], v[30:31], v[28:29] op_sel_hi:[1,0,1]
	v_pk_fma_f32 v[90:91], v[78:79], v[34:35], v[90:91] op_sel_hi:[1,0,1]
	v_pk_fma_f32 v[132:133], v[80:81], v[34:35], v[32:33] op_sel_hi:[1,0,1]
	v_pk_fma_f32 v[88:89], v[78:79], v[38:39], v[88:89] op_sel_hi:[1,0,1]
	v_pk_fma_f32 v[134:135], v[80:81], v[38:39], v[36:37] op_sel_hi:[1,0,1]
	v_pk_fma_f32 v[86:87], v[78:79], v[42:43], v[86:87] op_sel_hi:[1,0,1]
	v_pk_fma_f32 v[136:137], v[80:81], v[42:43], v[40:41] op_sel_hi:[1,0,1]
	v_pk_fma_f32 v[84:85], v[78:79], v[46:47], v[84:85] op_sel_hi:[1,0,1]
	v_pk_fma_f32 v[146:147], v[80:81], v[46:47], v[44:45] op_sel_hi:[1,0,1]
	v_pk_fma_f32 v[82:83], v[78:79], v[50:51], v[82:83] op_sel_hi:[1,0,1]
	v_pk_fma_f32 v[148:149], v[80:81], v[50:51], v[48:49] op_sel_hi:[1,0,1]
	v_pk_fma_f32 v[152:153], v[80:81], v[54:55], v[52:53] op_sel_hi:[1,0,1]
	v_pk_fma_f32 v[116:117], v[78:79], v[58:59], v[116:117] op_sel_hi:[1,0,1]
	v_pk_fma_f32 v[56:57], v[80:81], v[58:59], v[56:57] op_sel_hi:[1,0,1]
	v_pk_fma_f32 v[118:119], v[78:79], v[62:63], v[118:119] op_sel_hi:[1,0,1]
	v_pk_fma_f32 v[60:61], v[80:81], v[62:63], v[60:61] op_sel_hi:[1,0,1]
	v_pk_fma_f32 v[120:121], v[78:79], v[66:67], v[120:121] op_sel_hi:[1,0,1]
	v_pk_fma_f32 v[154:155], v[80:81], v[66:67], v[64:65] op_sel_hi:[1,0,1]
	v_pk_fma_f32 v[158:159], v[80:81], v[70:71], v[68:69] op_sel_hi:[1,0,1]
	s_mov_b32 s24, 0x18000
	s_waitcnt vmcnt(8)
	v_mov_b64_e32 v[112:113], v[228:229]
	v_mov_b64_e32 v[114:115], v[230:231]
	v_pk_fma_f32 v[162:163], v[114:115], v[6:7], v[4:5] op_sel_hi:[1,0,1]
	v_mov_b32_e32 v4, v11
	v_pk_fma_f32 v[12:13], v[112:113], v[4:5], v[102:103] op_sel_hi:[1,0,1]
	v_pk_fma_f32 v[108:109], v[114:115], v[4:5], v[8:9] op_sel_hi:[1,0,1]
	v_mov_b32_e32 v4, v15
	v_pk_fma_f32 v[160:161], v[112:113], v[6:7], v[104:105] op_sel_hi:[1,0,1]
	v_pk_fma_f32 v[16:17], v[112:113], v[4:5], v[100:101] op_sel_hi:[1,0,1]
	v_pk_fma_f32 v[104:105], v[114:115], v[4:5], v[122:123] op_sel_hi:[1,0,1]
	v_mov_b32_e32 v4, v19
	v_pk_fma_f32 v[20:21], v[112:113], v[4:5], v[98:99] op_sel_hi:[1,0,1]
	v_pk_fma_f32 v[102:103], v[114:115], v[4:5], v[124:125] op_sel_hi:[1,0,1]
	v_mov_b32_e32 v4, v23
	v_pk_fma_f32 v[24:25], v[112:113], v[4:5], v[96:97] op_sel_hi:[1,0,1]
	v_pk_fma_f32 v[100:101], v[114:115], v[4:5], v[126:127] op_sel_hi:[1,0,1]
	v_mov_b32_e32 v4, v27
	v_pk_fma_f32 v[28:29], v[112:113], v[4:5], v[94:95] op_sel_hi:[1,0,1]
	v_pk_fma_f32 v[98:99], v[114:115], v[4:5], v[128:129] op_sel_hi:[1,0,1]
	v_mov_b32_e32 v4, v31
	v_pk_fma_f32 v[32:33], v[112:113], v[4:5], v[92:93] op_sel_hi:[1,0,1]
	v_pk_fma_f32 v[96:97], v[114:115], v[4:5], v[130:131] op_sel_hi:[1,0,1]
	v_mov_b32_e32 v4, v35
	v_pk_fma_f32 v[36:37], v[112:113], v[4:5], v[90:91] op_sel_hi:[1,0,1]
	v_pk_fma_f32 v[94:95], v[114:115], v[4:5], v[132:133] op_sel_hi:[1,0,1]
	v_mov_b32_e32 v4, v39
	v_pk_fma_f32 v[40:41], v[112:113], v[4:5], v[88:89] op_sel_hi:[1,0,1]
	v_pk_fma_f32 v[92:93], v[114:115], v[4:5], v[134:135] op_sel_hi:[1,0,1]
	v_mov_b32_e32 v4, v43
	v_pk_fma_f32 v[44:45], v[112:113], v[4:5], v[86:87] op_sel_hi:[1,0,1]
	v_pk_fma_f32 v[90:91], v[114:115], v[4:5], v[136:137] op_sel_hi:[1,0,1]
	v_mov_b32_e32 v4, v47
	v_pk_fma_f32 v[48:49], v[112:113], v[4:5], v[84:85] op_sel_hi:[1,0,1]
	v_pk_fma_f32 v[88:89], v[114:115], v[4:5], v[146:147] op_sel_hi:[1,0,1]
	v_mov_b32_e32 v4, v51
	v_pk_fma_f32 v[52:53], v[112:113], v[4:5], v[82:83] op_sel_hi:[1,0,1]
	v_pk_fma_f32 v[86:87], v[114:115], v[4:5], v[148:149] op_sel_hi:[1,0,1]
	v_mov_b32_e32 v4, v55
	v_pk_fma_f32 v[82:83], v[112:113], v[4:5], v[150:151] op_sel_hi:[1,0,1]
	v_pk_fma_f32 v[84:85], v[114:115], v[4:5], v[152:153] op_sel_hi:[1,0,1]
	v_mov_b32_e32 v4, v59
	v_pk_fma_f32 v[78:79], v[112:113], v[4:5], v[116:117] op_sel_hi:[1,0,1]
	v_pk_fma_f32 v[80:81], v[114:115], v[4:5], v[56:57] op_sel_hi:[1,0,1]
	v_mov_b32_e32 v4, v63
	v_pk_fma_f32 v[64:65], v[112:113], v[4:5], v[118:119] op_sel_hi:[1,0,1]
	v_pk_fma_f32 v[68:69], v[114:115], v[4:5], v[60:61] op_sel_hi:[1,0,1]
	v_mov_b32_e32 v4, v67
	v_pk_fma_f32 v[60:61], v[112:113], v[4:5], v[120:121] op_sel_hi:[1,0,1]
	v_pk_fma_f32 v[62:63], v[114:115], v[4:5], v[154:155] op_sel_hi:[1,0,1]
	v_mov_b32_e32 v4, v71
	v_pk_fma_f32 v[56:57], v[112:113], v[4:5], v[156:157] op_sel_hi:[1,0,1]
	v_pk_fma_f32 v[58:59], v[114:115], v[4:5], v[158:159] op_sel_hi:[1,0,1]
	v_add_co_u32_e32 v4, vcc, s24, v106
	ds_read_b128 v[8:11], v72 offset:2064
	ds_read_b128 v[120:123], v72 offset:32784
	v_addc_co_u32_e32 v5, vcc, 0, v107, vcc
	ds_read_b128 v[112:115], v72 offset:26640
	ds_read_b128 v[116:119], v72 offset:30736
	s_mov_b32 s24, 0x1e000
	s_waitcnt vmcnt(8) lgkmcnt(3)
	v_mov_b64_e32 v[4:5], v[232:233]
	v_mov_b64_e32 v[6:7], v[234:235]
	v_pk_fma_f32 v[124:125], v[4:5], v[8:9], v[12:13] op_sel_hi:[1,0,1]
	ds_read_b128 v[12:15], v72 offset:4112
	s_waitcnt lgkmcnt(2)
	v_pk_fma_f32 v[154:155], v[4:5], v[112:113], v[78:79] op_sel_hi:[1,0,1]
	v_pk_fma_f32 v[156:157], v[6:7], v[112:113], v[80:81] op_sel_hi:[1,0,1]
	ds_read_b128 v[78:81], v72 offset:28688
	v_pk_fma_f32 v[66:67], v[4:5], v[0:1], v[160:161] op_sel_hi:[1,0,1]
	s_waitcnt lgkmcnt(1)
	v_pk_fma_f32 v[126:127], v[4:5], v[12:13], v[16:17] op_sel_hi:[1,0,1]
	ds_read_b128 v[16:19], v72 offset:6160
	v_pk_fma_f32 v[60:61], v[4:5], v[116:117], v[60:61] op_sel_hi:[1,0,1]
	s_waitcnt lgkmcnt(1)
	v_pk_fma_f32 v[64:65], v[4:5], v[78:79], v[64:65] op_sel_hi:[1,0,1]
	v_pk_fma_f32 v[56:57], v[4:5], v[120:121], v[56:57] op_sel_hi:[1,0,1]
	v_pk_fma_f32 v[70:71], v[6:7], v[0:1], v[162:163] op_sel_hi:[1,0,1]
	s_waitcnt lgkmcnt(0)
	v_pk_fma_f32 v[128:129], v[4:5], v[16:17], v[20:21] op_sel_hi:[1,0,1]
	ds_read_b128 v[20:23], v72 offset:8208
	v_pk_fma_f32 v[108:109], v[6:7], v[8:9], v[108:109] op_sel_hi:[1,0,1]
	v_pk_fma_f32 v[104:105], v[6:7], v[12:13], v[104:105] op_sel_hi:[1,0,1]
	v_pk_fma_f32 v[102:103], v[6:7], v[16:17], v[102:103] op_sel_hi:[1,0,1]
	v_pk_fma_f32 v[68:69], v[6:7], v[78:79], v[68:69] op_sel_hi:[1,0,1]
	s_waitcnt lgkmcnt(0)
	v_pk_fma_f32 v[130:131], v[4:5], v[20:21], v[24:25] op_sel_hi:[1,0,1]
	ds_read_b128 v[24:27], v72 offset:10256
	v_pk_fma_f32 v[100:101], v[6:7], v[20:21], v[100:101] op_sel_hi:[1,0,1]
	v_pk_fma_f32 v[62:63], v[6:7], v[116:117], v[62:63] op_sel_hi:[1,0,1]
	v_pk_fma_f32 v[58:59], v[6:7], v[120:121], v[58:59] op_sel_hi:[1,0,1]
	s_waitcnt lgkmcnt(0)
	v_pk_fma_f32 v[132:133], v[4:5], v[24:25], v[28:29] op_sel_hi:[1,0,1]
	ds_read_b128 v[28:31], v72 offset:12304
	v_pk_fma_f32 v[98:99], v[6:7], v[24:25], v[98:99] op_sel_hi:[1,0,1]
	s_waitcnt lgkmcnt(0)
	v_pk_fma_f32 v[134:135], v[4:5], v[28:29], v[32:33] op_sel_hi:[1,0,1]
	ds_read_b128 v[32:35], v72 offset:14352
	v_pk_fma_f32 v[96:97], v[6:7], v[28:29], v[96:97] op_sel_hi:[1,0,1]
	s_waitcnt lgkmcnt(0)
	v_pk_fma_f32 v[136:137], v[4:5], v[32:33], v[36:37] op_sel_hi:[1,0,1]
	ds_read_b128 v[36:39], v72 offset:16400
	v_pk_fma_f32 v[94:95], v[6:7], v[32:33], v[94:95] op_sel_hi:[1,0,1]
	s_waitcnt lgkmcnt(0)
	v_pk_fma_f32 v[146:147], v[4:5], v[36:37], v[40:41] op_sel_hi:[1,0,1]
	ds_read_b128 v[40:43], v72 offset:18448
	v_pk_fma_f32 v[92:93], v[6:7], v[36:37], v[92:93] op_sel_hi:[1,0,1]
	s_waitcnt lgkmcnt(0)
	v_pk_fma_f32 v[148:149], v[4:5], v[40:41], v[44:45] op_sel_hi:[1,0,1]
	ds_read_b128 v[44:47], v72 offset:20496
	v_pk_fma_f32 v[90:91], v[6:7], v[40:41], v[90:91] op_sel_hi:[1,0,1]
	s_waitcnt lgkmcnt(0)
	v_pk_fma_f32 v[150:151], v[4:5], v[44:45], v[48:49] op_sel_hi:[1,0,1]
	ds_read_b128 v[48:51], v72 offset:22544
	v_pk_fma_f32 v[88:89], v[6:7], v[44:45], v[88:89] op_sel_hi:[1,0,1]
	s_waitcnt lgkmcnt(0)
	v_pk_fma_f32 v[152:153], v[4:5], v[48:49], v[52:53] op_sel_hi:[1,0,1]
	ds_read_b128 v[52:55], v72 offset:24592
	v_pk_fma_f32 v[86:87], v[6:7], v[48:49], v[86:87] op_sel_hi:[1,0,1]
	v_add_u32_e32 v72, 32, v72
	s_waitcnt lgkmcnt(0)
	v_pk_fma_f32 v[82:83], v[4:5], v[52:53], v[82:83] op_sel_hi:[1,0,1]
	v_add_co_u32_e32 v4, vcc, s24, v106
	v_pk_fma_f32 v[84:85], v[6:7], v[52:53], v[84:85] op_sel_hi:[1,0,1]
	s_nop 0
	v_addc_co_u32_e32 v5, vcc, 0, v107, vcc
	s_mov_b32 s24, 0x24000
	s_waitcnt vmcnt(8)
	v_mov_b64_e32 v[4:5], v[236:237]
	v_mov_b64_e32 v[6:7], v[238:239]
	v_pk_fma_f32 v[66:67], v[4:5], v[0:1], v[66:67] op_sel:[0,1,0]
	v_pk_fma_f32 v[0:1], v[6:7], v[0:1], v[70:71] op_sel:[0,1,0]
	v_pk_fma_f32 v[70:71], v[4:5], v[8:9], v[124:125] op_sel:[0,1,0]
	v_pk_fma_f32 v[8:9], v[6:7], v[8:9], v[108:109] op_sel:[0,1,0]
	v_pk_fma_f32 v[108:109], v[4:5], v[12:13], v[126:127] op_sel:[0,1,0]
	v_pk_fma_f32 v[12:13], v[6:7], v[12:13], v[104:105] op_sel:[0,1,0]
	v_pk_fma_f32 v[104:105], v[4:5], v[16:17], v[128:129] op_sel:[0,1,0]
	v_pk_fma_f32 v[16:17], v[6:7], v[16:17], v[102:103] op_sel:[0,1,0]
	v_pk_fma_f32 v[102:103], v[4:5], v[20:21], v[130:131] op_sel:[0,1,0]
	v_pk_fma_f32 v[20:21], v[6:7], v[20:21], v[100:101] op_sel:[0,1,0]
	v_pk_fma_f32 v[100:101], v[4:5], v[24:25], v[132:133] op_sel:[0,1,0]
	v_pk_fma_f32 v[24:25], v[6:7], v[24:25], v[98:99] op_sel:[0,1,0]
	v_pk_fma_f32 v[98:99], v[4:5], v[28:29], v[134:135] op_sel:[0,1,0]
	v_pk_fma_f32 v[28:29], v[6:7], v[28:29], v[96:97] op_sel:[0,1,0]
	v_pk_fma_f32 v[96:97], v[4:5], v[32:33], v[136:137] op_sel:[0,1,0]
	v_pk_fma_f32 v[32:33], v[6:7], v[32:33], v[94:95] op_sel:[0,1,0]
	v_pk_fma_f32 v[94:95], v[4:5], v[36:37], v[146:147] op_sel:[0,1,0]
	v_pk_fma_f32 v[36:37], v[6:7], v[36:37], v[92:93] op_sel:[0,1,0]
	v_pk_fma_f32 v[92:93], v[4:5], v[40:41], v[148:149] op_sel:[0,1,0]
	v_pk_fma_f32 v[40:41], v[6:7], v[40:41], v[90:91] op_sel:[0,1,0]
	v_pk_fma_f32 v[90:91], v[4:5], v[44:45], v[150:151] op_sel:[0,1,0]
	v_pk_fma_f32 v[44:45], v[6:7], v[44:45], v[88:89] op_sel:[0,1,0]
	v_pk_fma_f32 v[88:89], v[4:5], v[48:49], v[152:153] op_sel:[0,1,0]
	v_pk_fma_f32 v[82:83], v[4:5], v[52:53], v[82:83] op_sel:[0,1,0]
	v_pk_fma_f32 v[52:53], v[6:7], v[52:53], v[84:85] op_sel:[0,1,0]
	v_pk_fma_f32 v[84:85], v[4:5], v[112:113], v[154:155] op_sel:[0,1,0]
	v_pk_fma_f32 v[64:65], v[4:5], v[78:79], v[64:65] op_sel:[0,1,0]
	v_pk_fma_f32 v[60:61], v[4:5], v[116:117], v[60:61] op_sel:[0,1,0]
	v_pk_fma_f32 v[56:57], v[4:5], v[120:121], v[56:57] op_sel:[0,1,0]
	v_add_co_u32_e32 v4, vcc, s24, v106
	v_pk_fma_f32 v[48:49], v[6:7], v[48:49], v[86:87] op_sel:[0,1,0]
	s_nop 0
	v_addc_co_u32_e32 v5, vcc, 0, v107, vcc
	v_pk_fma_f32 v[86:87], v[6:7], v[112:113], v[156:157] op_sel:[0,1,0]
	v_pk_fma_f32 v[68:69], v[6:7], v[78:79], v[68:69] op_sel:[0,1,0]
	v_pk_fma_f32 v[62:63], v[6:7], v[116:117], v[62:63] op_sel:[0,1,0]
	v_pk_fma_f32 v[58:59], v[6:7], v[120:121], v[58:59] op_sel:[0,1,0]
	s_mov_b32 s24, 0x2a000
	s_waitcnt vmcnt(8)
	v_mov_b64_e32 v[4:5], v[240:241]
	v_mov_b64_e32 v[6:7], v[242:243]
	v_pk_fma_f32 v[66:67], v[4:5], v[2:3], v[66:67] op_sel_hi:[1,0,1]
	v_pk_fma_f32 v[70:71], v[4:5], v[10:11], v[70:71] op_sel_hi:[1,0,1]
	v_pk_fma_f32 v[108:109], v[4:5], v[14:15], v[108:109] op_sel_hi:[1,0,1]
	v_pk_fma_f32 v[116:117], v[4:5], v[18:19], v[104:105] op_sel_hi:[1,0,1]
	v_pk_fma_f32 v[124:125], v[4:5], v[22:23], v[102:103] op_sel_hi:[1,0,1]
	v_pk_fma_f32 v[128:129], v[4:5], v[26:27], v[100:101] op_sel_hi:[1,0,1]
	v_pk_fma_f32 v[132:133], v[4:5], v[30:31], v[98:99] op_sel_hi:[1,0,1]
	v_pk_fma_f32 v[136:137], v[4:5], v[34:35], v[96:97] op_sel_hi:[1,0,1]
	v_pk_fma_f32 v[148:149], v[4:5], v[38:39], v[94:95] op_sel_hi:[1,0,1]
	v_pk_fma_f32 v[152:153], v[4:5], v[42:43], v[92:93] op_sel_hi:[1,0,1]
	v_pk_fma_f32 v[156:157], v[4:5], v[46:47], v[90:91] op_sel_hi:[1,0,1]
	v_pk_fma_f32 v[160:161], v[4:5], v[50:51], v[88:89] op_sel_hi:[1,0,1]
	v_pk_fma_f32 v[164:165], v[4:5], v[54:55], v[82:83] op_sel_hi:[1,0,1]
	v_pk_fma_f32 v[168:169], v[4:5], v[114:115], v[84:85] op_sel_hi:[1,0,1]
	v_pk_fma_f32 v[64:65], v[4:5], v[80:81], v[64:65] op_sel_hi:[1,0,1]
	v_pk_fma_f32 v[172:173], v[4:5], v[118:119], v[60:61] op_sel_hi:[1,0,1]
	v_pk_fma_f32 v[176:177], v[4:5], v[122:123], v[56:57] op_sel_hi:[1,0,1]
	v_add_co_u32_e32 v4, vcc, s24, v106
	v_pk_fma_f32 v[0:1], v[6:7], v[2:3], v[0:1] op_sel_hi:[1,0,1]
	s_nop 0
	v_addc_co_u32_e32 v5, vcc, 0, v107, vcc
	v_pk_fma_f32 v[78:79], v[6:7], v[10:11], v[8:9] op_sel_hi:[1,0,1]
	v_pk_fma_f32 v[112:113], v[6:7], v[14:15], v[12:13] op_sel_hi:[1,0,1]
	v_pk_fma_f32 v[120:121], v[6:7], v[18:19], v[16:17] op_sel_hi:[1,0,1]
	v_pk_fma_f32 v[126:127], v[6:7], v[22:23], v[20:21] op_sel_hi:[1,0,1]
	v_pk_fma_f32 v[130:131], v[6:7], v[26:27], v[24:25] op_sel_hi:[1,0,1]
	v_pk_fma_f32 v[134:135], v[6:7], v[30:31], v[28:29] op_sel_hi:[1,0,1]
	v_pk_fma_f32 v[146:147], v[6:7], v[34:35], v[32:33] op_sel_hi:[1,0,1]
	v_pk_fma_f32 v[150:151], v[6:7], v[38:39], v[36:37] op_sel_hi:[1,0,1]
	v_pk_fma_f32 v[154:155], v[6:7], v[42:43], v[40:41] op_sel_hi:[1,0,1]
	v_pk_fma_f32 v[158:159], v[6:7], v[46:47], v[44:45] op_sel_hi:[1,0,1]
	v_pk_fma_f32 v[162:163], v[6:7], v[50:51], v[48:49] op_sel_hi:[1,0,1]
	v_pk_fma_f32 v[166:167], v[6:7], v[54:55], v[52:53] op_sel_hi:[1,0,1]
	v_pk_fma_f32 v[170:171], v[6:7], v[114:115], v[86:87] op_sel_hi:[1,0,1]
	v_pk_fma_f32 v[68:69], v[6:7], v[80:81], v[68:69] op_sel_hi:[1,0,1]
	v_pk_fma_f32 v[174:175], v[6:7], v[118:119], v[62:63] op_sel_hi:[1,0,1]
	v_pk_fma_f32 v[178:179], v[6:7], v[122:123], v[58:59] op_sel_hi:[1,0,1]
	v_mov_b32_e32 v2, v3
	s_waitcnt vmcnt(8)
	v_mov_b64_e32 v[4:5], v[244:245]
	v_mov_b64_e32 v[6:7], v[246:247]
	v_pk_fma_f32 v[8:9], v[6:7], v[2:3], v[0:1] op_sel_hi:[1,0,1]
	v_mov_b32_e32 v0, v11
	v_pk_fma_f32 v[102:103], v[4:5], v[0:1], v[70:71] op_sel_hi:[1,0,1]
	v_pk_fma_f32 v[12:13], v[6:7], v[0:1], v[78:79] op_sel_hi:[1,0,1]
	v_mov_b32_e32 v0, v15
	v_pk_fma_f32 v[100:101], v[4:5], v[0:1], v[108:109] op_sel_hi:[1,0,1]
	v_pk_fma_f32 v[16:17], v[6:7], v[0:1], v[112:113] op_sel_hi:[1,0,1]
	v_mov_b32_e32 v0, v19
	v_pk_fma_f32 v[98:99], v[4:5], v[0:1], v[116:117] op_sel_hi:[1,0,1]
	v_pk_fma_f32 v[20:21], v[6:7], v[0:1], v[120:121] op_sel_hi:[1,0,1]
	v_mov_b32_e32 v0, v23
	v_pk_fma_f32 v[96:97], v[4:5], v[0:1], v[124:125] op_sel_hi:[1,0,1]
	v_pk_fma_f32 v[24:25], v[6:7], v[0:1], v[126:127] op_sel_hi:[1,0,1]
	v_mov_b32_e32 v0, v27
	v_pk_fma_f32 v[94:95], v[4:5], v[0:1], v[128:129] op_sel_hi:[1,0,1]
	v_pk_fma_f32 v[28:29], v[6:7], v[0:1], v[130:131] op_sel_hi:[1,0,1]
	v_mov_b32_e32 v0, v31
	v_pk_fma_f32 v[92:93], v[4:5], v[0:1], v[132:133] op_sel_hi:[1,0,1]
	v_pk_fma_f32 v[32:33], v[6:7], v[0:1], v[134:135] op_sel_hi:[1,0,1]
	v_mov_b32_e32 v0, v35
	v_pk_fma_f32 v[90:91], v[4:5], v[0:1], v[136:137] op_sel_hi:[1,0,1]
	v_pk_fma_f32 v[36:37], v[6:7], v[0:1], v[146:147] op_sel_hi:[1,0,1]
	v_mov_b32_e32 v0, v39
	v_pk_fma_f32 v[88:89], v[4:5], v[0:1], v[148:149] op_sel_hi:[1,0,1]
	v_pk_fma_f32 v[40:41], v[6:7], v[0:1], v[150:151] op_sel_hi:[1,0,1]
	v_mov_b32_e32 v0, v43
	v_pk_fma_f32 v[86:87], v[4:5], v[0:1], v[152:153] op_sel_hi:[1,0,1]
	v_pk_fma_f32 v[44:45], v[6:7], v[0:1], v[154:155] op_sel_hi:[1,0,1]
	v_mov_b32_e32 v0, v47
	v_pk_fma_f32 v[84:85], v[4:5], v[0:1], v[156:157] op_sel_hi:[1,0,1]
	v_pk_fma_f32 v[48:49], v[6:7], v[0:1], v[158:159] op_sel_hi:[1,0,1]
	v_mov_b32_e32 v0, v51
	v_pk_fma_f32 v[82:83], v[4:5], v[0:1], v[160:161] op_sel_hi:[1,0,1]
	v_pk_fma_f32 v[52:53], v[6:7], v[0:1], v[162:163] op_sel_hi:[1,0,1]
	v_mov_b32_e32 v0, v55
	v_pk_fma_f32 v[58:59], v[4:5], v[0:1], v[164:165] op_sel_hi:[1,0,1]
	v_pk_fma_f32 v[56:57], v[6:7], v[0:1], v[166:167] op_sel_hi:[1,0,1]
	v_mov_b32_e32 v0, v115
	v_pk_fma_f32 v[62:63], v[4:5], v[0:1], v[168:169] op_sel_hi:[1,0,1]
	v_pk_fma_f32 v[60:61], v[6:7], v[0:1], v[170:171] op_sel_hi:[1,0,1]
	v_mov_b32_e32 v0, v81
	v_pk_fma_f32 v[104:105], v[4:5], v[2:3], v[66:67] op_sel_hi:[1,0,1]
	v_pk_fma_f32 v[66:67], v[4:5], v[0:1], v[64:65] op_sel_hi:[1,0,1]
	v_pk_fma_f32 v[64:65], v[6:7], v[0:1], v[68:69] op_sel_hi:[1,0,1]
	v_mov_b32_e32 v0, v119
	v_pk_fma_f32 v[70:71], v[4:5], v[0:1], v[172:173] op_sel_hi:[1,0,1]
	v_pk_fma_f32 v[68:69], v[6:7], v[0:1], v[174:175] op_sel_hi:[1,0,1]
	v_mov_b32_e32 v0, v123
	v_pk_fma_f32 v[80:81], v[4:5], v[0:1], v[176:177] op_sel_hi:[1,0,1]
	v_pk_fma_f32 v[78:79], v[6:7], v[0:1], v[178:179] op_sel_hi:[1,0,1]
	v_lshl_add_u64 v[106:107], v[76:77], 0, s[68:69]
	ds_read_b128 v[4:7], v72
	ds_read_b128 v[0:3], v72 offset:16
	s_mov_b32 s24, 0xc000
	s_add_u32 s68, s68, 0x30000
	s_addc_u32 s69, s69, 0
	s_cmp_eq_u32 s68, 0xc0000
	s_waitcnt vmcnt(0) lgkmcnt(1)
	v_mov_b64_e32 v[112:113], v[180:181]
	v_mov_b64_e32 v[114:115], v[182:183]
	v_pk_fma_f32 v[108:109], v[114:115], v[4:5], v[8:9] op_sel_hi:[1,0,1]
	ds_read_b128 v[8:11], v72 offset:2048
	v_pk_fma_f32 v[104:105], v[112:113], v[4:5], v[104:105] op_sel_hi:[1,0,1]
	s_waitcnt lgkmcnt(0)
	v_pk_fma_f32 v[116:117], v[114:115], v[8:9], v[12:13] op_sel_hi:[1,0,1]
	ds_read_b128 v[12:15], v72 offset:4096
	v_pk_fma_f32 v[102:103], v[112:113], v[8:9], v[102:103] op_sel_hi:[1,0,1]
	s_waitcnt lgkmcnt(0)
	v_pk_fma_f32 v[118:119], v[114:115], v[12:13], v[16:17] op_sel_hi:[1,0,1]
	ds_read_b128 v[16:19], v72 offset:6144
	v_pk_fma_f32 v[100:101], v[112:113], v[12:13], v[100:101] op_sel_hi:[1,0,1]
	s_waitcnt lgkmcnt(0)
	v_pk_fma_f32 v[120:121], v[114:115], v[16:17], v[20:21] op_sel_hi:[1,0,1]
	ds_read_b128 v[20:23], v72 offset:8192
	v_pk_fma_f32 v[98:99], v[112:113], v[16:17], v[98:99] op_sel_hi:[1,0,1]
	s_waitcnt lgkmcnt(0)
	v_pk_fma_f32 v[122:123], v[114:115], v[20:21], v[24:25] op_sel_hi:[1,0,1]
	ds_read_b128 v[24:27], v72 offset:10240
	v_pk_fma_f32 v[96:97], v[112:113], v[20:21], v[96:97] op_sel_hi:[1,0,1]
	s_waitcnt lgkmcnt(0)
	v_pk_fma_f32 v[124:125], v[114:115], v[24:25], v[28:29] op_sel_hi:[1,0,1]
	ds_read_b128 v[28:31], v72 offset:12288
	v_pk_fma_f32 v[94:95], v[112:113], v[24:25], v[94:95] op_sel_hi:[1,0,1]
	s_waitcnt lgkmcnt(0)
	v_pk_fma_f32 v[126:127], v[114:115], v[28:29], v[32:33] op_sel_hi:[1,0,1]
	ds_read_b128 v[32:35], v72 offset:14336
	v_pk_fma_f32 v[92:93], v[112:113], v[28:29], v[92:93] op_sel_hi:[1,0,1]
	s_waitcnt lgkmcnt(0)
	v_pk_fma_f32 v[128:129], v[114:115], v[32:33], v[36:37] op_sel_hi:[1,0,1]
	ds_read_b128 v[36:39], v72 offset:16384
	v_pk_fma_f32 v[90:91], v[112:113], v[32:33], v[90:91] op_sel_hi:[1,0,1]
	s_waitcnt lgkmcnt(0)
	v_pk_fma_f32 v[130:131], v[114:115], v[36:37], v[40:41] op_sel_hi:[1,0,1]
	ds_read_b128 v[40:43], v72 offset:18432
	v_pk_fma_f32 v[88:89], v[112:113], v[36:37], v[88:89] op_sel_hi:[1,0,1]
	s_waitcnt lgkmcnt(0)
	v_pk_fma_f32 v[132:133], v[114:115], v[40:41], v[44:45] op_sel_hi:[1,0,1]
	ds_read_b128 v[44:47], v72 offset:20480
	v_pk_fma_f32 v[86:87], v[112:113], v[40:41], v[86:87] op_sel_hi:[1,0,1]
	s_waitcnt lgkmcnt(0)
	v_pk_fma_f32 v[134:135], v[114:115], v[44:45], v[48:49] op_sel_hi:[1,0,1]
	ds_read_b128 v[48:51], v72 offset:22528
	v_pk_fma_f32 v[84:85], v[112:113], v[44:45], v[84:85] op_sel_hi:[1,0,1]
	s_waitcnt lgkmcnt(0)
	v_pk_fma_f32 v[136:137], v[114:115], v[48:49], v[52:53] op_sel_hi:[1,0,1]
	ds_read_b128 v[52:55], v72 offset:24576
	v_pk_fma_f32 v[82:83], v[112:113], v[48:49], v[82:83] op_sel_hi:[1,0,1]
	s_waitcnt lgkmcnt(0)
	v_pk_fma_f32 v[146:147], v[112:113], v[52:53], v[58:59] op_sel_hi:[1,0,1]
	v_pk_fma_f32 v[148:149], v[114:115], v[52:53], v[56:57] op_sel_hi:[1,0,1]
	ds_read_b128 v[56:59], v72 offset:26624
	s_waitcnt lgkmcnt(0)
	v_pk_fma_f32 v[150:151], v[112:113], v[56:57], v[62:63] op_sel_hi:[1,0,1]
	v_pk_fma_f32 v[152:153], v[114:115], v[56:57], v[60:61] op_sel_hi:[1,0,1]
	ds_read_b128 v[60:63], v72 offset:28672
	s_waitcnt lgkmcnt(0)
	v_pk_fma_f32 v[154:155], v[112:113], v[60:61], v[66:67] op_sel_hi:[1,0,1]
	v_pk_fma_f32 v[156:157], v[114:115], v[60:61], v[64:65] op_sel_hi:[1,0,1]
	ds_read_b128 v[64:67], v72 offset:30720
	s_waitcnt lgkmcnt(0)
	v_pk_fma_f32 v[158:159], v[112:113], v[64:65], v[70:71] op_sel_hi:[1,0,1]
	v_pk_fma_f32 v[160:161], v[114:115], v[64:65], v[68:69] op_sel_hi:[1,0,1]
	ds_read_b128 v[68:71], v72 offset:32768
	s_waitcnt lgkmcnt(0)
	v_pk_fma_f32 v[114:115], v[114:115], v[68:69], v[78:79] op_sel_hi:[1,0,1]
	v_add_co_u32_e32 v78, vcc, s75, v106
	v_pk_fma_f32 v[112:113], v[112:113], v[68:69], v[80:81] op_sel_hi:[1,0,1]
	s_nop 0
	v_addc_co_u32_e32 v79, vcc, 0, v107, vcc
	s_waitcnt vmcnt(0)
	v_mov_b64_e32 v[78:79], v[184:185]
	v_mov_b64_e32 v[80:81], v[186:187]
	v_pk_fma_f32 v[104:105], v[78:79], v[4:5], v[104:105] op_sel:[0,1,0]
	v_pk_fma_f32 v[4:5], v[80:81], v[4:5], v[108:109] op_sel:[0,1,0]
	v_pk_fma_f32 v[102:103], v[78:79], v[8:9], v[102:103] op_sel:[0,1,0]
	v_pk_fma_f32 v[8:9], v[80:81], v[8:9], v[116:117] op_sel:[0,1,0]
	v_pk_fma_f32 v[100:101], v[78:79], v[12:13], v[100:101] op_sel:[0,1,0]
	v_pk_fma_f32 v[12:13], v[80:81], v[12:13], v[118:119] op_sel:[0,1,0]
	v_pk_fma_f32 v[98:99], v[78:79], v[16:17], v[98:99] op_sel:[0,1,0]
	v_pk_fma_f32 v[16:17], v[80:81], v[16:17], v[120:121] op_sel:[0,1,0]
	v_pk_fma_f32 v[96:97], v[78:79], v[20:21], v[96:97] op_sel:[0,1,0]
	v_pk_fma_f32 v[94:95], v[78:79], v[24:25], v[94:95] op_sel:[0,1,0]
	v_pk_fma_f32 v[92:93], v[78:79], v[28:29], v[92:93] op_sel:[0,1,0]
	v_pk_fma_f32 v[90:91], v[78:79], v[32:33], v[90:91] op_sel:[0,1,0]
	v_pk_fma_f32 v[88:89], v[78:79], v[36:37], v[88:89] op_sel:[0,1,0]
	v_pk_fma_f32 v[86:87], v[78:79], v[40:41], v[86:87] op_sel:[0,1,0]
	v_pk_fma_f32 v[84:85], v[78:79], v[44:45], v[84:85] op_sel:[0,1,0]
	v_pk_fma_f32 v[82:83], v[78:79], v[48:49], v[82:83] op_sel:[0,1,0]
	v_pk_fma_f32 v[108:109], v[78:79], v[52:53], v[146:147] op_sel:[0,1,0]
	v_pk_fma_f32 v[116:117], v[78:79], v[56:57], v[150:151] op_sel:[0,1,0]
	v_pk_fma_f32 v[118:119], v[78:79], v[60:61], v[154:155] op_sel:[0,1,0]
	v_pk_fma_f32 v[120:121], v[78:79], v[64:65], v[158:159] op_sel:[0,1,0]
	v_pk_fma_f32 v[112:113], v[78:79], v[68:69], v[112:113] op_sel:[0,1,0]
	v_add_co_u32_e32 v78, vcc, s24, v106
	v_pk_fma_f32 v[20:21], v[80:81], v[20:21], v[122:123] op_sel:[0,1,0]
	s_nop 0
	v_addc_co_u32_e32 v79, vcc, 0, v107, vcc
	v_pk_fma_f32 v[24:25], v[80:81], v[24:25], v[124:125] op_sel:[0,1,0]
	v_pk_fma_f32 v[28:29], v[80:81], v[28:29], v[126:127] op_sel:[0,1,0]
	v_pk_fma_f32 v[32:33], v[80:81], v[32:33], v[128:129] op_sel:[0,1,0]
	v_pk_fma_f32 v[36:37], v[80:81], v[36:37], v[130:131] op_sel:[0,1,0]
	v_pk_fma_f32 v[40:41], v[80:81], v[40:41], v[132:133] op_sel:[0,1,0]
	v_pk_fma_f32 v[44:45], v[80:81], v[44:45], v[134:135] op_sel:[0,1,0]
	v_pk_fma_f32 v[48:49], v[80:81], v[48:49], v[136:137] op_sel:[0,1,0]
	v_pk_fma_f32 v[52:53], v[80:81], v[52:53], v[148:149] op_sel:[0,1,0]
	v_pk_fma_f32 v[56:57], v[80:81], v[56:57], v[152:153] op_sel:[0,1,0]
	v_pk_fma_f32 v[60:61], v[80:81], v[60:61], v[156:157] op_sel:[0,1,0]
	v_pk_fma_f32 v[64:65], v[80:81], v[64:65], v[160:161] op_sel:[0,1,0]
	v_pk_fma_f32 v[68:69], v[80:81], v[68:69], v[114:115] op_sel:[0,1,0]
	s_mov_b32 s24, 0x12000
	s_waitcnt vmcnt(0)
	v_mov_b64_e32 v[78:79], v[188:189]
	v_mov_b64_e32 v[80:81], v[190:191]
	v_pk_fma_f32 v[122:123], v[80:81], v[14:15], v[12:13] op_sel_hi:[1,0,1]
	v_add_co_u32_e32 v12, vcc, s24, v106
	v_pk_fma_f32 v[156:157], v[78:79], v[70:71], v[112:113] op_sel_hi:[1,0,1]
	s_nop 0
	v_addc_co_u32_e32 v13, vcc, 0, v107, vcc
	v_pk_fma_f32 v[104:105], v[78:79], v[6:7], v[104:105] op_sel_hi:[1,0,1]
	v_pk_fma_f32 v[4:5], v[80:81], v[6:7], v[4:5] op_sel_hi:[1,0,1]
	v_mov_b32_e32 v6, v7
	v_pk_fma_f32 v[102:103], v[78:79], v[10:11], v[102:103] op_sel_hi:[1,0,1]
	v_pk_fma_f32 v[8:9], v[80:81], v[10:11], v[8:9] op_sel_hi:[1,0,1]
	v_pk_fma_f32 v[100:101], v[78:79], v[14:15], v[100:101] op_sel_hi:[1,0,1]
	v_pk_fma_f32 v[150:151], v[78:79], v[54:55], v[108:109] op_sel_hi:[1,0,1]
	v_pk_fma_f32 v[98:99], v[78:79], v[18:19], v[98:99] op_sel_hi:[1,0,1]
	v_pk_fma_f32 v[124:125], v[80:81], v[18:19], v[16:17] op_sel_hi:[1,0,1]
	v_pk_fma_f32 v[96:97], v[78:79], v[22:23], v[96:97] op_sel_hi:[1,0,1]
	v_pk_fma_f32 v[126:127], v[80:81], v[22:23], v[20:21] op_sel_hi:[1,0,1]
	v_pk_fma_f32 v[94:95], v[78:79], v[26:27], v[94:95] op_sel_hi:[1,0,1]
	v_pk_fma_f32 v[128:129], v[80:81], v[26:27], v[24:25] op_sel_hi:[1,0,1]
	v_pk_fma_f32 v[92:93], v[78:79], v[30:31], v[92:93] op_sel_hi:[1,0,1]
	v_pk_fma_f32 v[130:131], v[80:81], v[30:31], v[28:29] op_sel_hi:[1,0,1]
	v_pk_fma_f32 v[90:91], v[78:79], v[34:35], v[90:91] op_sel_hi:[1,0,1]
	v_pk_fma_f32 v[132:133], v[80:81], v[34:35], v[32:33] op_sel_hi:[1,0,1]
	v_pk_fma_f32 v[88:89], v[78:79], v[38:39], v[88:89] op_sel_hi:[1,0,1]
	v_pk_fma_f32 v[134:135], v[80:81], v[38:39], v[36:37] op_sel_hi:[1,0,1]
	v_pk_fma_f32 v[86:87], v[78:79], v[42:43], v[86:87] op_sel_hi:[1,0,1]
	v_pk_fma_f32 v[136:137], v[80:81], v[42:43], v[40:41] op_sel_hi:[1,0,1]
	v_pk_fma_f32 v[84:85], v[78:79], v[46:47], v[84:85] op_sel_hi:[1,0,1]
	v_pk_fma_f32 v[146:147], v[80:81], v[46:47], v[44:45] op_sel_hi:[1,0,1]
	v_pk_fma_f32 v[82:83], v[78:79], v[50:51], v[82:83] op_sel_hi:[1,0,1]
	v_pk_fma_f32 v[148:149], v[80:81], v[50:51], v[48:49] op_sel_hi:[1,0,1]
	v_pk_fma_f32 v[152:153], v[80:81], v[54:55], v[52:53] op_sel_hi:[1,0,1]
	v_pk_fma_f32 v[116:117], v[78:79], v[58:59], v[116:117] op_sel_hi:[1,0,1]
	v_pk_fma_f32 v[56:57], v[80:81], v[58:59], v[56:57] op_sel_hi:[1,0,1]
	v_pk_fma_f32 v[118:119], v[78:79], v[62:63], v[118:119] op_sel_hi:[1,0,1]
	v_pk_fma_f32 v[60:61], v[80:81], v[62:63], v[60:61] op_sel_hi:[1,0,1]
	v_pk_fma_f32 v[120:121], v[78:79], v[66:67], v[120:121] op_sel_hi:[1,0,1]
	v_pk_fma_f32 v[154:155], v[80:81], v[66:67], v[64:65] op_sel_hi:[1,0,1]
	v_pk_fma_f32 v[158:159], v[80:81], v[70:71], v[68:69] op_sel_hi:[1,0,1]
	s_mov_b32 s24, 0x18000
	s_waitcnt vmcnt(0)
	v_mov_b64_e32 v[112:113], v[192:193]
	v_mov_b64_e32 v[114:115], v[194:195]
	v_pk_fma_f32 v[162:163], v[114:115], v[6:7], v[4:5] op_sel_hi:[1,0,1]
	v_mov_b32_e32 v4, v11
	v_pk_fma_f32 v[12:13], v[112:113], v[4:5], v[102:103] op_sel_hi:[1,0,1]
	v_pk_fma_f32 v[108:109], v[114:115], v[4:5], v[8:9] op_sel_hi:[1,0,1]
	v_mov_b32_e32 v4, v15
	v_pk_fma_f32 v[160:161], v[112:113], v[6:7], v[104:105] op_sel_hi:[1,0,1]
	v_pk_fma_f32 v[16:17], v[112:113], v[4:5], v[100:101] op_sel_hi:[1,0,1]
	v_pk_fma_f32 v[104:105], v[114:115], v[4:5], v[122:123] op_sel_hi:[1,0,1]
	v_mov_b32_e32 v4, v19
	v_pk_fma_f32 v[20:21], v[112:113], v[4:5], v[98:99] op_sel_hi:[1,0,1]
	v_pk_fma_f32 v[102:103], v[114:115], v[4:5], v[124:125] op_sel_hi:[1,0,1]
	v_mov_b32_e32 v4, v23
	v_pk_fma_f32 v[24:25], v[112:113], v[4:5], v[96:97] op_sel_hi:[1,0,1]
	v_pk_fma_f32 v[100:101], v[114:115], v[4:5], v[126:127] op_sel_hi:[1,0,1]
	v_mov_b32_e32 v4, v27
	v_pk_fma_f32 v[28:29], v[112:113], v[4:5], v[94:95] op_sel_hi:[1,0,1]
	v_pk_fma_f32 v[98:99], v[114:115], v[4:5], v[128:129] op_sel_hi:[1,0,1]
	v_mov_b32_e32 v4, v31
	v_pk_fma_f32 v[32:33], v[112:113], v[4:5], v[92:93] op_sel_hi:[1,0,1]
	v_pk_fma_f32 v[96:97], v[114:115], v[4:5], v[130:131] op_sel_hi:[1,0,1]
	v_mov_b32_e32 v4, v35
	v_pk_fma_f32 v[36:37], v[112:113], v[4:5], v[90:91] op_sel_hi:[1,0,1]
	v_pk_fma_f32 v[94:95], v[114:115], v[4:5], v[132:133] op_sel_hi:[1,0,1]
	v_mov_b32_e32 v4, v39
	v_pk_fma_f32 v[40:41], v[112:113], v[4:5], v[88:89] op_sel_hi:[1,0,1]
	v_pk_fma_f32 v[92:93], v[114:115], v[4:5], v[134:135] op_sel_hi:[1,0,1]
	v_mov_b32_e32 v4, v43
	v_pk_fma_f32 v[44:45], v[112:113], v[4:5], v[86:87] op_sel_hi:[1,0,1]
	v_pk_fma_f32 v[90:91], v[114:115], v[4:5], v[136:137] op_sel_hi:[1,0,1]
	v_mov_b32_e32 v4, v47
	v_pk_fma_f32 v[48:49], v[112:113], v[4:5], v[84:85] op_sel_hi:[1,0,1]
	v_pk_fma_f32 v[88:89], v[114:115], v[4:5], v[146:147] op_sel_hi:[1,0,1]
	v_mov_b32_e32 v4, v51
	v_pk_fma_f32 v[52:53], v[112:113], v[4:5], v[82:83] op_sel_hi:[1,0,1]
	v_pk_fma_f32 v[86:87], v[114:115], v[4:5], v[148:149] op_sel_hi:[1,0,1]
	v_mov_b32_e32 v4, v55
	v_pk_fma_f32 v[82:83], v[112:113], v[4:5], v[150:151] op_sel_hi:[1,0,1]
	v_pk_fma_f32 v[84:85], v[114:115], v[4:5], v[152:153] op_sel_hi:[1,0,1]
	v_mov_b32_e32 v4, v59
	v_pk_fma_f32 v[78:79], v[112:113], v[4:5], v[116:117] op_sel_hi:[1,0,1]
	v_pk_fma_f32 v[80:81], v[114:115], v[4:5], v[56:57] op_sel_hi:[1,0,1]
	v_mov_b32_e32 v4, v63
	v_pk_fma_f32 v[64:65], v[112:113], v[4:5], v[118:119] op_sel_hi:[1,0,1]
	v_pk_fma_f32 v[68:69], v[114:115], v[4:5], v[60:61] op_sel_hi:[1,0,1]
	v_mov_b32_e32 v4, v67
	v_pk_fma_f32 v[60:61], v[112:113], v[4:5], v[120:121] op_sel_hi:[1,0,1]
	v_pk_fma_f32 v[62:63], v[114:115], v[4:5], v[154:155] op_sel_hi:[1,0,1]
	v_mov_b32_e32 v4, v71
	v_pk_fma_f32 v[56:57], v[112:113], v[4:5], v[156:157] op_sel_hi:[1,0,1]
	v_pk_fma_f32 v[58:59], v[114:115], v[4:5], v[158:159] op_sel_hi:[1,0,1]
	v_add_co_u32_e32 v4, vcc, s24, v106
	ds_read_b128 v[8:11], v72 offset:2064
	ds_read_b128 v[120:123], v72 offset:32784
	v_addc_co_u32_e32 v5, vcc, 0, v107, vcc
	ds_read_b128 v[112:115], v72 offset:26640
	ds_read_b128 v[116:119], v72 offset:30736
	s_mov_b32 s24, 0x1e000
	s_waitcnt vmcnt(0) lgkmcnt(3)
	v_mov_b64_e32 v[4:5], v[196:197]
	v_mov_b64_e32 v[6:7], v[198:199]
	v_pk_fma_f32 v[124:125], v[4:5], v[8:9], v[12:13] op_sel_hi:[1,0,1]
	ds_read_b128 v[12:15], v72 offset:4112
	s_waitcnt lgkmcnt(2)
	v_pk_fma_f32 v[154:155], v[4:5], v[112:113], v[78:79] op_sel_hi:[1,0,1]
	v_pk_fma_f32 v[156:157], v[6:7], v[112:113], v[80:81] op_sel_hi:[1,0,1]
	ds_read_b128 v[78:81], v72 offset:28688
	v_pk_fma_f32 v[66:67], v[4:5], v[0:1], v[160:161] op_sel_hi:[1,0,1]
	s_waitcnt lgkmcnt(1)
	v_pk_fma_f32 v[126:127], v[4:5], v[12:13], v[16:17] op_sel_hi:[1,0,1]
	ds_read_b128 v[16:19], v72 offset:6160
	v_pk_fma_f32 v[60:61], v[4:5], v[116:117], v[60:61] op_sel_hi:[1,0,1]
	s_waitcnt lgkmcnt(1)
	v_pk_fma_f32 v[64:65], v[4:5], v[78:79], v[64:65] op_sel_hi:[1,0,1]
	v_pk_fma_f32 v[56:57], v[4:5], v[120:121], v[56:57] op_sel_hi:[1,0,1]
	v_pk_fma_f32 v[70:71], v[6:7], v[0:1], v[162:163] op_sel_hi:[1,0,1]
	s_waitcnt lgkmcnt(0)
	v_pk_fma_f32 v[128:129], v[4:5], v[16:17], v[20:21] op_sel_hi:[1,0,1]
	ds_read_b128 v[20:23], v72 offset:8208
	v_pk_fma_f32 v[108:109], v[6:7], v[8:9], v[108:109] op_sel_hi:[1,0,1]
	v_pk_fma_f32 v[104:105], v[6:7], v[12:13], v[104:105] op_sel_hi:[1,0,1]
	v_pk_fma_f32 v[102:103], v[6:7], v[16:17], v[102:103] op_sel_hi:[1,0,1]
	v_pk_fma_f32 v[68:69], v[6:7], v[78:79], v[68:69] op_sel_hi:[1,0,1]
	s_waitcnt lgkmcnt(0)
	v_pk_fma_f32 v[130:131], v[4:5], v[20:21], v[24:25] op_sel_hi:[1,0,1]
	ds_read_b128 v[24:27], v72 offset:10256
	v_pk_fma_f32 v[100:101], v[6:7], v[20:21], v[100:101] op_sel_hi:[1,0,1]
	v_pk_fma_f32 v[62:63], v[6:7], v[116:117], v[62:63] op_sel_hi:[1,0,1]
	v_pk_fma_f32 v[58:59], v[6:7], v[120:121], v[58:59] op_sel_hi:[1,0,1]
	s_waitcnt lgkmcnt(0)
	v_pk_fma_f32 v[132:133], v[4:5], v[24:25], v[28:29] op_sel_hi:[1,0,1]
	ds_read_b128 v[28:31], v72 offset:12304
	v_pk_fma_f32 v[98:99], v[6:7], v[24:25], v[98:99] op_sel_hi:[1,0,1]
	s_waitcnt lgkmcnt(0)
	v_pk_fma_f32 v[134:135], v[4:5], v[28:29], v[32:33] op_sel_hi:[1,0,1]
	ds_read_b128 v[32:35], v72 offset:14352
	v_pk_fma_f32 v[96:97], v[6:7], v[28:29], v[96:97] op_sel_hi:[1,0,1]
	s_waitcnt lgkmcnt(0)
	v_pk_fma_f32 v[136:137], v[4:5], v[32:33], v[36:37] op_sel_hi:[1,0,1]
	ds_read_b128 v[36:39], v72 offset:16400
	v_pk_fma_f32 v[94:95], v[6:7], v[32:33], v[94:95] op_sel_hi:[1,0,1]
	s_waitcnt lgkmcnt(0)
	v_pk_fma_f32 v[146:147], v[4:5], v[36:37], v[40:41] op_sel_hi:[1,0,1]
	ds_read_b128 v[40:43], v72 offset:18448
	v_pk_fma_f32 v[92:93], v[6:7], v[36:37], v[92:93] op_sel_hi:[1,0,1]
	s_waitcnt lgkmcnt(0)
	v_pk_fma_f32 v[148:149], v[4:5], v[40:41], v[44:45] op_sel_hi:[1,0,1]
	ds_read_b128 v[44:47], v72 offset:20496
	v_pk_fma_f32 v[90:91], v[6:7], v[40:41], v[90:91] op_sel_hi:[1,0,1]
	s_waitcnt lgkmcnt(0)
	v_pk_fma_f32 v[150:151], v[4:5], v[44:45], v[48:49] op_sel_hi:[1,0,1]
	ds_read_b128 v[48:51], v72 offset:22544
	v_pk_fma_f32 v[88:89], v[6:7], v[44:45], v[88:89] op_sel_hi:[1,0,1]
	s_waitcnt lgkmcnt(0)
	v_pk_fma_f32 v[152:153], v[4:5], v[48:49], v[52:53] op_sel_hi:[1,0,1]
	ds_read_b128 v[52:55], v72 offset:24592
	v_pk_fma_f32 v[86:87], v[6:7], v[48:49], v[86:87] op_sel_hi:[1,0,1]
	v_add_u32_e32 v72, 32, v72
	s_waitcnt lgkmcnt(0)
	v_pk_fma_f32 v[82:83], v[4:5], v[52:53], v[82:83] op_sel_hi:[1,0,1]
	v_add_co_u32_e32 v4, vcc, s24, v106
	v_pk_fma_f32 v[84:85], v[6:7], v[52:53], v[84:85] op_sel_hi:[1,0,1]
	s_nop 0
	v_addc_co_u32_e32 v5, vcc, 0, v107, vcc
	s_mov_b32 s24, 0x24000
	s_waitcnt vmcnt(0)
	v_mov_b64_e32 v[4:5], v[200:201]
	v_mov_b64_e32 v[6:7], v[202:203]
	v_pk_fma_f32 v[66:67], v[4:5], v[0:1], v[66:67] op_sel:[0,1,0]
	v_pk_fma_f32 v[0:1], v[6:7], v[0:1], v[70:71] op_sel:[0,1,0]
	v_pk_fma_f32 v[70:71], v[4:5], v[8:9], v[124:125] op_sel:[0,1,0]
	v_pk_fma_f32 v[8:9], v[6:7], v[8:9], v[108:109] op_sel:[0,1,0]
	v_pk_fma_f32 v[108:109], v[4:5], v[12:13], v[126:127] op_sel:[0,1,0]
	v_pk_fma_f32 v[12:13], v[6:7], v[12:13], v[104:105] op_sel:[0,1,0]
	v_pk_fma_f32 v[104:105], v[4:5], v[16:17], v[128:129] op_sel:[0,1,0]
	v_pk_fma_f32 v[16:17], v[6:7], v[16:17], v[102:103] op_sel:[0,1,0]
	v_pk_fma_f32 v[102:103], v[4:5], v[20:21], v[130:131] op_sel:[0,1,0]
	v_pk_fma_f32 v[20:21], v[6:7], v[20:21], v[100:101] op_sel:[0,1,0]
	v_pk_fma_f32 v[100:101], v[4:5], v[24:25], v[132:133] op_sel:[0,1,0]
	v_pk_fma_f32 v[24:25], v[6:7], v[24:25], v[98:99] op_sel:[0,1,0]
	v_pk_fma_f32 v[98:99], v[4:5], v[28:29], v[134:135] op_sel:[0,1,0]
	v_pk_fma_f32 v[28:29], v[6:7], v[28:29], v[96:97] op_sel:[0,1,0]
	v_pk_fma_f32 v[96:97], v[4:5], v[32:33], v[136:137] op_sel:[0,1,0]
	v_pk_fma_f32 v[32:33], v[6:7], v[32:33], v[94:95] op_sel:[0,1,0]
	v_pk_fma_f32 v[94:95], v[4:5], v[36:37], v[146:147] op_sel:[0,1,0]
	v_pk_fma_f32 v[36:37], v[6:7], v[36:37], v[92:93] op_sel:[0,1,0]
	v_pk_fma_f32 v[92:93], v[4:5], v[40:41], v[148:149] op_sel:[0,1,0]
	v_pk_fma_f32 v[40:41], v[6:7], v[40:41], v[90:91] op_sel:[0,1,0]
	v_pk_fma_f32 v[90:91], v[4:5], v[44:45], v[150:151] op_sel:[0,1,0]
	v_pk_fma_f32 v[44:45], v[6:7], v[44:45], v[88:89] op_sel:[0,1,0]
	v_pk_fma_f32 v[88:89], v[4:5], v[48:49], v[152:153] op_sel:[0,1,0]
	v_pk_fma_f32 v[82:83], v[4:5], v[52:53], v[82:83] op_sel:[0,1,0]
	v_pk_fma_f32 v[52:53], v[6:7], v[52:53], v[84:85] op_sel:[0,1,0]
	v_pk_fma_f32 v[84:85], v[4:5], v[112:113], v[154:155] op_sel:[0,1,0]
	v_pk_fma_f32 v[64:65], v[4:5], v[78:79], v[64:65] op_sel:[0,1,0]
	v_pk_fma_f32 v[60:61], v[4:5], v[116:117], v[60:61] op_sel:[0,1,0]
	v_pk_fma_f32 v[56:57], v[4:5], v[120:121], v[56:57] op_sel:[0,1,0]
	v_add_co_u32_e32 v4, vcc, s24, v106
	v_pk_fma_f32 v[48:49], v[6:7], v[48:49], v[86:87] op_sel:[0,1,0]
	s_nop 0
	v_addc_co_u32_e32 v5, vcc, 0, v107, vcc
	v_pk_fma_f32 v[86:87], v[6:7], v[112:113], v[156:157] op_sel:[0,1,0]
	v_pk_fma_f32 v[68:69], v[6:7], v[78:79], v[68:69] op_sel:[0,1,0]
	v_pk_fma_f32 v[62:63], v[6:7], v[116:117], v[62:63] op_sel:[0,1,0]
	v_pk_fma_f32 v[58:59], v[6:7], v[120:121], v[58:59] op_sel:[0,1,0]
	s_mov_b32 s24, 0x2a000
	s_waitcnt vmcnt(0)
	v_mov_b64_e32 v[4:5], v[204:205]
	v_mov_b64_e32 v[6:7], v[206:207]
	v_pk_fma_f32 v[66:67], v[4:5], v[2:3], v[66:67] op_sel_hi:[1,0,1]
	v_pk_fma_f32 v[70:71], v[4:5], v[10:11], v[70:71] op_sel_hi:[1,0,1]
	v_pk_fma_f32 v[108:109], v[4:5], v[14:15], v[108:109] op_sel_hi:[1,0,1]
	v_pk_fma_f32 v[116:117], v[4:5], v[18:19], v[104:105] op_sel_hi:[1,0,1]
	v_pk_fma_f32 v[124:125], v[4:5], v[22:23], v[102:103] op_sel_hi:[1,0,1]
	v_pk_fma_f32 v[128:129], v[4:5], v[26:27], v[100:101] op_sel_hi:[1,0,1]
	v_pk_fma_f32 v[132:133], v[4:5], v[30:31], v[98:99] op_sel_hi:[1,0,1]
	v_pk_fma_f32 v[136:137], v[4:5], v[34:35], v[96:97] op_sel_hi:[1,0,1]
	v_pk_fma_f32 v[148:149], v[4:5], v[38:39], v[94:95] op_sel_hi:[1,0,1]
	v_pk_fma_f32 v[152:153], v[4:5], v[42:43], v[92:93] op_sel_hi:[1,0,1]
	v_pk_fma_f32 v[156:157], v[4:5], v[46:47], v[90:91] op_sel_hi:[1,0,1]
	v_pk_fma_f32 v[160:161], v[4:5], v[50:51], v[88:89] op_sel_hi:[1,0,1]
	v_pk_fma_f32 v[164:165], v[4:5], v[54:55], v[82:83] op_sel_hi:[1,0,1]
	v_pk_fma_f32 v[168:169], v[4:5], v[114:115], v[84:85] op_sel_hi:[1,0,1]
	v_pk_fma_f32 v[64:65], v[4:5], v[80:81], v[64:65] op_sel_hi:[1,0,1]
	v_pk_fma_f32 v[172:173], v[4:5], v[118:119], v[60:61] op_sel_hi:[1,0,1]
	v_pk_fma_f32 v[176:177], v[4:5], v[122:123], v[56:57] op_sel_hi:[1,0,1]
	v_add_co_u32_e32 v4, vcc, s24, v106
	v_pk_fma_f32 v[0:1], v[6:7], v[2:3], v[0:1] op_sel_hi:[1,0,1]
	s_nop 0
	v_addc_co_u32_e32 v5, vcc, 0, v107, vcc
	v_pk_fma_f32 v[78:79], v[6:7], v[10:11], v[8:9] op_sel_hi:[1,0,1]
	v_pk_fma_f32 v[112:113], v[6:7], v[14:15], v[12:13] op_sel_hi:[1,0,1]
	v_pk_fma_f32 v[120:121], v[6:7], v[18:19], v[16:17] op_sel_hi:[1,0,1]
	v_pk_fma_f32 v[126:127], v[6:7], v[22:23], v[20:21] op_sel_hi:[1,0,1]
	v_pk_fma_f32 v[130:131], v[6:7], v[26:27], v[24:25] op_sel_hi:[1,0,1]
	v_pk_fma_f32 v[134:135], v[6:7], v[30:31], v[28:29] op_sel_hi:[1,0,1]
	v_pk_fma_f32 v[146:147], v[6:7], v[34:35], v[32:33] op_sel_hi:[1,0,1]
	v_pk_fma_f32 v[150:151], v[6:7], v[38:39], v[36:37] op_sel_hi:[1,0,1]
	v_pk_fma_f32 v[154:155], v[6:7], v[42:43], v[40:41] op_sel_hi:[1,0,1]
	v_pk_fma_f32 v[158:159], v[6:7], v[46:47], v[44:45] op_sel_hi:[1,0,1]
	v_pk_fma_f32 v[162:163], v[6:7], v[50:51], v[48:49] op_sel_hi:[1,0,1]
	v_pk_fma_f32 v[166:167], v[6:7], v[54:55], v[52:53] op_sel_hi:[1,0,1]
	v_pk_fma_f32 v[170:171], v[6:7], v[114:115], v[86:87] op_sel_hi:[1,0,1]
	v_pk_fma_f32 v[68:69], v[6:7], v[80:81], v[68:69] op_sel_hi:[1,0,1]
	v_pk_fma_f32 v[174:175], v[6:7], v[118:119], v[62:63] op_sel_hi:[1,0,1]
	v_pk_fma_f32 v[178:179], v[6:7], v[122:123], v[58:59] op_sel_hi:[1,0,1]
	v_mov_b32_e32 v2, v3
	s_waitcnt vmcnt(0)
	v_mov_b64_e32 v[4:5], v[208:209]
	v_mov_b64_e32 v[6:7], v[210:211]
	v_pk_fma_f32 v[8:9], v[6:7], v[2:3], v[0:1] op_sel_hi:[1,0,1]
	v_mov_b32_e32 v0, v11
	v_pk_fma_f32 v[102:103], v[4:5], v[0:1], v[70:71] op_sel_hi:[1,0,1]
	v_pk_fma_f32 v[12:13], v[6:7], v[0:1], v[78:79] op_sel_hi:[1,0,1]
	v_mov_b32_e32 v0, v15
	v_pk_fma_f32 v[100:101], v[4:5], v[0:1], v[108:109] op_sel_hi:[1,0,1]
	v_pk_fma_f32 v[16:17], v[6:7], v[0:1], v[112:113] op_sel_hi:[1,0,1]
	v_mov_b32_e32 v0, v19
	v_pk_fma_f32 v[98:99], v[4:5], v[0:1], v[116:117] op_sel_hi:[1,0,1]
	v_pk_fma_f32 v[20:21], v[6:7], v[0:1], v[120:121] op_sel_hi:[1,0,1]
	v_mov_b32_e32 v0, v23
	v_pk_fma_f32 v[96:97], v[4:5], v[0:1], v[124:125] op_sel_hi:[1,0,1]
	v_pk_fma_f32 v[24:25], v[6:7], v[0:1], v[126:127] op_sel_hi:[1,0,1]
	v_mov_b32_e32 v0, v27
	v_pk_fma_f32 v[94:95], v[4:5], v[0:1], v[128:129] op_sel_hi:[1,0,1]
	v_pk_fma_f32 v[28:29], v[6:7], v[0:1], v[130:131] op_sel_hi:[1,0,1]
	v_mov_b32_e32 v0, v31
	v_pk_fma_f32 v[92:93], v[4:5], v[0:1], v[132:133] op_sel_hi:[1,0,1]
	v_pk_fma_f32 v[32:33], v[6:7], v[0:1], v[134:135] op_sel_hi:[1,0,1]
	v_mov_b32_e32 v0, v35
	v_pk_fma_f32 v[90:91], v[4:5], v[0:1], v[136:137] op_sel_hi:[1,0,1]
	v_pk_fma_f32 v[36:37], v[6:7], v[0:1], v[146:147] op_sel_hi:[1,0,1]
	v_mov_b32_e32 v0, v39
	v_pk_fma_f32 v[88:89], v[4:5], v[0:1], v[148:149] op_sel_hi:[1,0,1]
	v_pk_fma_f32 v[40:41], v[6:7], v[0:1], v[150:151] op_sel_hi:[1,0,1]
	v_mov_b32_e32 v0, v43
	v_pk_fma_f32 v[86:87], v[4:5], v[0:1], v[152:153] op_sel_hi:[1,0,1]
	v_pk_fma_f32 v[44:45], v[6:7], v[0:1], v[154:155] op_sel_hi:[1,0,1]
	v_mov_b32_e32 v0, v47
	v_pk_fma_f32 v[84:85], v[4:5], v[0:1], v[156:157] op_sel_hi:[1,0,1]
	v_pk_fma_f32 v[48:49], v[6:7], v[0:1], v[158:159] op_sel_hi:[1,0,1]
	v_mov_b32_e32 v0, v51
	v_pk_fma_f32 v[82:83], v[4:5], v[0:1], v[160:161] op_sel_hi:[1,0,1]
	v_pk_fma_f32 v[52:53], v[6:7], v[0:1], v[162:163] op_sel_hi:[1,0,1]
	v_mov_b32_e32 v0, v55
	v_pk_fma_f32 v[58:59], v[4:5], v[0:1], v[164:165] op_sel_hi:[1,0,1]
	v_pk_fma_f32 v[56:57], v[6:7], v[0:1], v[166:167] op_sel_hi:[1,0,1]
	v_mov_b32_e32 v0, v115
	v_pk_fma_f32 v[62:63], v[4:5], v[0:1], v[168:169] op_sel_hi:[1,0,1]
	v_pk_fma_f32 v[60:61], v[6:7], v[0:1], v[170:171] op_sel_hi:[1,0,1]
	v_mov_b32_e32 v0, v81
	v_pk_fma_f32 v[104:105], v[4:5], v[2:3], v[66:67] op_sel_hi:[1,0,1]
	v_pk_fma_f32 v[66:67], v[4:5], v[0:1], v[64:65] op_sel_hi:[1,0,1]
	v_pk_fma_f32 v[64:65], v[6:7], v[0:1], v[68:69] op_sel_hi:[1,0,1]
	v_mov_b32_e32 v0, v119
	v_pk_fma_f32 v[70:71], v[4:5], v[0:1], v[172:173] op_sel_hi:[1,0,1]
	v_pk_fma_f32 v[68:69], v[6:7], v[0:1], v[174:175] op_sel_hi:[1,0,1]
	v_mov_b32_e32 v0, v123
	v_pk_fma_f32 v[80:81], v[4:5], v[0:1], v[176:177] op_sel_hi:[1,0,1]
	v_pk_fma_f32 v[78:79], v[6:7], v[0:1], v[178:179] op_sel_hi:[1,0,1]
	s_movk_i32 s76, 0x200
	s_mov_b64 s[68:69], 0
	s_and_b64 vcc, exec, s[6:7]
	s_cbranch_vccz .LBB0_139
	v_and_b32_e32 v1, 64, v138
	v_xor_b32_e32 v0, 16, v138
	v_add_u32_e32 v2, 64, v1
	v_cmp_lt_i32_e32 vcc, v0, v2
	v_xor_b32_e32 v3, 32, v138
	v_and_b32_e32 v72, 48, v139
	v_cndmask_b32_e32 v0, v138, v0, vcc
	v_lshlrev_b32_e32 v137, 2, v0
	ds_bpermute_b32 v4, v137, v8
	ds_bpermute_b32 v5, v137, v9
	ds_bpermute_b32 v0, v137, v104
	ds_bpermute_b32 v1, v137, v105
	ds_bpermute_b32 v18, v137, v100
	ds_bpermute_b32 v19, v137, v101
	s_waitcnt lgkmcnt(4)
	v_pk_add_f32 v[4:5], v[8:9], v[4:5]
	ds_bpermute_b32 v8, v137, v102
	ds_bpermute_b32 v9, v137, v103
	ds_bpermute_b32 v30, v137, v98
	ds_bpermute_b32 v31, v137, v99
	ds_bpermute_b32 v42, v137, v96
	ds_bpermute_b32 v43, v137, v97
	ds_bpermute_b32 v54, v137, v94
	ds_bpermute_b32 v55, v137, v95
	s_waitcnt lgkmcnt(10)
	v_pk_add_f32 v[0:1], v[104:105], v[0:1]
	ds_bpermute_b32 v14, v137, v12
	ds_bpermute_b32 v15, v137, v13
	s_waitcnt lgkmcnt(8)
	v_pk_add_f32 v[8:9], v[102:103], v[8:9]
	ds_bpermute_b32 v26, v137, v16
	ds_bpermute_b32 v27, v137, v17
	v_pk_add_f32 v[18:19], v[100:101], v[18:19]
	ds_bpermute_b32 v38, v137, v20
	ds_bpermute_b32 v39, v137, v21
	s_waitcnt lgkmcnt(10)
	v_pk_add_f32 v[30:31], v[98:99], v[30:31]
	ds_bpermute_b32 v50, v137, v24
	ds_bpermute_b32 v51, v137, v25
	s_waitcnt lgkmcnt(10)
	v_pk_add_f32 v[42:43], v[96:97], v[42:43]
	ds_bpermute_b32 v76, v137, v28
	ds_bpermute_b32 v77, v137, v29
	s_waitcnt lgkmcnt(10)
	v_pk_add_f32 v[54:55], v[94:95], v[54:55]
	ds_bpermute_b32 v94, v137, v92
	ds_bpermute_b32 v95, v137, v93
	ds_bpermute_b32 v96, v137, v32
	ds_bpermute_b32 v97, v137, v33
	ds_bpermute_b32 v98, v137, v90
	ds_bpermute_b32 v99, v137, v91
	ds_bpermute_b32 v100, v137, v36
	ds_bpermute_b32 v101, v137, v37
	ds_bpermute_b32 v102, v137, v88
	ds_bpermute_b32 v103, v137, v89
	ds_bpermute_b32 v104, v137, v40
	ds_bpermute_b32 v105, v137, v41
	ds_bpermute_b32 v106, v137, v86
	ds_bpermute_b32 v107, v137, v87
	ds_bpermute_b32 v108, v137, v44
	ds_bpermute_b32 v109, v137, v45
	ds_bpermute_b32 v110, v137, v84
	ds_bpermute_b32 v111, v137, v85
	ds_bpermute_b32 v112, v137, v48
	ds_bpermute_b32 v113, v137, v49
	ds_bpermute_b32 v114, v137, v82
	ds_bpermute_b32 v115, v137, v83
	ds_bpermute_b32 v116, v137, v52
	ds_bpermute_b32 v117, v137, v53
	ds_bpermute_b32 v118, v137, v58
	ds_bpermute_b32 v119, v137, v59
	ds_bpermute_b32 v120, v137, v56
	ds_bpermute_b32 v121, v137, v57
	ds_bpermute_b32 v122, v137, v62
	ds_bpermute_b32 v123, v137, v63
	ds_bpermute_b32 v124, v137, v60
	ds_bpermute_b32 v125, v137, v61
	ds_bpermute_b32 v126, v137, v66
	ds_bpermute_b32 v127, v137, v67
	ds_bpermute_b32 v128, v137, v64
	ds_bpermute_b32 v129, v137, v65
	ds_bpermute_b32 v130, v137, v70
	ds_bpermute_b32 v131, v137, v71
	ds_bpermute_b32 v132, v137, v68
	ds_bpermute_b32 v133, v137, v69
	ds_bpermute_b32 v134, v137, v80
	ds_bpermute_b32 v135, v137, v81
	ds_bpermute_b32 v136, v137, v78
	ds_bpermute_b32 v137, v137, v79
	v_cmp_lt_i32_e32 vcc, v3, v2
	s_waitcnt lgkmcnt(14)
	v_pk_add_f32 v[12:13], v[12:13], v[14:15]
	v_pk_add_f32 v[16:17], v[16:17], v[26:27]
	v_cndmask_b32_e32 v2, v138, v3, vcc
	v_lshlrev_b32_e32 v146, 2, v2
	v_pk_add_f32 v[20:21], v[20:21], v[38:39]
	v_pk_add_f32 v[24:25], v[24:25], v[50:51]
	v_pk_add_f32 v[28:29], v[28:29], v[76:77]
	v_pk_add_f32 v[92:93], v[92:93], v[94:95]
	v_pk_add_f32 v[32:33], v[32:33], v[96:97]
	v_pk_add_f32 v[90:91], v[90:91], v[98:99]
	v_pk_add_f32 v[36:37], v[36:37], v[100:101]
	v_pk_add_f32 v[88:89], v[88:89], v[102:103]
	v_pk_add_f32 v[40:41], v[40:41], v[104:105]
	v_pk_add_f32 v[86:87], v[86:87], v[106:107]
	v_pk_add_f32 v[44:45], v[44:45], v[108:109]
	v_pk_add_f32 v[84:85], v[84:85], v[110:111]
	v_pk_add_f32 v[48:49], v[48:49], v[112:113]
	v_pk_add_f32 v[82:83], v[82:83], v[114:115]
	v_pk_add_f32 v[52:53], v[52:53], v[116:117]
	v_pk_add_f32 v[58:59], v[58:59], v[118:119]
	v_pk_add_f32 v[56:57], v[56:57], v[120:121]
	v_pk_add_f32 v[62:63], v[62:63], v[122:123]
	s_waitcnt lgkmcnt(12)
	v_pk_add_f32 v[60:61], v[60:61], v[124:125]
	s_waitcnt lgkmcnt(10)
	v_pk_add_f32 v[66:67], v[66:67], v[126:127]
	s_waitcnt lgkmcnt(8)
	v_pk_add_f32 v[64:65], v[64:65], v[128:129]
	s_waitcnt lgkmcnt(6)
	v_pk_add_f32 v[70:71], v[70:71], v[130:131]
	s_waitcnt lgkmcnt(4)
	v_pk_add_f32 v[68:69], v[68:69], v[132:133]
	s_waitcnt lgkmcnt(2)
	v_pk_add_f32 v[80:81], v[80:81], v[134:135]
	s_waitcnt lgkmcnt(0)
	v_pk_add_f32 v[78:79], v[78:79], v[136:137]
	ds_bpermute_b32 v2, v146, v0
	ds_bpermute_b32 v3, v146, v1
	ds_bpermute_b32 v6, v146, v4
	ds_bpermute_b32 v7, v146, v5
	ds_bpermute_b32 v10, v146, v8
	ds_bpermute_b32 v11, v146, v9
	ds_bpermute_b32 v14, v146, v12
	ds_bpermute_b32 v15, v146, v13
	ds_bpermute_b32 v22, v146, v18
	ds_bpermute_b32 v23, v146, v19
	ds_bpermute_b32 v26, v146, v16
	ds_bpermute_b32 v27, v146, v17
	ds_bpermute_b32 v34, v146, v30
	ds_bpermute_b32 v35, v146, v31
	ds_bpermute_b32 v38, v146, v20
	ds_bpermute_b32 v39, v146, v21
	ds_bpermute_b32 v46, v146, v42
	ds_bpermute_b32 v47, v146, v43
	ds_bpermute_b32 v50, v146, v24
	ds_bpermute_b32 v51, v146, v25
	ds_bpermute_b32 v74, v146, v54
	ds_bpermute_b32 v75, v146, v55
	ds_bpermute_b32 v76, v146, v28
	ds_bpermute_b32 v77, v146, v29
	ds_bpermute_b32 v94, v146, v92
	ds_bpermute_b32 v95, v146, v93
	ds_bpermute_b32 v96, v146, v32
	ds_bpermute_b32 v97, v146, v33
	ds_bpermute_b32 v98, v146, v90
	ds_bpermute_b32 v99, v146, v91
	ds_bpermute_b32 v100, v146, v36
	ds_bpermute_b32 v101, v146, v37
	ds_bpermute_b32 v102, v146, v88
	ds_bpermute_b32 v103, v146, v89
	ds_bpermute_b32 v104, v146, v40
	ds_bpermute_b32 v105, v146, v41
	ds_bpermute_b32 v106, v146, v86
	ds_bpermute_b32 v107, v146, v87
	ds_bpermute_b32 v108, v146, v44
	ds_bpermute_b32 v109, v146, v45
	ds_bpermute_b32 v110, v146, v84
	ds_bpermute_b32 v111, v146, v85
	ds_bpermute_b32 v112, v146, v48
	ds_bpermute_b32 v113, v146, v49
	ds_bpermute_b32 v114, v146, v82
	ds_bpermute_b32 v115, v146, v83
	ds_bpermute_b32 v116, v146, v52
	ds_bpermute_b32 v117, v146, v53
	ds_bpermute_b32 v118, v146, v58
	ds_bpermute_b32 v119, v146, v59
	ds_bpermute_b32 v120, v146, v56
	ds_bpermute_b32 v121, v146, v57
	ds_bpermute_b32 v122, v146, v62
	ds_bpermute_b32 v123, v146, v63
	ds_bpermute_b32 v124, v146, v60
	ds_bpermute_b32 v125, v146, v61
	ds_bpermute_b32 v126, v146, v66
	ds_bpermute_b32 v127, v146, v67
	ds_bpermute_b32 v128, v146, v64
	ds_bpermute_b32 v129, v146, v65
	ds_bpermute_b32 v130, v146, v70
	ds_bpermute_b32 v131, v146, v71
	ds_bpermute_b32 v132, v146, v68
	ds_bpermute_b32 v133, v146, v69
	ds_bpermute_b32 v134, v146, v80
	ds_bpermute_b32 v135, v146, v81
	ds_bpermute_b32 v136, v146, v78
	ds_bpermute_b32 v137, v146, v79
	v_cmp_eq_u32_e32 vcc, 0, v72
	s_waitcnt lgkmcnt(0)
	s_barrier
	s_and_saveexec_b64 s[4:5], vcc
	s_cbranch_execz .LBB0_151
	v_lshrrev_b32_e32 v72, 6, v139
	s_movk_i32 s6, 0x1100
	v_mul_lo_u32 v72, v72, s6
	v_lshl_or_b32 v72, v141, 2, v72
	v_pk_add_f32 v[0:1], v[0:1], v[2:3]
	v_pk_add_f32 v[2:3], v[4:5], v[6:7]
	ds_write_b128 v72, v[0:3] offset:34816
	v_pk_add_f32 v[0:1], v[8:9], v[10:11]
	v_pk_add_f32 v[2:3], v[12:13], v[14:15]
	ds_write_b128 v72, v[0:3] offset:35072
	v_pk_add_f32 v[0:1], v[18:19], v[22:23]
	v_pk_add_f32 v[2:3], v[16:17], v[26:27]
	ds_write_b128 v72, v[0:3] offset:35328
	v_pk_add_f32 v[0:1], v[30:31], v[34:35]
	v_pk_add_f32 v[2:3], v[20:21], v[38:39]
	ds_write_b128 v72, v[0:3] offset:35584
	v_pk_add_f32 v[0:1], v[42:43], v[46:47]
	v_pk_add_f32 v[2:3], v[24:25], v[50:51]
	ds_write_b128 v72, v[0:3] offset:35840
	v_pk_add_f32 v[0:1], v[54:55], v[74:75]
	v_pk_add_f32 v[2:3], v[28:29], v[76:77]
	ds_write_b128 v72, v[0:3] offset:36096
	v_pk_add_f32 v[0:1], v[92:93], v[94:95]
	v_pk_add_f32 v[2:3], v[32:33], v[96:97]
	ds_write_b128 v72, v[0:3] offset:36352
	v_pk_add_f32 v[0:1], v[90:91], v[98:99]
	v_pk_add_f32 v[2:3], v[36:37], v[100:101]
	ds_write_b128 v72, v[0:3] offset:36608
	v_pk_add_f32 v[0:1], v[88:89], v[102:103]
	v_pk_add_f32 v[2:3], v[40:41], v[104:105]
	ds_write_b128 v72, v[0:3] offset:36864
	v_pk_add_f32 v[0:1], v[86:87], v[106:107]
	v_pk_add_f32 v[2:3], v[44:45], v[108:109]
	ds_write_b128 v72, v[0:3] offset:37120
	v_pk_add_f32 v[0:1], v[84:85], v[110:111]
	v_pk_add_f32 v[2:3], v[48:49], v[112:113]
	ds_write_b128 v72, v[0:3] offset:37376
	v_pk_add_f32 v[0:1], v[82:83], v[114:115]
	v_pk_add_f32 v[2:3], v[52:53], v[116:117]
	ds_write_b128 v72, v[0:3] offset:37632
	v_pk_add_f32 v[0:1], v[58:59], v[118:119]
	v_pk_add_f32 v[2:3], v[56:57], v[120:121]
	ds_write_b128 v72, v[0:3] offset:37888
	v_pk_add_f32 v[0:1], v[62:63], v[122:123]
	v_pk_add_f32 v[2:3], v[60:61], v[124:125]
	ds_write_b128 v72, v[0:3] offset:38144
	v_pk_add_f32 v[0:1], v[66:67], v[126:127]
	v_pk_add_f32 v[2:3], v[64:65], v[128:129]
	ds_write_b128 v72, v[0:3] offset:38400
	v_pk_add_f32 v[0:1], v[70:71], v[130:131]
	v_pk_add_f32 v[2:3], v[68:69], v[132:133]
	ds_write_b128 v72, v[0:3] offset:38656
	v_pk_add_f32 v[0:1], v[80:81], v[134:135]
	v_pk_add_f32 v[2:3], v[78:79], v[136:137]
	ds_write_b128 v72, v[0:3] offset:38912
